# peel first K-iteration of all 9 GEMM loops with C=0 (no acc zeroing) + ResNorm partial loads merged, prefetch wait relaxed
# speedup vs baseline: 1.0098x; 1.0098x over previous
; #define PG8_STAGE(bufoff, gbase, voff) do { _Pragma("unroll") for (int _i = 0; _i < 2; ++_i) \
;         __builtin_amdgcn_global_load_lds((const unsigned*)((const char*)(gbase) + (voff)[_i]), (PG8_LAS unsigned*)(lds + (bufoff) + ldsw + _i * 8192), 16, 0, 0); } while (0)
; #define PG8_LDA(dst, b, h) do { _Pragma("unroll") for (int m = 0; m < 4; ++m) _Pragma("unroll") for (int k = 0; k < 2; ++k) dst[m][k] = *(const PG8_LAS bf16x8*)(lds + PG8_SA(b, h) + aoff + m * 2048 + k * 1024); } while (0)
; #define PG8_LDB(dst, b, h) do { _Pragma("unroll") for (int n = 0; n < 2; ++n) _Pragma("unroll") for (int k = 0; k < 2; ++k) dst[n][k] = *(const PG8_LAS bf16x8*)(lds + PG8_SB(b, h) + boff + n * 2048 + k * 1024); } while (0)
; #define PG8_WAIT_V(n) asm volatile("s_waitcnt vmcnt(" #n ")" ::: "memory")
; #define PG8_BAR __builtin_amdgcn_s_barrier()
; template <class Epi, class Sched, bool ALIGN_EPI = false, bool SP2 = false>
; __device__ __forceinline__ void gemm_phase(PG8_LAS unsigned char* lds, const Gemm g, const Sched& S, const Epi& E) {
;     ...
;         const char* nA = has_next ? (const char*)g.A + (size_t)nxt.pm * tstepA + (size_t)nxt.pb * g.sA : cA; const char* nB = has_next ? (const char*)g.Bt + (size_t)nxt.pn * tstepB + (size_t)nxt.pb * g.sB : cB;
;         for (int t = 0; t < nt; t += 2) {
;             const bool last = (t == nt - 2);
;             const char* a1 = cA + (size_t)(t + 1) * kstep;
;             const char* a2 = last ? nA : cA + (size_t)(t + 2) * kstep; const char* b2 = last ? nB : cB + (size_t)(t + 2) * kstep;
;             const char* a3 = a2 + kstep; const char* b3 = b2 + kstep;
;             if (last && has_next) S.a_ready(nxt);
;             if constexpr (SP2) {
;             PG8_LDB(B0, 0, 0); PG8_LDB(B1, 0, 1); PG8_SCHED; PG8_LDA(At, 0, 0); PG8_STAGE(PG8_SA(1, 1), a1 + hstepA, voffA);
;             PG8_WAIT_V(8); PG8_WAIT_L(0); PG8_BAR; PG8_MMA(0, 0, At, B0); PG8_MMA(0, 1, At, B1); PG8_BAR; PG8_SCHED;
;             PG8_LDA(At, 0, 1); PG8_STAGE(PG8_SB(0, 0), b2, voffB); PG8_STAGE(PG8_SB(0, 1), b2 + hstepB, voffB); PG8_STAGE(PG8_SA(0, 0), a2, voffA);
;     ...
; #pragma unroll
;         for (int a = 0; a < 2; ++a)
; #pragma unroll
;             for (int b = 0; b < 2; ++b)
; #pragma unroll
;                 for (int m = 0; m < 4; ++m)
; #pragma unroll
;                     for (int n = 0; n < 2; ++n) acc[a][b][m][n] = (f32x4){0.f, 0.f, 0.f, 0.f};
.LBB0_285:
	s_ashr_i32 s15, s14, 31
	s_lshl_b64 s[16:17], s[14:15], 19
	s_add_u32 s16, s0, s16
	s_addc_u32 s17, s1, s17
	s_and_b64 s[18:19], s[44:45], exec
	s_cselect_b32 s15, s17, s31
	s_cselect_b32 s62, s16, s30
	s_ashr_i32 s9, s8, 31
	s_lshl_b64 s[18:19], s[8:9], 19
	s_add_u32 s18, s38, s18
	s_addc_u32 s19, s39, s19
	s_and_b64 s[36:37], s[44:45], exec
	s_cselect_b32 s9, s19, s35
	s_cselect_b32 s63, s18, s34
	s_add_u32 s30, s30, 0x40080
	s_addc_u32 s31, s31, 0
	s_add_u32 s70, s34, 0x100
	s_addc_u32 s71, s35, 0
	s_mov_b32 s78, -2
	s_add_u32 s20, s30, 0xfffc0080
	s_addc_u32 s21, s31, -1
	s_add_i32 s79, 0, 0x10000
	s_cmp_eq_u32 s78, 12
	s_cselect_b32 s37, s15, s21
	s_cselect_b32 s36, s62, s20
	v_add_u32_e32 v0, s79, v149
	s_cselect_b32 s35, s9, s71
	s_cselect_b32 s34, s63, s70
	s_add_i32 s20, 0, 0x14000
	ds_read_b128 v[144:147], v0
	ds_read_b128 v[152:155], v0 offset:1024
	ds_read_b128 v[156:159], v0 offset:2048
	ds_read_b128 v[160:163], v0 offset:3072
	v_add_u32_e32 v0, s20, v149
	ds_read_b128 v[164:167], v0
	ds_read_b128 v[168:171], v0 offset:1024
	ds_read_b128 v[172:175], v0 offset:2048
	ds_read_b128 v[176:179], v0 offset:3072
	v_lshl_add_u64 v[200:201], s[30:31], 0, v[138:139]
	s_add_i32 m0, s42, 0xc000
	ds_read_b128 v[180:183], v150
	ds_read_b128 v[184:187], v150 offset:1024
	ds_read_b128 v[188:191], v150 offset:2048
	ds_read_b128 v[192:195], v150 offset:3072
	ds_read_b128 v[196:199], v150 offset:4096
	ds_read_b128 v[208:211], v150 offset:5120
	ds_read_b128 v[212:215], v150 offset:6144
	ds_read_b128 v[216:219], v150 offset:7168
	global_load_lds_dwordx4 v[200:201], off
	v_lshl_add_u64 v[200:201], s[30:31], 0, v[140:141]
	s_add_i32 m0, s42, 0xe000
	s_nop 0
	global_load_lds_dwordx4 v[200:201], off
	s_waitcnt vmcnt(8)
	s_waitcnt lgkmcnt(0)
	s_barrier
	s_setprio 1
	s_waitcnt lgkmcnt(0)
	v_mfma_f32_16x16x32_bf16 v[126:129], v[144:147], v[180:183], 0
	v_mfma_f32_16x16x32_bf16 v[122:125], v[156:159], v[180:183], 0
	v_mfma_f32_16x16x32_bf16 v[110:113], v[144:147], v[188:191], 0
	v_mfma_f32_16x16x32_bf16 v[106:109], v[156:159], v[188:191], 0
	v_mfma_f32_16x16x32_bf16 v[98:101], v[144:147], v[196:199], 0
	v_mfma_f32_16x16x32_bf16 v[90:93], v[156:159], v[196:199], 0
	v_mfma_f32_16x16x32_bf16 v[82:85], v[144:147], v[212:215], 0
	v_mfma_f32_16x16x32_bf16 v[74:77], v[156:159], v[212:215], 0
	v_mfma_f32_16x16x32_bf16 v[126:129], v[152:155], v[184:187], v[126:129]
	v_mfma_f32_16x16x32_bf16 v[122:125], v[160:163], v[184:187], v[122:125]
	v_mfma_f32_16x16x32_bf16 v[110:113], v[152:155], v[192:195], v[110:113]
	v_mfma_f32_16x16x32_bf16 v[106:109], v[160:163], v[192:195], v[106:109]
	v_mfma_f32_16x16x32_bf16 v[98:101], v[152:155], v[208:211], v[98:101]
	v_mfma_f32_16x16x32_bf16 v[90:93], v[160:163], v[208:211], v[90:93]
	v_mfma_f32_16x16x32_bf16 v[82:85], v[152:155], v[216:219], v[82:85]
	v_mfma_f32_16x16x32_bf16 v[74:77], v[160:163], v[216:219], v[74:77]
	s_setprio 0
	s_setprio 1
	v_mfma_f32_16x16x32_bf16 v[118:121], v[164:167], v[180:183], 0
	v_mfma_f32_16x16x32_bf16 v[114:117], v[172:175], v[180:183], 0
	v_mfma_f32_16x16x32_bf16 v[102:105], v[164:167], v[188:191], 0
	v_mfma_f32_16x16x32_bf16 v[94:97], v[172:175], v[188:191], 0
	v_mfma_f32_16x16x32_bf16 v[86:89], v[164:167], v[196:199], 0
	v_mfma_f32_16x16x32_bf16 v[78:81], v[172:175], v[196:199], 0
	v_mfma_f32_16x16x32_bf16 v[70:73], v[164:167], v[212:215], 0
	v_mfma_f32_16x16x32_bf16 v[66:69], v[172:175], v[212:215], 0
	v_mfma_f32_16x16x32_bf16 v[118:121], v[168:171], v[184:187], v[118:121]
	v_mfma_f32_16x16x32_bf16 v[114:117], v[176:179], v[184:187], v[114:117]
	v_mfma_f32_16x16x32_bf16 v[102:105], v[168:171], v[192:195], v[102:105]
	v_mfma_f32_16x16x32_bf16 v[94:97], v[176:179], v[192:195], v[94:97]
	v_mfma_f32_16x16x32_bf16 v[86:89], v[168:171], v[208:211], v[86:89]
	v_mfma_f32_16x16x32_bf16 v[78:81], v[176:179], v[208:211], v[78:81]
	v_mfma_f32_16x16x32_bf16 v[70:73], v[168:171], v[216:219], v[70:73]
	v_mfma_f32_16x16x32_bf16 v[66:69], v[176:179], v[216:219], v[66:69]
	s_setprio 0
	s_barrier
	s_add_i32 s21, s79, s26
	v_lshl_add_u64 v[200:201], s[34:35], 0, v[134:135]
	s_mov_b32 m0, s21
	ds_read_b128 v[180:183], v150 offset:16384
	ds_read_b128 v[184:187], v150 offset:17408
	ds_read_b128 v[188:191], v150 offset:18432
	ds_read_b128 v[192:195], v150 offset:19456
	ds_read_b128 v[196:199], v150 offset:20480
	ds_read_b128 v[208:211], v150 offset:21504
	ds_read_b128 v[212:215], v150 offset:22528
	ds_read_b128 v[216:219], v150 offset:23552
	global_load_lds_dwordx4 v[200:201], off
	s_add_i32 m0, s21, 0x2000
	s_add_u32 s80, s34, 0x40000
	v_lshl_add_u64 v[204:205], s[34:35], 0, v[130:131]
	s_addc_u32 s81, s35, 0
	s_add_i32 s20, s20, s26
	global_load_lds_dwordx4 v[204:205], off
	v_lshl_add_u64 v[220:221], s[80:81], 0, v[134:135]
	s_mov_b32 m0, s20
	v_lshl_add_u64 v[222:223], s[36:37], 0, v[132:133]
	global_load_lds_dwordx4 v[220:221], off
	v_lshl_add_u64 v[220:221], s[80:81], 0, v[130:131]
	s_add_i32 m0, s20, 0x2000
	s_nop 0
	global_load_lds_dwordx4 v[220:221], off
	v_lshl_add_u64 v[220:221], s[36:37], 0, v[136:137]
	s_mov_b32 m0, s42
	s_nop 0
	global_load_lds_dwordx4 v[220:221], off
	s_mov_b32 m0, s43
	s_nop 0
	global_load_lds_dwordx4 v[222:223], off
	s_waitcnt vmcnt(8)
	s_waitcnt lgkmcnt(0)
	s_barrier
; #define PG8_STAGE(bufoff, gbase, voff) do { _Pragma("unroll") for (int _i = 0; _i < 2; ++_i) \
;         __builtin_amdgcn_global_load_lds((const unsigned*)((const char*)(gbase) + (voff)[_i]), (PG8_LAS unsigned*)(lds + (bufoff) + ldsw + _i * 8192), 16, 0, 0); } while (0)
; #define PG8_LDA(dst, b, h) do { _Pragma("unroll") for (int m = 0; m < 4; ++m) _Pragma("unroll") for (int k = 0; k < 2; ++k) dst[m][k] = *(const PG8_LAS bf16x8*)(lds + PG8_SA(b, h) + aoff + m * 2048 + k * 1024); } while (0)
; #define PG8_LDB(dst, b, h) do { _Pragma("unroll") for (int n = 0; n < 2; ++n) _Pragma("unroll") for (int k = 0; k < 2; ++k) dst[n][k] = *(const PG8_LAS bf16x8*)(lds + PG8_SB(b, h) + boff + n * 2048 + k * 1024); } while (0)
; #define PG8_MMA(ai, bj, At, Bt) do { __builtin_amdgcn_s_setprio(1); _Pragma("unroll") for (int m = 0; m < 4; ++m) _Pragma("unroll") for (int n = 0; n < 2; ++n) _Pragma("unroll") for (int k = 0; k < 2; ++k) \
;         acc[ai][bj][m][n] = __builtin_amdgcn_mfma_f32_16x16x32_bf16(Bt[n][k], At[m][k], acc[ai][bj][m][n], 0, 0, 0); __builtin_amdgcn_s_setprio(0); } while (0)
; #define PG8_WAIT_V(n) asm volatile("s_waitcnt vmcnt(" #n ")" ::: "memory")
; #define PG8_WAIT_L(n) asm volatile("s_waitcnt lgkmcnt(" #n ")" ::: "memory")
; #define PG8_BAR __builtin_amdgcn_s_barrier()
; #define PG8_SCHED __builtin_amdgcn_sched_barrier(0)
; template <class Epi, class Sched, bool ALIGN_EPI = false, bool SP2 = false>
; __device__ __forceinline__ void gemm_phase(PG8_LAS unsigned char* lds, const Gemm g, const Sched& S, const Epi& E) {
;     ...
;             PG8_WAIT_V(8); PG8_WAIT_L(0); PG8_BAR; PG8_MMA(1, 0, At, B0); PG8_MMA(1, 1, At, B1); PG8_BAR; PG8_SCHED;
;             PG8_LDB(B0, 1, 0); PG8_LDB(B1, 1, 1); PG8_SCHED; PG8_LDA(At, 1, 0); PG8_STAGE(PG8_SA(0, 1), a2 + hstepA, voffA);
;             PG8_WAIT_V(8); PG8_WAIT_L(0); PG8_BAR; PG8_MMA(0, 0, At, B0); PG8_MMA(0, 1, At, B1); PG8_BAR; PG8_SCHED;
;             PG8_LDA(At, 1, 1); PG8_STAGE(PG8_SB(1, 0), b3, voffB); PG8_STAGE(PG8_SB(1, 1), b3 + hstepB, voffB); PG8_STAGE(PG8_SA(1, 0), a3, voffA);
	s_setprio 1
	s_waitcnt lgkmcnt(0)
	v_mfma_f32_16x16x32_bf16 v[62:65], v[144:147], v[180:183], 0
	v_mfma_f32_16x16x32_bf16 v[58:61], v[156:159], v[180:183], 0
	v_mfma_f32_16x16x32_bf16 v[46:49], v[144:147], v[188:191], 0
	v_mfma_f32_16x16x32_bf16 v[42:45], v[156:159], v[188:191], 0
	v_mfma_f32_16x16x32_bf16 v[34:37], v[144:147], v[196:199], 0
	v_mfma_f32_16x16x32_bf16 v[26:29], v[156:159], v[196:199], 0
	v_mfma_f32_16x16x32_bf16 v[18:21], v[144:147], v[212:215], 0
	v_mfma_f32_16x16x32_bf16 v[10:13], v[156:159], v[212:215], 0
	v_mfma_f32_16x16x32_bf16 v[62:65], v[152:155], v[184:187], v[62:65]
	v_mfma_f32_16x16x32_bf16 v[58:61], v[160:163], v[184:187], v[58:61]
	v_mfma_f32_16x16x32_bf16 v[46:49], v[152:155], v[192:195], v[46:49]
	v_mfma_f32_16x16x32_bf16 v[42:45], v[160:163], v[192:195], v[42:45]
	v_mfma_f32_16x16x32_bf16 v[34:37], v[152:155], v[208:211], v[34:37]
	v_mfma_f32_16x16x32_bf16 v[26:29], v[160:163], v[208:211], v[26:29]
	v_mfma_f32_16x16x32_bf16 v[18:21], v[152:155], v[216:219], v[18:21]
	v_mfma_f32_16x16x32_bf16 v[10:13], v[160:163], v[216:219], v[10:13]
	s_setprio 0
	s_setprio 1
	v_mfma_f32_16x16x32_bf16 v[54:57], v[164:167], v[180:183], 0
	v_mfma_f32_16x16x32_bf16 v[50:53], v[172:175], v[180:183], 0
	v_mfma_f32_16x16x32_bf16 v[38:41], v[164:167], v[188:191], 0
	v_mfma_f32_16x16x32_bf16 v[30:33], v[172:175], v[188:191], 0
	v_mfma_f32_16x16x32_bf16 v[22:25], v[164:167], v[196:199], 0
	v_mfma_f32_16x16x32_bf16 v[14:17], v[172:175], v[196:199], 0
	v_mfma_f32_16x16x32_bf16 v[6:9], v[164:167], v[212:215], 0
	v_mfma_f32_16x16x32_bf16 v[2:5], v[172:175], v[212:215], 0
	v_mfma_f32_16x16x32_bf16 v[54:57], v[168:171], v[184:187], v[54:57]
	v_mfma_f32_16x16x32_bf16 v[50:53], v[176:179], v[184:187], v[50:53]
	v_mfma_f32_16x16x32_bf16 v[38:41], v[168:171], v[192:195], v[38:41]
	v_mfma_f32_16x16x32_bf16 v[30:33], v[176:179], v[192:195], v[30:33]
	v_mfma_f32_16x16x32_bf16 v[22:25], v[168:171], v[208:211], v[22:25]
	v_mfma_f32_16x16x32_bf16 v[14:17], v[176:179], v[208:211], v[14:17]
	v_mfma_f32_16x16x32_bf16 v[6:9], v[168:171], v[216:219], v[6:9]
	v_mfma_f32_16x16x32_bf16 v[2:5], v[176:179], v[216:219], v[2:5]
	s_setprio 0
	s_barrier
	s_add_i32 s20, 0, 0x18000
	v_add_u32_e32 v0, s20, v149
	s_add_i32 s21, 0, 0x1c000
	ds_read_b128 v[144:147], v0
	ds_read_b128 v[152:155], v0 offset:1024
	ds_read_b128 v[156:159], v0 offset:2048
	ds_read_b128 v[160:163], v0 offset:3072
	v_add_u32_e32 v0, s21, v149
	ds_read_b128 v[164:167], v0
	ds_read_b128 v[168:171], v0 offset:1024
	ds_read_b128 v[172:175], v0 offset:2048
	ds_read_b128 v[176:179], v0 offset:3072
	s_add_u32 s36, s36, 0x40000
	s_addc_u32 s37, s37, 0
	s_mov_b32 m0, s46
	v_lshl_add_u64 v[224:225], s[36:37], 0, v[136:137]
	ds_read_b128 v[180:183], v150 offset:32768
	ds_read_b128 v[184:187], v150 offset:33792
	ds_read_b128 v[188:191], v150 offset:34816
	ds_read_b128 v[192:195], v150 offset:35840
	ds_read_b128 v[196:199], v150 offset:36864
	ds_read_b128 v[208:211], v150 offset:37888
	ds_read_b128 v[212:215], v150 offset:38912
	ds_read_b128 v[216:219], v150 offset:39936
	global_load_lds_dwordx4 v[224:225], off
	v_lshl_add_u64 v[224:225], s[36:37], 0, v[132:133]
	s_mov_b32 m0, s47
	s_nop 0
	global_load_lds_dwordx4 v[224:225], off
	s_waitcnt vmcnt(8)
	s_waitcnt lgkmcnt(0)
	s_barrier
	s_setprio 1
	s_waitcnt lgkmcnt(0)
	v_mfma_f32_16x16x32_bf16 v[126:129], v[144:147], v[180:183], v[126:129]
	v_mfma_f32_16x16x32_bf16 v[122:125], v[156:159], v[180:183], v[122:125]
	v_mfma_f32_16x16x32_bf16 v[110:113], v[144:147], v[188:191], v[110:113]
	v_mfma_f32_16x16x32_bf16 v[106:109], v[156:159], v[188:191], v[106:109]
	v_mfma_f32_16x16x32_bf16 v[98:101], v[144:147], v[196:199], v[98:101]
	v_mfma_f32_16x16x32_bf16 v[90:93], v[156:159], v[196:199], v[90:93]
	v_mfma_f32_16x16x32_bf16 v[82:85], v[144:147], v[212:215], v[82:85]
	v_mfma_f32_16x16x32_bf16 v[74:77], v[156:159], v[212:215], v[74:77]
	v_mfma_f32_16x16x32_bf16 v[126:129], v[152:155], v[184:187], v[126:129]
	v_mfma_f32_16x16x32_bf16 v[122:125], v[160:163], v[184:187], v[122:125]
	v_mfma_f32_16x16x32_bf16 v[110:113], v[152:155], v[192:195], v[110:113]
	v_mfma_f32_16x16x32_bf16 v[106:109], v[160:163], v[192:195], v[106:109]
	v_mfma_f32_16x16x32_bf16 v[98:101], v[152:155], v[208:211], v[98:101]
	v_mfma_f32_16x16x32_bf16 v[90:93], v[160:163], v[208:211], v[90:93]
	v_mfma_f32_16x16x32_bf16 v[82:85], v[152:155], v[216:219], v[82:85]
	v_mfma_f32_16x16x32_bf16 v[74:77], v[160:163], v[216:219], v[74:77]
	s_setprio 0
	s_setprio 1
	v_mfma_f32_16x16x32_bf16 v[118:121], v[164:167], v[180:183], v[118:121]
	v_mfma_f32_16x16x32_bf16 v[114:117], v[172:175], v[180:183], v[114:117]
	v_mfma_f32_16x16x32_bf16 v[102:105], v[164:167], v[188:191], v[102:105]
	v_mfma_f32_16x16x32_bf16 v[94:97], v[172:175], v[188:191], v[94:97]
	v_mfma_f32_16x16x32_bf16 v[86:89], v[164:167], v[196:199], v[86:89]
	v_mfma_f32_16x16x32_bf16 v[78:81], v[172:175], v[196:199], v[78:81]
	v_mfma_f32_16x16x32_bf16 v[70:73], v[164:167], v[212:215], v[70:73]
	v_mfma_f32_16x16x32_bf16 v[66:69], v[172:175], v[212:215], v[66:69]
	v_mfma_f32_16x16x32_bf16 v[118:121], v[168:171], v[184:187], v[118:121]
	v_mfma_f32_16x16x32_bf16 v[114:117], v[176:179], v[184:187], v[114:117]
	v_mfma_f32_16x16x32_bf16 v[102:105], v[168:171], v[192:195], v[102:105]
	v_mfma_f32_16x16x32_bf16 v[94:97], v[176:179], v[192:195], v[94:97]
	v_mfma_f32_16x16x32_bf16 v[86:89], v[168:171], v[208:211], v[86:89]
	v_mfma_f32_16x16x32_bf16 v[78:81], v[176:179], v[208:211], v[78:81]
	v_mfma_f32_16x16x32_bf16 v[70:73], v[168:171], v[216:219], v[70:73]
	v_mfma_f32_16x16x32_bf16 v[66:69], v[176:179], v[216:219], v[66:69]
	s_setprio 0
	s_barrier
; #define PG8_STAGE(bufoff, gbase, voff) do { _Pragma("unroll") for (int _i = 0; _i < 2; ++_i) \
;         __builtin_amdgcn_global_load_lds((const unsigned*)((const char*)(gbase) + (voff)[_i]), (PG8_LAS unsigned*)(lds + (bufoff) + ldsw + _i * 8192), 16, 0, 0); } while (0)
; #define PG8_LDA(dst, b, h) do { _Pragma("unroll") for (int m = 0; m < 4; ++m) _Pragma("unroll") for (int k = 0; k < 2; ++k) dst[m][k] = *(const PG8_LAS bf16x8*)(lds + PG8_SA(b, h) + aoff + m * 2048 + k * 1024); } while (0)
; #define PG8_MMA(ai, bj, At, Bt) do { __builtin_amdgcn_s_setprio(1); _Pragma("unroll") for (int m = 0; m < 4; ++m) _Pragma("unroll") for (int n = 0; n < 2; ++n) _Pragma("unroll") for (int k = 0; k < 2; ++k) \
;         acc[ai][bj][m][n] = __builtin_amdgcn_mfma_f32_16x16x32_bf16(Bt[n][k], At[m][k], acc[ai][bj][m][n], 0, 0, 0); __builtin_amdgcn_s_setprio(0); } while (0)
; #define PG8_WAIT_V(n) asm volatile("s_waitcnt vmcnt(" #n ")" ::: "memory")
; #define PG8_WAIT_L(n) asm volatile("s_waitcnt lgkmcnt(" #n ")" ::: "memory")
; #define PG8_BAR __builtin_amdgcn_s_barrier()
; #define PG8_SCHED __builtin_amdgcn_sched_barrier(0)
; template <class Epi, class Sched, bool ALIGN_EPI = false, bool SP2 = false>
; __device__ __forceinline__ void gemm_phase(PG8_LAS unsigned char* lds, const Gemm g, const Sched& S, const Epi& E) {
;     ...
;         for (int t = 0; t < nt; t += 2) {
;             const bool last = (t == nt - 2);
;     ...
;             PG8_LDA(At, 1, 1); PG8_STAGE(PG8_SB(1, 0), b3, voffB); PG8_STAGE(PG8_SB(1, 1), b3 + hstepB, voffB); PG8_STAGE(PG8_SA(1, 0), a3, voffA);
;             PG8_WAIT_V(8); PG8_WAIT_L(0); PG8_BAR; PG8_MMA(1, 0, At, B0); PG8_MMA(1, 1, At, B1); PG8_BAR; PG8_SCHED;
	s_add_i32 s20, s20, s26
	v_lshl_add_u64 v[200:201], v[200:201], 0, s[22:23]
	s_mov_b32 m0, s20
	ds_read_b128 v[180:183], v150 offset:49152
	ds_read_b128 v[184:187], v150 offset:50176
	ds_read_b128 v[188:191], v150 offset:51200
	ds_read_b128 v[192:195], v150 offset:52224
	ds_read_b128 v[196:199], v150 offset:53248
	ds_read_b128 v[208:211], v150 offset:54272
	ds_read_b128 v[212:215], v150 offset:55296
	ds_read_b128 v[216:219], v150 offset:56320
	global_load_lds_dwordx4 v[200:201], off
	s_add_i32 m0, s20, 0x2000
	s_add_u32 s34, s34, 0x40080
	v_lshl_add_u64 v[200:201], v[204:205], 0, s[22:23]
	s_addc_u32 s35, s35, 0
	s_add_i32 s20, s21, s26
	global_load_lds_dwordx4 v[200:201], off
	v_lshl_add_u64 v[200:201], s[34:35], 0, v[134:135]
	s_mov_b32 m0, s20
	s_nop 0
	global_load_lds_dwordx4 v[200:201], off
	v_lshl_add_u64 v[200:201], s[34:35], 0, v[130:131]
	s_add_i32 m0, s20, 0x2000
	s_nop 0
	global_load_lds_dwordx4 v[200:201], off
	v_lshl_add_u64 v[200:201], v[220:221], 0, s[22:23]
	s_mov_b32 m0, s56
	s_nop 0
	global_load_lds_dwordx4 v[200:201], off
	v_lshl_add_u64 v[200:201], v[222:223], 0, s[22:23]
	s_mov_b32 m0, s57
	s_nop 0
	global_load_lds_dwordx4 v[200:201], off
	s_waitcnt vmcnt(8)
	s_waitcnt lgkmcnt(0)
	s_barrier
	s_setprio 1
	s_waitcnt lgkmcnt(0)
	v_mfma_f32_16x16x32_bf16 v[62:65], v[144:147], v[180:183], v[62:65]
	v_mfma_f32_16x16x32_bf16 v[58:61], v[156:159], v[180:183], v[58:61]
	v_mfma_f32_16x16x32_bf16 v[46:49], v[144:147], v[188:191], v[46:49]
	v_mfma_f32_16x16x32_bf16 v[42:45], v[156:159], v[188:191], v[42:45]
	v_mfma_f32_16x16x32_bf16 v[34:37], v[144:147], v[196:199], v[34:37]
	v_mfma_f32_16x16x32_bf16 v[26:29], v[156:159], v[196:199], v[26:29]
	v_mfma_f32_16x16x32_bf16 v[18:21], v[144:147], v[212:215], v[18:21]
	v_mfma_f32_16x16x32_bf16 v[10:13], v[156:159], v[212:215], v[10:13]
	v_mfma_f32_16x16x32_bf16 v[62:65], v[152:155], v[184:187], v[62:65]
	v_mfma_f32_16x16x32_bf16 v[58:61], v[160:163], v[184:187], v[58:61]
	v_mfma_f32_16x16x32_bf16 v[46:49], v[152:155], v[192:195], v[46:49]
	v_mfma_f32_16x16x32_bf16 v[42:45], v[160:163], v[192:195], v[42:45]
	v_mfma_f32_16x16x32_bf16 v[34:37], v[152:155], v[208:211], v[34:37]
	v_mfma_f32_16x16x32_bf16 v[26:29], v[160:163], v[208:211], v[26:29]
	v_mfma_f32_16x16x32_bf16 v[18:21], v[152:155], v[216:219], v[18:21]
	v_mfma_f32_16x16x32_bf16 v[10:13], v[160:163], v[216:219], v[10:13]
	s_setprio 0
	s_setprio 1
	v_mfma_f32_16x16x32_bf16 v[54:57], v[164:167], v[180:183], v[54:57]
	v_mfma_f32_16x16x32_bf16 v[50:53], v[172:175], v[180:183], v[50:53]
	v_mfma_f32_16x16x32_bf16 v[38:41], v[164:167], v[188:191], v[38:41]
	v_mfma_f32_16x16x32_bf16 v[30:33], v[172:175], v[188:191], v[30:33]
	v_mfma_f32_16x16x32_bf16 v[22:25], v[164:167], v[196:199], v[22:25]
	v_mfma_f32_16x16x32_bf16 v[14:17], v[172:175], v[196:199], v[14:17]
	v_mfma_f32_16x16x32_bf16 v[6:9], v[164:167], v[212:215], v[6:9]
	v_mfma_f32_16x16x32_bf16 v[2:5], v[172:175], v[212:215], v[2:5]
	v_mfma_f32_16x16x32_bf16 v[54:57], v[168:171], v[184:187], v[54:57]
	v_mfma_f32_16x16x32_bf16 v[50:53], v[176:179], v[184:187], v[50:53]
	v_mfma_f32_16x16x32_bf16 v[38:41], v[168:171], v[192:195], v[38:41]
	v_mfma_f32_16x16x32_bf16 v[30:33], v[176:179], v[192:195], v[30:33]
	v_mfma_f32_16x16x32_bf16 v[22:25], v[168:171], v[208:211], v[22:25]
	v_mfma_f32_16x16x32_bf16 v[14:17], v[176:179], v[208:211], v[14:17]
	v_mfma_f32_16x16x32_bf16 v[6:9], v[168:171], v[216:219], v[6:9]
	v_mfma_f32_16x16x32_bf16 v[2:5], v[176:179], v[216:219], v[2:5]
	s_setprio 0
	s_barrier
	s_add_i32 s78, s78, 2
	s_add_u32 s30, s30, 0x100
	s_addc_u32 s31, s31, 0
	s_add_u32 s70, s70, 0x100
	s_addc_u32 s71, s71, 0
	s_cmp_gt_u32 s78, 13
	s_cbranch_scc1 .Lpk_done_g286

; #define PG8_BAR __builtin_amdgcn_s_barrier()
; template <class Epi, class Sched, bool ALIGN_EPI = false, bool SP2 = false>
; __device__ __forceinline__ void gemm_phase(PG8_LAS unsigned char* lds, const Gemm g, const Sched& S, const Epi& E) {
;     ...
;         }
;         if constexpr (ALIGN_EPI) { if (wr == 0) PG8_BAR; }
.Lpk_done_g286:
	s_and_b64 vcc, exec, s[12:13]
	s_cbranch_vccz .LBB0_289
	s_barrier

; #define PG8_STAGE(bufoff, gbase, voff) do { _Pragma("unroll") for (int _i = 0; _i < 2; ++_i) \
;         __builtin_amdgcn_global_load_lds((const unsigned*)((const char*)(gbase) + (voff)[_i]), (PG8_LAS unsigned*)(lds + (bufoff) + ldsw + _i * 8192), 16, 0, 0); } while (0)
; #define PG8_LDA(dst, b, h) do { _Pragma("unroll") for (int m = 0; m < 4; ++m) _Pragma("unroll") for (int k = 0; k < 2; ++k) dst[m][k] = *(const PG8_LAS bf16x8*)(lds + PG8_SA(b, h) + aoff + m * 2048 + k * 1024); } while (0)
; #define PG8_LDB(dst, b, h) do { _Pragma("unroll") for (int n = 0; n < 2; ++n) _Pragma("unroll") for (int k = 0; k < 2; ++k) dst[n][k] = *(const PG8_LAS bf16x8*)(lds + PG8_SB(b, h) + boff + n * 2048 + k * 1024); } while (0)
; #define PG8_WAIT_V(n) asm volatile("s_waitcnt vmcnt(" #n ")" ::: "memory")
; #define PG8_BAR __builtin_amdgcn_s_barrier()
; template <class Epi, class Sched, bool ALIGN_EPI = false, bool SP2 = false>
; __device__ __forceinline__ void gemm_phase(PG8_LAS unsigned char* lds, const Gemm g, const Sched& S, const Epi& E) {
;     ...
;         const char* nA = has_next ? (const char*)g.A + (size_t)nxt.pm * tstepA + (size_t)nxt.pb * g.sA : cA; const char* nB = has_next ? (const char*)g.Bt + (size_t)nxt.pn * tstepB + (size_t)nxt.pb * g.sB : cB;
;         for (int t = 0; t < nt; t += 2) {
;             const bool last = (t == nt - 2);
;             const char* a1 = cA + (size_t)(t + 1) * kstep;
;             const char* a2 = last ? nA : cA + (size_t)(t + 2) * kstep; const char* b2 = last ? nB : cB + (size_t)(t + 2) * kstep;
;             const char* a3 = a2 + kstep; const char* b3 = b2 + kstep;
;             if (last && has_next) S.a_ready(nxt);
;             if constexpr (SP2) {
;             PG8_LDB(B0, 0, 0); PG8_LDB(B1, 0, 1); PG8_SCHED; PG8_LDA(At, 0, 0); PG8_STAGE(PG8_SA(1, 1), a1 + hstepA, voffA);
;             PG8_WAIT_V(8); PG8_WAIT_L(0); PG8_BAR; PG8_MMA(0, 0, At, B0); PG8_MMA(0, 1, At, B1); PG8_BAR; PG8_SCHED;
;             PG8_LDA(At, 0, 1); PG8_STAGE(PG8_SB(0, 0), b2, voffB); PG8_STAGE(PG8_SB(0, 1), b2 + hstepB, voffB); PG8_STAGE(PG8_SA(0, 0), a2, voffA);
;     ...
; #pragma unroll
;         for (int a = 0; a < 2; ++a)
; #pragma unroll
;             for (int b = 0; b < 2; ++b)
; #pragma unroll
;                 for (int m = 0; m < 4; ++m)
; #pragma unroll
;                     for (int n = 0; n < 2; ++n) acc[a][b][m][n] = (f32x4){0.f, 0.f, 0.f, 0.f};
.LBB0_454:
	s_ashr_i32 s9, s8, 31
	s_lshl_b64 s[0:1], s[8:9], 19
	s_add_u32 s34, s56, s0
	s_addc_u32 s35, s57, s1
	s_and_b64 s[0:1], s[46:47], exec
	s_cselect_b32 s9, s35, s37
	s_cselect_b32 s39, s34, s36
	s_ashr_i32 s53, s52, 31
	s_lshl_b64 s[0:1], s[52:53], 19
	s_add_u32 s0, s26, s0
	s_addc_u32 s1, s78, s1
	s_and_b64 s[54:55], s[46:47], exec
	s_cselect_b32 s43, s1, s71
	s_cselect_b32 s53, s0, s70
	s_add_u32 s36, s36, 0x40080
	s_addc_u32 s37, s37, 0
	s_add_u32 s54, s70, 0x100
	s_addc_u32 s55, s71, 0
	s_mov_b32 s60, -2
	s_waitcnt lgkmcnt(0)
	s_add_u32 s20, s36, 0xfffc0080
	s_addc_u32 s21, s37, -1
	s_add_i32 s61, 0, 0x10000
	s_cmp_eq_u32 s60, 12
	s_cselect_b32 vcc_hi, s9, s21
	s_cselect_b32 vcc_lo, s39, s20
	s_cselect_b32 s71, s43, s55
	s_cselect_b32 s70, s53, s54
	s_add_i32 s63, 0, 0x14000
	v_add_u32_e32 v102, s61, v222
	v_add_u32_e32 v158, s63, v222
	ds_read_b128 v[90:93], v102
	ds_read_b128 v[94:97], v102 offset:1024
	ds_read_b128 v[98:101], v102 offset:2048
	ds_read_b128 v[102:105], v102 offset:3072
	ds_read_b128 v[146:149], v158
	ds_read_b128 v[150:153], v158 offset:1024
	ds_read_b128 v[154:157], v158 offset:2048
	ds_read_b128 v[158:161], v158 offset:3072
	v_lshl_add_u64 v[204:205], s[36:37], 0, v[214:215]
	s_add_i32 m0, s80, 0xc000
	ds_read_b128 v[162:165], v227
	ds_read_b128 v[166:169], v227 offset:1024
	ds_read_b128 v[170:173], v227 offset:2048
	ds_read_b128 v[174:177], v227 offset:3072
	ds_read_b128 v[178:181], v227 offset:4096
	ds_read_b128 v[182:185], v227 offset:5120
	ds_read_b128 v[218:221], v227 offset:6144
	ds_read_b128 v[240:243], v227 offset:7168
	global_load_lds_dwordx4 v[204:205], off
	v_lshl_add_u64 v[204:205], s[36:37], 0, v[216:217]
	s_add_i32 m0, s80, 0xe000
	s_nop 0
	global_load_lds_dwordx4 v[204:205], off
	s_waitcnt vmcnt(8)
	s_waitcnt lgkmcnt(0)
	s_barrier
	s_setprio 1
	s_waitcnt lgkmcnt(0)
	v_mfma_f32_16x16x32_bf16 v[142:145], v[90:93], v[162:165], 0
	v_mfma_f32_16x16x32_bf16 v[138:141], v[98:101], v[162:165], 0
	v_mfma_f32_16x16x32_bf16 v[126:129], v[90:93], v[170:173], 0
	v_mfma_f32_16x16x32_bf16 v[122:125], v[98:101], v[170:173], 0
	v_mfma_f32_16x16x32_bf16 v[110:113], v[90:93], v[178:181], 0
	v_mfma_f32_16x16x32_bf16 v[106:109], v[98:101], v[178:181], 0
	v_mfma_f32_16x16x32_bf16 v[78:81], v[90:93], v[218:221], 0
	v_mfma_f32_16x16x32_bf16 v[74:77], v[98:101], v[218:221], 0
	v_mfma_f32_16x16x32_bf16 v[142:145], v[94:97], v[166:169], v[142:145]
	v_mfma_f32_16x16x32_bf16 v[138:141], v[102:105], v[166:169], v[138:141]
	v_mfma_f32_16x16x32_bf16 v[126:129], v[94:97], v[174:177], v[126:129]
	v_mfma_f32_16x16x32_bf16 v[122:125], v[102:105], v[174:177], v[122:125]
	v_mfma_f32_16x16x32_bf16 v[110:113], v[94:97], v[182:185], v[110:113]
	v_mfma_f32_16x16x32_bf16 v[106:109], v[102:105], v[182:185], v[106:109]
	v_mfma_f32_16x16x32_bf16 v[78:81], v[94:97], v[240:243], v[78:81]
	v_mfma_f32_16x16x32_bf16 v[74:77], v[102:105], v[240:243], v[74:77]
	s_setprio 0
	s_setprio 1
	v_mfma_f32_16x16x32_bf16 v[134:137], v[146:149], v[162:165], 0
	v_mfma_f32_16x16x32_bf16 v[130:133], v[154:157], v[162:165], 0
	v_mfma_f32_16x16x32_bf16 v[118:121], v[146:149], v[170:173], 0
	v_mfma_f32_16x16x32_bf16 v[114:117], v[154:157], v[170:173], 0
	v_mfma_f32_16x16x32_bf16 v[86:89], v[146:149], v[178:181], 0
	v_mfma_f32_16x16x32_bf16 v[82:85], v[154:157], v[178:181], 0
	v_mfma_f32_16x16x32_bf16 v[70:73], v[146:149], v[218:221], 0
	v_mfma_f32_16x16x32_bf16 v[66:69], v[154:157], v[218:221], 0
	v_mfma_f32_16x16x32_bf16 v[134:137], v[150:153], v[166:169], v[134:137]
	v_mfma_f32_16x16x32_bf16 v[130:133], v[158:161], v[166:169], v[130:133]
	v_mfma_f32_16x16x32_bf16 v[118:121], v[150:153], v[174:177], v[118:121]
	v_mfma_f32_16x16x32_bf16 v[114:117], v[158:161], v[174:177], v[114:117]
	v_mfma_f32_16x16x32_bf16 v[86:89], v[150:153], v[182:185], v[86:89]
	v_mfma_f32_16x16x32_bf16 v[82:85], v[158:161], v[182:185], v[82:85]
	v_mfma_f32_16x16x32_bf16 v[70:73], v[150:153], v[240:243], v[70:73]
	v_mfma_f32_16x16x32_bf16 v[66:69], v[158:161], v[240:243], v[66:69]
	s_setprio 0
	s_barrier
	s_add_i32 s20, s61, s79
	v_lshl_add_u64 v[204:205], s[70:71], 0, v[0:1]
	s_mov_b32 m0, s20
	ds_read_b128 v[162:165], v227 offset:16384
	ds_read_b128 v[166:169], v227 offset:17408
	ds_read_b128 v[170:173], v227 offset:18432
	ds_read_b128 v[174:177], v227 offset:19456
	ds_read_b128 v[178:181], v227 offset:20480
	ds_read_b128 v[182:185], v227 offset:21504
	ds_read_b128 v[218:221], v227 offset:22528
	ds_read_b128 v[240:243], v227 offset:23552
	global_load_lds_dwordx4 v[204:205], off
	s_add_i32 m0, s20, 0x2000
	s_add_u32 s20, s70, 0x40000
	v_lshl_add_u64 v[234:235], s[70:71], 0, v[186:187]
	s_addc_u32 s21, s71, 0
	s_add_i32 s61, s63, s79
	global_load_lds_dwordx4 v[234:235], off
	v_lshl_add_u64 v[244:245], s[20:21], 0, v[0:1]
	s_mov_b32 m0, s61
	v_lshl_add_u64 v[246:247], vcc, 0, v[188:189]
	global_load_lds_dwordx4 v[244:245], off
	v_lshl_add_u64 v[244:245], s[20:21], 0, v[186:187]
	s_add_i32 m0, s61, 0x2000
	s_nop 0
	global_load_lds_dwordx4 v[244:245], off
	v_lshl_add_u64 v[244:245], vcc, 0, v[190:191]
	s_mov_b32 m0, s80
	s_nop 0
	global_load_lds_dwordx4 v[244:245], off
	s_mov_b32 m0, s81
	s_nop 0
	global_load_lds_dwordx4 v[246:247], off
	s_waitcnt vmcnt(8)
	s_waitcnt lgkmcnt(0)
	s_barrier
; #define PG8_STAGE(bufoff, gbase, voff) do { _Pragma("unroll") for (int _i = 0; _i < 2; ++_i) \
;         __builtin_amdgcn_global_load_lds((const unsigned*)((const char*)(gbase) + (voff)[_i]), (PG8_LAS unsigned*)(lds + (bufoff) + ldsw + _i * 8192), 16, 0, 0); } while (0)
; #define PG8_LDA(dst, b, h) do { _Pragma("unroll") for (int m = 0; m < 4; ++m) _Pragma("unroll") for (int k = 0; k < 2; ++k) dst[m][k] = *(const PG8_LAS bf16x8*)(lds + PG8_SA(b, h) + aoff + m * 2048 + k * 1024); } while (0)
; #define PG8_LDB(dst, b, h) do { _Pragma("unroll") for (int n = 0; n < 2; ++n) _Pragma("unroll") for (int k = 0; k < 2; ++k) dst[n][k] = *(const PG8_LAS bf16x8*)(lds + PG8_SB(b, h) + boff + n * 2048 + k * 1024); } while (0)
; #define PG8_MMA(ai, bj, At, Bt) do { __builtin_amdgcn_s_setprio(1); _Pragma("unroll") for (int m = 0; m < 4; ++m) _Pragma("unroll") for (int n = 0; n < 2; ++n) _Pragma("unroll") for (int k = 0; k < 2; ++k) \
;         acc[ai][bj][m][n] = __builtin_amdgcn_mfma_f32_16x16x32_bf16(Bt[n][k], At[m][k], acc[ai][bj][m][n], 0, 0, 0); __builtin_amdgcn_s_setprio(0); } while (0)
; #define PG8_WAIT_V(n) asm volatile("s_waitcnt vmcnt(" #n ")" ::: "memory")
; #define PG8_WAIT_L(n) asm volatile("s_waitcnt lgkmcnt(" #n ")" ::: "memory")
; #define PG8_BAR __builtin_amdgcn_s_barrier()
; #define PG8_SCHED __builtin_amdgcn_sched_barrier(0)
; template <class Epi, class Sched, bool ALIGN_EPI = false, bool SP2 = false>
; __device__ __forceinline__ void gemm_phase(PG8_LAS unsigned char* lds, const Gemm g, const Sched& S, const Epi& E) {
;     ...
;             PG8_WAIT_V(8); PG8_WAIT_L(0); PG8_BAR; PG8_MMA(1, 0, At, B0); PG8_MMA(1, 1, At, B1); PG8_BAR; PG8_SCHED;
;             PG8_LDB(B0, 1, 0); PG8_LDB(B1, 1, 1); PG8_SCHED; PG8_LDA(At, 1, 0); PG8_STAGE(PG8_SA(0, 1), a2 + hstepA, voffA);
;             PG8_WAIT_V(8); PG8_WAIT_L(0); PG8_BAR; PG8_MMA(0, 0, At, B0); PG8_MMA(0, 1, At, B1); PG8_BAR; PG8_SCHED;
;             PG8_LDA(At, 1, 1); PG8_STAGE(PG8_SB(1, 0), b3, voffB); PG8_STAGE(PG8_SB(1, 1), b3 + hstepB, voffB); PG8_STAGE(PG8_SA(1, 0), a3, voffA);
	s_setprio 1
	s_waitcnt lgkmcnt(0)
	v_mfma_f32_16x16x32_bf16 v[62:65], v[90:93], v[162:165], 0
	v_mfma_f32_16x16x32_bf16 v[58:61], v[98:101], v[162:165], 0
	v_mfma_f32_16x16x32_bf16 v[46:49], v[90:93], v[170:173], 0
	v_mfma_f32_16x16x32_bf16 v[42:45], v[98:101], v[170:173], 0
	v_mfma_f32_16x16x32_bf16 v[30:33], v[90:93], v[178:181], 0
	v_mfma_f32_16x16x32_bf16 v[26:29], v[98:101], v[178:181], 0
	v_mfma_f32_16x16x32_bf16 v[14:17], v[90:93], v[218:221], 0
	v_mfma_f32_16x16x32_bf16 v[10:13], v[98:101], v[218:221], 0
	v_mfma_f32_16x16x32_bf16 v[62:65], v[94:97], v[166:169], v[62:65]
	v_mfma_f32_16x16x32_bf16 v[58:61], v[102:105], v[166:169], v[58:61]
	v_mfma_f32_16x16x32_bf16 v[46:49], v[94:97], v[174:177], v[46:49]
	v_mfma_f32_16x16x32_bf16 v[42:45], v[102:105], v[174:177], v[42:45]
	v_mfma_f32_16x16x32_bf16 v[30:33], v[94:97], v[182:185], v[30:33]
	v_mfma_f32_16x16x32_bf16 v[26:29], v[102:105], v[182:185], v[26:29]
	v_mfma_f32_16x16x32_bf16 v[14:17], v[94:97], v[240:243], v[14:17]
	v_mfma_f32_16x16x32_bf16 v[10:13], v[102:105], v[240:243], v[10:13]
	s_setprio 0
	s_setprio 1
	v_mfma_f32_16x16x32_bf16 v[54:57], v[146:149], v[162:165], 0
	v_mfma_f32_16x16x32_bf16 v[50:53], v[154:157], v[162:165], 0
	v_mfma_f32_16x16x32_bf16 v[38:41], v[146:149], v[170:173], 0
	v_mfma_f32_16x16x32_bf16 v[34:37], v[154:157], v[170:173], 0
	v_mfma_f32_16x16x32_bf16 v[22:25], v[146:149], v[178:181], 0
	v_mfma_f32_16x16x32_bf16 v[18:21], v[154:157], v[178:181], 0
	v_mfma_f32_16x16x32_bf16 v[6:9], v[146:149], v[218:221], 0
	v_mfma_f32_16x16x32_bf16 v[2:5], v[154:157], v[218:221], 0
	v_mfma_f32_16x16x32_bf16 v[54:57], v[150:153], v[166:169], v[54:57]
	v_mfma_f32_16x16x32_bf16 v[50:53], v[158:161], v[166:169], v[50:53]
	v_mfma_f32_16x16x32_bf16 v[38:41], v[150:153], v[174:177], v[38:41]
	v_mfma_f32_16x16x32_bf16 v[34:37], v[158:161], v[174:177], v[34:37]
	v_mfma_f32_16x16x32_bf16 v[22:25], v[150:153], v[182:185], v[22:25]
	v_mfma_f32_16x16x32_bf16 v[18:21], v[158:161], v[182:185], v[18:21]
	v_mfma_f32_16x16x32_bf16 v[6:9], v[150:153], v[240:243], v[6:9]
	v_mfma_f32_16x16x32_bf16 v[2:5], v[158:161], v[240:243], v[2:5]
	s_setprio 0
	s_barrier
	s_add_i32 s61, 0, 0x18000
	s_add_i32 s63, 0, 0x1c000
	v_add_u32_e32 v102, s61, v222
	v_add_u32_e32 v158, s63, v222
	ds_read_b128 v[90:93], v102
	ds_read_b128 v[94:97], v102 offset:1024
	ds_read_b128 v[98:101], v102 offset:2048
	ds_read_b128 v[102:105], v102 offset:3072
	ds_read_b128 v[146:149], v158
	ds_read_b128 v[150:153], v158 offset:1024
	ds_read_b128 v[154:157], v158 offset:2048
	ds_read_b128 v[158:161], v158 offset:3072
	s_add_u32 s20, vcc_lo, 0x40000
	s_addc_u32 s21, vcc_hi, 0
	s_mov_b32 m0, s82
	v_lshl_add_u64 v[248:249], s[20:21], 0, v[190:191]
	ds_read_b128 v[162:165], v227 offset:32768
	ds_read_b128 v[166:169], v227 offset:33792
	ds_read_b128 v[170:173], v227 offset:34816
	ds_read_b128 v[174:177], v227 offset:35840
	ds_read_b128 v[178:181], v227 offset:36864
	ds_read_b128 v[182:185], v227 offset:37888
	ds_read_b128 v[218:221], v227 offset:38912
	ds_read_b128 v[240:243], v227 offset:39936
	global_load_lds_dwordx4 v[248:249], off
	v_lshl_add_u64 v[248:249], s[20:21], 0, v[188:189]
	s_mov_b32 m0, s83
	s_nop 0
	global_load_lds_dwordx4 v[248:249], off
	s_waitcnt vmcnt(8)
	s_waitcnt lgkmcnt(0)
	s_barrier
	s_setprio 1
	s_waitcnt lgkmcnt(0)
	v_mfma_f32_16x16x32_bf16 v[142:145], v[90:93], v[162:165], v[142:145]
	v_mfma_f32_16x16x32_bf16 v[138:141], v[98:101], v[162:165], v[138:141]
	v_mfma_f32_16x16x32_bf16 v[126:129], v[90:93], v[170:173], v[126:129]
	v_mfma_f32_16x16x32_bf16 v[122:125], v[98:101], v[170:173], v[122:125]
	v_mfma_f32_16x16x32_bf16 v[110:113], v[90:93], v[178:181], v[110:113]
	v_mfma_f32_16x16x32_bf16 v[106:109], v[98:101], v[178:181], v[106:109]
	v_mfma_f32_16x16x32_bf16 v[78:81], v[90:93], v[218:221], v[78:81]
	v_mfma_f32_16x16x32_bf16 v[74:77], v[98:101], v[218:221], v[74:77]
	v_mfma_f32_16x16x32_bf16 v[142:145], v[94:97], v[166:169], v[142:145]
	v_mfma_f32_16x16x32_bf16 v[138:141], v[102:105], v[166:169], v[138:141]
	v_mfma_f32_16x16x32_bf16 v[126:129], v[94:97], v[174:177], v[126:129]
	v_mfma_f32_16x16x32_bf16 v[122:125], v[102:105], v[174:177], v[122:125]
	v_mfma_f32_16x16x32_bf16 v[110:113], v[94:97], v[182:185], v[110:113]
	v_mfma_f32_16x16x32_bf16 v[106:109], v[102:105], v[182:185], v[106:109]
	v_mfma_f32_16x16x32_bf16 v[78:81], v[94:97], v[240:243], v[78:81]
	v_mfma_f32_16x16x32_bf16 v[74:77], v[102:105], v[240:243], v[74:77]
	s_setprio 0
	s_setprio 1
	v_mfma_f32_16x16x32_bf16 v[134:137], v[146:149], v[162:165], v[134:137]
	v_mfma_f32_16x16x32_bf16 v[130:133], v[154:157], v[162:165], v[130:133]
	v_mfma_f32_16x16x32_bf16 v[118:121], v[146:149], v[170:173], v[118:121]
	v_mfma_f32_16x16x32_bf16 v[114:117], v[154:157], v[170:173], v[114:117]
	v_mfma_f32_16x16x32_bf16 v[86:89], v[146:149], v[178:181], v[86:89]
	v_mfma_f32_16x16x32_bf16 v[82:85], v[154:157], v[178:181], v[82:85]
	v_mfma_f32_16x16x32_bf16 v[70:73], v[146:149], v[218:221], v[70:73]
	v_mfma_f32_16x16x32_bf16 v[66:69], v[154:157], v[218:221], v[66:69]
	v_mfma_f32_16x16x32_bf16 v[134:137], v[150:153], v[166:169], v[134:137]
	v_mfma_f32_16x16x32_bf16 v[130:133], v[158:161], v[166:169], v[130:133]
	v_mfma_f32_16x16x32_bf16 v[118:121], v[150:153], v[174:177], v[118:121]
	v_mfma_f32_16x16x32_bf16 v[114:117], v[158:161], v[174:177], v[114:117]
	v_mfma_f32_16x16x32_bf16 v[86:89], v[150:153], v[182:185], v[86:89]
	v_mfma_f32_16x16x32_bf16 v[82:85], v[158:161], v[182:185], v[82:85]
	v_mfma_f32_16x16x32_bf16 v[70:73], v[150:153], v[240:243], v[70:73]
	v_mfma_f32_16x16x32_bf16 v[66:69], v[158:161], v[240:243], v[66:69]
	s_setprio 0
	s_barrier
; #define PG8_STAGE(bufoff, gbase, voff) do { _Pragma("unroll") for (int _i = 0; _i < 2; ++_i) \
;         __builtin_amdgcn_global_load_lds((const unsigned*)((const char*)(gbase) + (voff)[_i]), (PG8_LAS unsigned*)(lds + (bufoff) + ldsw + _i * 8192), 16, 0, 0); } while (0)
; #define PG8_LDA(dst, b, h) do { _Pragma("unroll") for (int m = 0; m < 4; ++m) _Pragma("unroll") for (int k = 0; k < 2; ++k) dst[m][k] = *(const PG8_LAS bf16x8*)(lds + PG8_SA(b, h) + aoff + m * 2048 + k * 1024); } while (0)
; #define PG8_MMA(ai, bj, At, Bt) do { __builtin_amdgcn_s_setprio(1); _Pragma("unroll") for (int m = 0; m < 4; ++m) _Pragma("unroll") for (int n = 0; n < 2; ++n) _Pragma("unroll") for (int k = 0; k < 2; ++k) \
;         acc[ai][bj][m][n] = __builtin_amdgcn_mfma_f32_16x16x32_bf16(Bt[n][k], At[m][k], acc[ai][bj][m][n], 0, 0, 0); __builtin_amdgcn_s_setprio(0); } while (0)
; #define PG8_WAIT_V(n) asm volatile("s_waitcnt vmcnt(" #n ")" ::: "memory")
; #define PG8_WAIT_L(n) asm volatile("s_waitcnt lgkmcnt(" #n ")" ::: "memory")
; #define PG8_BAR __builtin_amdgcn_s_barrier()
; #define PG8_SCHED __builtin_amdgcn_sched_barrier(0)
; template <class Epi, class Sched, bool ALIGN_EPI = false, bool SP2 = false>
; __device__ __forceinline__ void gemm_phase(PG8_LAS unsigned char* lds, const Gemm g, const Sched& S, const Epi& E) {
;     ...
;         for (int t = 0; t < nt; t += 2) {
;             const bool last = (t == nt - 2);
;     ...
;             PG8_LDA(At, 1, 1); PG8_STAGE(PG8_SB(1, 0), b3, voffB); PG8_STAGE(PG8_SB(1, 1), b3 + hstepB, voffB); PG8_STAGE(PG8_SA(1, 0), a3, voffA);
;             PG8_WAIT_V(8); PG8_WAIT_L(0); PG8_BAR; PG8_MMA(1, 0, At, B0); PG8_MMA(1, 1, At, B1); PG8_BAR; PG8_SCHED;
	s_add_i32 s20, s61, s79
	v_lshl_add_u64 v[204:205], v[204:205], 0, s[22:23]
	s_mov_b32 m0, s20
	ds_read_b128 v[162:165], v227 offset:49152
	ds_read_b128 v[166:169], v227 offset:50176
	ds_read_b128 v[170:173], v227 offset:51200
	ds_read_b128 v[174:177], v227 offset:52224
	ds_read_b128 v[178:181], v227 offset:53248
	ds_read_b128 v[182:185], v227 offset:54272
	ds_read_b128 v[218:221], v227 offset:55296
	ds_read_b128 v[240:243], v227 offset:56320
	global_load_lds_dwordx4 v[204:205], off
	s_add_i32 m0, s20, 0x2000
	s_add_u32 s20, s70, 0x40080
	v_lshl_add_u64 v[204:205], v[234:235], 0, s[22:23]
	s_addc_u32 s21, s71, 0
	s_add_i32 s61, s63, s79
	global_load_lds_dwordx4 v[204:205], off
	v_lshl_add_u64 v[204:205], s[20:21], 0, v[0:1]
	s_mov_b32 m0, s61
	s_nop 0
	global_load_lds_dwordx4 v[204:205], off
	v_lshl_add_u64 v[204:205], s[20:21], 0, v[186:187]
	s_add_i32 m0, s61, 0x2000
	s_nop 0
	global_load_lds_dwordx4 v[204:205], off
	v_lshl_add_u64 v[204:205], v[244:245], 0, s[22:23]
	s_mov_b32 m0, s86
	s_nop 0
	global_load_lds_dwordx4 v[204:205], off
	v_lshl_add_u64 v[204:205], v[246:247], 0, s[22:23]
	s_mov_b32 m0, s87
	s_nop 0
	global_load_lds_dwordx4 v[204:205], off
	s_waitcnt vmcnt(8)
	s_waitcnt lgkmcnt(0)
	s_barrier
	s_setprio 1
	s_waitcnt lgkmcnt(0)
	v_mfma_f32_16x16x32_bf16 v[62:65], v[90:93], v[162:165], v[62:65]
	v_mfma_f32_16x16x32_bf16 v[58:61], v[98:101], v[162:165], v[58:61]
	v_mfma_f32_16x16x32_bf16 v[46:49], v[90:93], v[170:173], v[46:49]
	v_mfma_f32_16x16x32_bf16 v[42:45], v[98:101], v[170:173], v[42:45]
	v_mfma_f32_16x16x32_bf16 v[30:33], v[90:93], v[178:181], v[30:33]
	v_mfma_f32_16x16x32_bf16 v[26:29], v[98:101], v[178:181], v[26:29]
	v_mfma_f32_16x16x32_bf16 v[14:17], v[90:93], v[218:221], v[14:17]
	v_mfma_f32_16x16x32_bf16 v[10:13], v[98:101], v[218:221], v[10:13]
	v_mfma_f32_16x16x32_bf16 v[62:65], v[94:97], v[166:169], v[62:65]
	v_mfma_f32_16x16x32_bf16 v[58:61], v[102:105], v[166:169], v[58:61]
	v_mfma_f32_16x16x32_bf16 v[46:49], v[94:97], v[174:177], v[46:49]
	v_mfma_f32_16x16x32_bf16 v[42:45], v[102:105], v[174:177], v[42:45]
	v_mfma_f32_16x16x32_bf16 v[30:33], v[94:97], v[182:185], v[30:33]
	v_mfma_f32_16x16x32_bf16 v[26:29], v[102:105], v[182:185], v[26:29]
	v_mfma_f32_16x16x32_bf16 v[14:17], v[94:97], v[240:243], v[14:17]
	v_mfma_f32_16x16x32_bf16 v[10:13], v[102:105], v[240:243], v[10:13]
	s_setprio 0
	s_setprio 1
	v_mfma_f32_16x16x32_bf16 v[54:57], v[146:149], v[162:165], v[54:57]
	v_mfma_f32_16x16x32_bf16 v[50:53], v[154:157], v[162:165], v[50:53]
	v_mfma_f32_16x16x32_bf16 v[38:41], v[146:149], v[170:173], v[38:41]
	v_mfma_f32_16x16x32_bf16 v[34:37], v[154:157], v[170:173], v[34:37]
	v_mfma_f32_16x16x32_bf16 v[22:25], v[146:149], v[178:181], v[22:25]
	v_mfma_f32_16x16x32_bf16 v[18:21], v[154:157], v[178:181], v[18:21]
	v_mfma_f32_16x16x32_bf16 v[6:9], v[146:149], v[218:221], v[6:9]
	v_mfma_f32_16x16x32_bf16 v[2:5], v[154:157], v[218:221], v[2:5]
	v_mfma_f32_16x16x32_bf16 v[54:57], v[150:153], v[166:169], v[54:57]
	v_mfma_f32_16x16x32_bf16 v[50:53], v[158:161], v[166:169], v[50:53]
	v_mfma_f32_16x16x32_bf16 v[38:41], v[150:153], v[174:177], v[38:41]
	v_mfma_f32_16x16x32_bf16 v[34:37], v[158:161], v[174:177], v[34:37]
	v_mfma_f32_16x16x32_bf16 v[22:25], v[150:153], v[182:185], v[22:25]
	v_mfma_f32_16x16x32_bf16 v[18:21], v[158:161], v[182:185], v[18:21]
	v_mfma_f32_16x16x32_bf16 v[6:9], v[150:153], v[240:243], v[6:9]
	v_mfma_f32_16x16x32_bf16 v[2:5], v[158:161], v[240:243], v[2:5]
	s_setprio 0
	s_barrier
	s_add_i32 s60, s60, 2
	s_add_u32 s36, s36, 0x100
	s_addc_u32 s37, s37, 0
	s_add_u32 s54, s54, 0x100
	s_addc_u32 s55, s55, 0
	s_cmp_gt_u32 s60, 13
	s_cbranch_scc1 .Lpk_done_g455

; #define PG8_BAR __builtin_amdgcn_s_barrier()
; template <class Epi, class Sched, bool ALIGN_EPI = false, bool SP2 = false>
; __device__ __forceinline__ void gemm_phase(PG8_LAS unsigned char* lds, const Gemm g, const Sched& S, const Epi& E) {
;     ...
;         }
;         if constexpr (ALIGN_EPI) { if (wr == 0) PG8_BAR; }
.Lpk_done_g455:
	s_and_b64 vcc, exec, s[30:31]
	s_cbranch_vccz .LBB0_458
	s_barrier

; __device__ __forceinline__ void unpack8(const u32x4 w, float (&v)[8]) { v[0] = bf_lo(w.x); v[1] = bf_hi(w.x); v[2] = bf_lo(w.y); v[3] = bf_hi(w.y); v[4] = bf_lo(w.z); v[5] = bf_hi(w.z); v[6] = bf_lo(w.w); v[7] = bf_hi(w.w); }
;     __device__ __forceinline__ void operator()(const f32x4 (&acc)[2][2][4][2], const Unit& u, int wr, int wc, int fr, int fq) const {
;     ...
;         if (tid < 256) { float ss = 0.f;
; #pragma unroll
;             for (int t = 0; t < 4; ++t) ss += __uint_as_float(__hip_atomic_load((unsigned*)(XS + (grow0 + tid) * 4 + t), __ATOMIC_RELAXED, __HIP_MEMORY_SCOPE_AGENT));
;             S[tid] = alpha * rsqrtf(ss * (1.0f / DM) + RMS_EPS); }
;         asm volatile("s_waitcnt vmcnt(0) lgkmcnt(0)" ::: "memory"); __builtin_amdgcn_s_barrier(); asm volatile("" ::: "memory");
; #pragma unroll
;         for (int ai = 0; ai < 2; ++ai)
; #pragma unroll
;             for (int m = 0; m < 4; ++m) { const int rloc = rloc0 + ai * 128 + m * 16; const float rs = S[rloc]; float q2 = 0.f;
;                 u32x4 cur[2]; cur[0] = pre[m][0]; cur[1] = pre[m][1];
;                 if (ai == 0) {
; #pragma unroll
;                     for (int bj = 0; bj < 2; ++bj) pre[m][bj] = *(const u32x4*)(HB + (grow0 + rloc + 128) * DM + colb + bj * 128); }
; #pragma unroll
;                 for (int bj = 0; bj < 2; ++bj) { float h[8]; unpack8(cur[bj], h);
; #pragma unroll
;                     for (int e = 0; e < 4; ++e) { h[e] += acc[ai][bj][m][0][e] * g[bj][0][e] * rs; h[4 + e] += acc[ai][bj][m][1][e] * g[bj][1][e] * rs; }
.LBB0_487:
	s_or_b64 exec, exec, s[70:71]
	s_waitcnt vmcnt(0) lgkmcnt(0)
	s_barrier
	s_and_saveexec_b64 s[62:63], s[40:41]
	s_cbranch_execz .LBB0_489
	v_mov_b32_e32 v221, s37
	s_waitcnt lgkmcnt(0)
	v_lshl_add_u64 v[176:177], v[220:221], 4, s[18:19]
	global_load_dwordx4 v[182:185], v[176:177], off sc1
	s_mov_b32 s9, 0x800000
	s_waitcnt vmcnt(0)
	v_add_f32_e32 v182, 0, v182
	v_add_f32_e32 v182, v182, v183
	v_add_f32_e32 v182, v182, v184
	v_add_f32_e32 v176, v182, v185
	v_fmamk_f32 v176, v176, 0x3a800000, v203
	v_cmp_gt_f32_e32 vcc, s9, v176
	v_mul_f32_e32 v177, 0x4b800000, v176
	s_nop 0
	v_cndmask_b32_e32 v176, v176, v177, vcc
	v_rsq_f32_e32 v176, v176
	s_nop 0
	v_mul_f32_e32 v177, 0x45800000, v176
	v_cndmask_b32_e32 v176, v176, v177, vcc
	ds_write_b32 v252, v176
.LBB0_489:
	s_or_b64 exec, exec, s[62:63]
	v_lshl_add_u64 v[174:175], s[58:59], 0, v[174:175]
	v_lshl_add_u64 v[204:205], v[218:219], 1, v[174:175]
	s_mov_b32 s9, 0x40000
	v_add_co_u32_e32 v176, vcc, s9, v204
	s_waitcnt vmcnt(0) lgkmcnt(0)
	s_barrier
	v_lshl_add_u64 v[174:175], v[204:205], 0, s[24:25]
	s_waitcnt lgkmcnt(0)
	v_addc_co_u32_e32 v177, vcc, 0, v205, vcc
	ds_read_b32 v221, v225
	global_load_dwordx4 v[182:185], v[176:177], off
	s_nop 0
	global_load_dwordx4 v[174:177], v[174:175], off offset:256
	s_waitcnt vmcnt(2)
	v_lshlrev_b32_e32 v241, 16, v180
	v_mul_f32_e32 v138, v138, v98
	v_lshlrev_b32_e32 v234, 16, v178
	v_and_b32_e32 v178, 0xffff0000, v178
	s_waitcnt lgkmcnt(0)
	v_fmac_f32_e32 v241, v138, v221
	v_mul_f32_e32 v138, v143, v103
	v_and_b32_e32 v180, 0xffff0000, v180
	v_fmac_f32_e32 v178, v138, v221
	v_mul_f32_e32 v138, v139, v99
	v_lshlrev_b32_e32 v235, 16, v179
	v_fmac_f32_e32 v180, v138, v221
	v_mul_f32_e32 v138, v144, v104
	v_lshlrev_b32_e32 v242, 16, v181
	v_fmac_f32_e32 v235, v138, v221
	v_mul_f32_e32 v138, v140, v100
	v_and_b32_e32 v179, 0xffff0000, v179
	v_fmac_f32_e32 v242, v138, v221
	v_mul_f32_e32 v138, v145, v105
	v_and_b32_e32 v181, 0xffff0000, v181
	v_mul_f32_e32 v142, v142, v102
	v_fmac_f32_e32 v179, v138, v221
	v_mul_f32_e32 v138, v141, v101
	v_fmac_f32_e32 v234, v142, v221
	v_fmac_f32_e32 v181, v138, v221
	v_cvt_pk_bf16_f32 v138, v234, v178
	v_cvt_pk_bf16_f32 v139, v235, v179
	v_cvt_pk_bf16_f32 v140, v241, v180
	v_cvt_pk_bf16_f32 v141, v242, v181
	global_store_dwordx4 v[204:205], v[138:141], off
	v_lshlrev_b32_e32 v142, 16, v138
	v_lshlrev_b32_e32 v143, 16, v139
	v_and_b32_e32 v138, 0xffff0000, v138
	v_mul_f32_e32 v138, v138, v138
	v_fmac_f32_e32 v138, v142, v142
	v_and_b32_e32 v139, 0xffff0000, v139
	v_fmac_f32_e32 v138, v143, v143
	v_lshlrev_b32_e32 v144, 16, v140
	v_fmac_f32_e32 v138, v139, v139
	v_and_b32_e32 v140, 0xffff0000, v140
	v_fmac_f32_e32 v138, v144, v144
	v_lshlrev_b32_e32 v143, 16, v172
	v_mul_f32_e32 v130, v130, v90
	v_lshlrev_b32_e32 v145, 16, v141
	v_fmac_f32_e32 v138, v140, v140
	v_and_b32_e32 v140, 0xffff0000, v170
	v_fmac_f32_e32 v143, v130, v221
	v_mul_f32_e32 v130, v135, v95
	v_and_b32_e32 v141, 0xffff0000, v141
	v_fmac_f32_e32 v138, v145, v145
	v_and_b32_e32 v144, 0xffff0000, v172
	v_fmac_f32_e32 v140, v130, v221
	v_mul_f32_e32 v130, v131, v91
	v_fmac_f32_e32 v138, v141, v141
	v_lshlrev_b32_e32 v141, 16, v171
	v_fmac_f32_e32 v144, v130, v221
	v_mul_f32_e32 v130, v136, v96
	v_lshlrev_b32_e32 v145, 16, v173
	v_fmac_f32_e32 v141, v130, v221
	v_mul_f32_e32 v130, v132, v92
	v_and_b32_e32 v142, 0xffff0000, v171
	v_fmac_f32_e32 v145, v130, v221
	v_mul_f32_e32 v130, v137, v97
	v_lshlrev_b32_e32 v139, 16, v170
	v_and_b32_e32 v170, 0xffff0000, v173
	v_mul_f32_e32 v134, v134, v94
	v_fmac_f32_e32 v142, v130, v221
	v_mul_f32_e32 v130, v133, v93
	v_fmac_f32_e32 v139, v134, v221
	v_fmac_f32_e32 v170, v130, v221
	v_cvt_pk_bf16_f32 v132, v139, v140
	v_cvt_pk_bf16_f32 v133, v141, v142
	v_cvt_pk_bf16_f32 v134, v143, v144
	v_cvt_pk_bf16_f32 v135, v145, v170
	global_store_dwordx4 v[204:205], v[132:135], off offset:256
	v_lshlrev_b32_e32 v130, 16, v132
	v_and_b32_e32 v131, 0xffff0000, v132
	v_fmac_f32_e32 v138, v130, v130
	v_lshlrev_b32_e32 v136, 16, v133
	v_fmac_f32_e32 v138, v131, v131
	v_and_b32_e32 v137, 0xffff0000, v133
	v_fmac_f32_e32 v138, v136, v136
	v_lshlrev_b32_e32 v139, 16, v134
	v_fmac_f32_e32 v138, v137, v137
	v_and_b32_e32 v140, 0xffff0000, v134
	v_fmac_f32_e32 v138, v139, v139
	v_lshlrev_b32_e32 v141, 16, v135
	v_fmac_f32_e32 v138, v140, v140
	v_and_b32_e32 v142, 0xffff0000, v135
	v_fmac_f32_e32 v138, v141, v141
	v_fmac_f32_e32 v138, v142, v142
	ds_bpermute_b32 v130, v239, v138
	s_waitcnt lgkmcnt(0)
	v_add_f32_e32 v130, v138, v130
	ds_bpermute_b32 v131, v240, v130
	s_and_saveexec_b64 s[54:55], s[44:45]
	s_cbranch_execz .LBB0_491
	s_waitcnt lgkmcnt(0)
	v_add_f32_e32 v130, v130, v131
	ds_write_b32 v224, v130

; __device__ __forceinline__ unsigned cvt_pk_bf16(float lo, float hi) { unsigned r; asm volatile("v_cvt_pk_bf16_f32 %0, %1, %2" : "=v"(r) : "v"(lo), "v"(hi)); return r; }
; __device__ __forceinline__ void unpack8(const u32x4 w, float (&v)[8]) { v[0] = bf_lo(w.x); v[1] = bf_hi(w.x); v[2] = bf_lo(w.y); v[3] = bf_hi(w.y); v[4] = bf_lo(w.z); v[5] = bf_hi(w.z); v[6] = bf_lo(w.w); v[7] = bf_hi(w.w); }
;     __device__ __forceinline__ void operator()(const f32x4 (&acc)[2][2][4][2], const Unit& u, int wr, int wc, int fr, int fq) const {
;     ...
;         for (int ai = 0; ai < 2; ++ai)
; #pragma unroll
;             for (int m = 0; m < 4; ++m) { const int rloc = rloc0 + ai * 128 + m * 16; const float rs = S[rloc]; float q2 = 0.f;
;                 u32x4 cur[2]; cur[0] = pre[m][0]; cur[1] = pre[m][1];
;                 if (ai == 0) {
; #pragma unroll
;                     for (int bj = 0; bj < 2; ++bj) pre[m][bj] = *(const u32x4*)(HB + (grow0 + rloc + 128) * DM + colb + bj * 128); }
; #pragma unroll
;                 for (int bj = 0; bj < 2; ++bj) { float h[8]; unpack8(cur[bj], h);
; #pragma unroll
;                     for (int e = 0; e < 4; ++e) { h[e] += acc[ai][bj][m][0][e] * g[bj][0][e] * rs; h[4 + e] += acc[ai][bj][m][1][e] * g[bj][1][e] * rs; }
;                     if (OUT) { float* op = OUT + (grow0 + rloc) * DM + colb + bj * 128; *(f32x4*)op = (f32x4){h[0], h[1], h[2], h[3]}; *(f32x4*)(op + 4) = (f32x4){h[4], h[5], h[6], h[7]}; }
;                     else { u32x4 w; w.x = cvt_pk_bf16(h[0], h[1]); w.y = cvt_pk_bf16(h[2], h[3]); w.z = cvt_pk_bf16(h[4], h[5]); w.w = cvt_pk_bf16(h[6], h[7]);
;                         *(u32x4*)(HB + (grow0 + rloc) * DM + colb + bj * 128) = w; float qv[8]; unpack8(w, qv);
; #pragma unroll
;                         for (int e = 0; e < 8; ++e) q2 += qv[e] * qv[e]; } }
;                 q2 += __shfl_xor(q2, 16); q2 += __shfl_xor(q2, 32);
;                 if (fq == 0) P[rloc * 4 + wc] = q2; }
.LBB0_497:
	s_or_b64 exec, exec, s[54:55]
	v_lshl_add_u32 v66, v200, 2, s64
	ds_read_b32 v68, v66
	s_waitcnt vmcnt(8)
	v_lshlrev_b32_e32 v73, 16, v184
	v_mul_f32_e32 v58, v58, v98
	v_and_b32_e32 v70, 0xffff0000, v182
	v_and_b32_e32 v74, 0xffff0000, v184
	s_waitcnt lgkmcnt(0)
	v_fmac_f32_e32 v73, v58, v68
	v_mul_f32_e32 v58, v63, v103
	v_fmac_f32_e32 v70, v58, v68
	v_mul_f32_e32 v58, v59, v99
	v_lshlrev_b32_e32 v71, 16, v183
	v_fmac_f32_e32 v74, v58, v68
	v_mul_f32_e32 v58, v64, v104
	v_lshl_add_u64 v[66:67], s[36:37], 0, v[200:201]
	v_lshlrev_b32_e32 v75, 16, v185
	v_fmac_f32_e32 v71, v58, v68
	v_mul_f32_e32 v58, v60, v100
	v_lshlrev_b64 v[66:67], 11, v[66:67]
	v_lshlrev_b32_e32 v69, 16, v182
	v_and_b32_e32 v72, 0xffff0000, v183
	v_mul_f32_e32 v62, v62, v102
	v_fmac_f32_e32 v75, v58, v68
	v_mul_f32_e32 v58, v65, v105
	v_and_b32_e32 v76, 0xffff0000, v185
	v_fmac_f32_e32 v69, v62, v68
	v_fmac_f32_e32 v72, v58, v68
	v_mul_f32_e32 v58, v61, v101
	v_lshl_add_u64 v[62:63], s[58:59], 0, v[66:67]
	v_fmac_f32_e32 v76, v58, v68
	v_cvt_pk_bf16_f32 v58, v69, v70
	v_lshl_add_u64 v[62:63], v[218:219], 1, v[62:63]
	v_cvt_pk_bf16_f32 v59, v71, v72
	v_cvt_pk_bf16_f32 v60, v73, v74
	v_cvt_pk_bf16_f32 v61, v75, v76
	global_store_dwordx4 v[62:63], v[58:61], off
	v_lshlrev_b32_e32 v64, 16, v58
	v_lshlrev_b32_e32 v65, 16, v59
	v_and_b32_e32 v58, 0xffff0000, v58
	v_mul_f32_e32 v58, v58, v58
	v_fmac_f32_e32 v58, v64, v64
	v_and_b32_e32 v59, 0xffff0000, v59
	v_fmac_f32_e32 v58, v65, v65
	v_lshlrev_b32_e32 v66, 16, v60
	v_fmac_f32_e32 v58, v59, v59
	v_and_b32_e32 v60, 0xffff0000, v60
	v_fmac_f32_e32 v58, v66, v66
	v_lshlrev_b32_e32 v65, 16, v176
	v_mul_f32_e32 v50, v50, v90
	v_lshlrev_b32_e32 v67, 16, v61
	v_fmac_f32_e32 v58, v60, v60
	v_and_b32_e32 v60, 0xffff0000, v174
	v_fmac_f32_e32 v65, v50, v68
	v_mul_f32_e32 v50, v55, v95
	v_and_b32_e32 v61, 0xffff0000, v61
	v_fmac_f32_e32 v58, v67, v67
	v_and_b32_e32 v66, 0xffff0000, v176
	v_fmac_f32_e32 v60, v50, v68
	v_mul_f32_e32 v50, v51, v91
	v_fmac_f32_e32 v58, v61, v61
	v_lshlrev_b32_e32 v61, 16, v175
	v_fmac_f32_e32 v66, v50, v68
	v_mul_f32_e32 v50, v56, v96
	v_lshlrev_b32_e32 v67, 16, v177
	v_fmac_f32_e32 v61, v50, v68
	v_mul_f32_e32 v50, v52, v92
	v_and_b32_e32 v64, 0xffff0000, v175
	v_fmac_f32_e32 v67, v50, v68
	v_mul_f32_e32 v50, v57, v97
	v_lshlrev_b32_e32 v59, 16, v174
	v_and_b32_e32 v69, 0xffff0000, v177
	v_mul_f32_e32 v54, v54, v94
	v_fmac_f32_e32 v64, v50, v68
	v_mul_f32_e32 v50, v53, v93
	v_fmac_f32_e32 v59, v54, v68
	v_fmac_f32_e32 v69, v50, v68
	v_cvt_pk_bf16_f32 v52, v59, v60
	v_cvt_pk_bf16_f32 v53, v61, v64
	v_cvt_pk_bf16_f32 v54, v65, v66
	v_cvt_pk_bf16_f32 v55, v67, v69
	global_store_dwordx4 v[62:63], v[52:55], off offset:256
	v_lshlrev_b32_e32 v50, 16, v52
	v_and_b32_e32 v51, 0xffff0000, v52
	v_fmac_f32_e32 v58, v50, v50
	v_lshlrev_b32_e32 v56, 16, v53
	v_fmac_f32_e32 v58, v51, v51
	v_and_b32_e32 v57, 0xffff0000, v53
	v_fmac_f32_e32 v58, v56, v56
	v_lshlrev_b32_e32 v59, 16, v54
	v_fmac_f32_e32 v58, v57, v57
	v_and_b32_e32 v60, 0xffff0000, v54
	v_fmac_f32_e32 v58, v59, v59
	v_lshlrev_b32_e32 v61, 16, v55
	v_fmac_f32_e32 v58, v60, v60
	v_and_b32_e32 v64, 0xffff0000, v55
	v_fmac_f32_e32 v58, v61, v61
	v_fmac_f32_e32 v58, v64, v64
	ds_bpermute_b32 v50, v239, v58
	s_waitcnt lgkmcnt(0)
	v_add_f32_e32 v50, v58, v50
	ds_bpermute_b32 v51, v240, v50
	s_and_saveexec_b64 s[54:55], s[44:45]
	s_cbranch_execz .LBB0_499
	s_waitcnt lgkmcnt(0)
	v_add_f32_e32 v50, v50, v51
	ds_write_b32 v231, v50

; #define PG8_STAGE(bufoff, gbase, voff) do { _Pragma("unroll") for (int _i = 0; _i < 2; ++_i) \
;         __builtin_amdgcn_global_load_lds((const unsigned*)((const char*)(gbase) + (voff)[_i]), (PG8_LAS unsigned*)(lds + (bufoff) + ldsw + _i * 8192), 16, 0, 0); } while (0)
; #define PG8_LDA(dst, b, h) do { _Pragma("unroll") for (int m = 0; m < 4; ++m) _Pragma("unroll") for (int k = 0; k < 2; ++k) dst[m][k] = *(const PG8_LAS bf16x8*)(lds + PG8_SA(b, h) + aoff + m * 2048 + k * 1024); } while (0)
; #define PG8_LDB(dst, b, h) do { _Pragma("unroll") for (int n = 0; n < 2; ++n) _Pragma("unroll") for (int k = 0; k < 2; ++k) dst[n][k] = *(const PG8_LAS bf16x8*)(lds + PG8_SB(b, h) + boff + n * 2048 + k * 1024); } while (0)
; #define PG8_WAIT_V(n) asm volatile("s_waitcnt vmcnt(" #n ")" ::: "memory")
; #define PG8_BAR __builtin_amdgcn_s_barrier()
; template <class Epi, class Sched, bool ALIGN_EPI = false, bool SP2 = false>
; __device__ __forceinline__ void gemm_phase(PG8_LAS unsigned char* lds, const Gemm g, const Sched& S, const Epi& E) {
;     ...
;         const char* nA = has_next ? (const char*)g.A + (size_t)nxt.pm * tstepA + (size_t)nxt.pb * g.sA : cA; const char* nB = has_next ? (const char*)g.Bt + (size_t)nxt.pn * tstepB + (size_t)nxt.pb * g.sB : cB;
;         for (int t = 0; t < nt; t += 2) {
;             const bool last = (t == nt - 2);
;             const char* a1 = cA + (size_t)(t + 1) * kstep;
;             const char* a2 = last ? nA : cA + (size_t)(t + 2) * kstep; const char* b2 = last ? nB : cB + (size_t)(t + 2) * kstep;
;             const char* a3 = a2 + kstep; const char* b3 = b2 + kstep;
;             if (last && has_next) S.a_ready(nxt);
;             if constexpr (SP2) {
;             PG8_LDB(B0, 0, 0); PG8_LDB(B1, 0, 1); PG8_SCHED; PG8_LDA(At, 0, 0); PG8_STAGE(PG8_SA(1, 1), a1 + hstepA, voffA);
;             PG8_WAIT_V(8); PG8_WAIT_L(0); PG8_BAR; PG8_MMA(0, 0, At, B0); PG8_MMA(0, 1, At, B1); PG8_BAR; PG8_SCHED;
;             PG8_LDA(At, 0, 1); PG8_STAGE(PG8_SB(0, 0), b2, voffB); PG8_STAGE(PG8_SB(0, 1), b2 + hstepB, voffB); PG8_STAGE(PG8_SA(0, 0), a2, voffA);
;     ...
; #pragma unroll
;         for (int a = 0; a < 2; ++a)
; #pragma unroll
;             for (int b = 0; b < 2; ++b)
; #pragma unroll
;                 for (int m = 0; m < 4; ++m)
; #pragma unroll
;                     for (int n = 0; n < 2; ++n) acc[a][b][m][n] = (f32x4){0.f, 0.f, 0.f, 0.f};
.LBB0_596:
	s_ashr_i32 s35, s34, 31
	s_lshl_b64 s[36:37], s[34:35], 19
	s_add_u32 s38, s0, s36
	s_addc_u32 s39, s1, s37
	s_and_b64 s[36:37], s[42:43], exec
	s_cselect_b32 s35, s39, s9
	s_cselect_b32 s62, s38, s8
	s_ashr_i32 s31, s30, 31
	s_lshl_b64 s[36:37], s[30:31], 19
	s_add_u32 s46, s52, s36
	s_addc_u32 s47, s53, s37
	s_and_b64 s[36:37], s[42:43], exec
	s_cselect_b32 s31, s47, s15
	s_cselect_b32 s63, s46, s14
	s_add_u32 s8, s8, 0x40080
	s_addc_u32 s9, s9, 0
	s_add_u32 s70, s14, 0x100
	s_addc_u32 s71, s15, 0
	s_mov_b32 s78, -2
	s_add_u32 s14, s8, 0xfffc0080
	s_addc_u32 s15, s9, -1
	s_add_i32 s20, 0, 0x10000
	s_cmp_eq_u32 s78, 12
	s_cselect_b32 s37, s35, s15
	s_cselect_b32 s36, s62, s14
	v_add_u32_e32 v0, s20, v161
	s_cselect_b32 s15, s31, s71
	s_cselect_b32 s14, s63, s70
	s_add_i32 s21, 0, 0x14000
	ds_read_b128 v[146:149], v0
	ds_read_b128 v[150:153], v0 offset:1024
	ds_read_b128 v[154:157], v0 offset:2048
	ds_read_b128 v[164:167], v0 offset:3072
	v_add_u32_e32 v0, s21, v161
	ds_read_b128 v[168:171], v0
	ds_read_b128 v[172:175], v0 offset:1024
	ds_read_b128 v[176:179], v0 offset:2048
	ds_read_b128 v[180:183], v0 offset:3072
	v_lshl_add_u64 v[158:159], s[8:9], 0, v[142:143]
	s_add_i32 m0, s54, 0xc000
	ds_read_b128 v[184:187], v163
	ds_read_b128 v[188:191], v163 offset:1024
	ds_read_b128 v[192:195], v163 offset:2048
	ds_read_b128 v[196:199], v163 offset:3072
	ds_read_b128 v[208:211], v163 offset:4096
	ds_read_b128 v[212:215], v163 offset:5120
	ds_read_b128 v[216:219], v163 offset:6144
	ds_read_b128 v[220:223], v163 offset:7168
	global_load_lds_dwordx4 v[158:159], off
	v_lshl_add_u64 v[158:159], s[8:9], 0, v[144:145]
	s_add_i32 m0, s54, 0xe000
	s_nop 0
	global_load_lds_dwordx4 v[158:159], off
	s_waitcnt vmcnt(8)
	s_waitcnt lgkmcnt(0)
	s_barrier
	s_setprio 1
	s_waitcnt lgkmcnt(0)
	v_mfma_f32_16x16x32_bf16 v[126:129], v[146:149], v[184:187], 0
	v_mfma_f32_16x16x32_bf16 v[122:125], v[154:157], v[184:187], 0
	v_mfma_f32_16x16x32_bf16 v[110:113], v[146:149], v[192:195], 0
	v_mfma_f32_16x16x32_bf16 v[106:109], v[154:157], v[192:195], 0
	v_mfma_f32_16x16x32_bf16 v[94:97], v[146:149], v[208:211], 0
	v_mfma_f32_16x16x32_bf16 v[90:93], v[154:157], v[208:211], 0
	v_mfma_f32_16x16x32_bf16 v[78:81], v[146:149], v[216:219], 0
	v_mfma_f32_16x16x32_bf16 v[74:77], v[154:157], v[216:219], 0
	v_mfma_f32_16x16x32_bf16 v[126:129], v[150:153], v[188:191], v[126:129]
	v_mfma_f32_16x16x32_bf16 v[122:125], v[164:167], v[188:191], v[122:125]
	v_mfma_f32_16x16x32_bf16 v[110:113], v[150:153], v[196:199], v[110:113]
	v_mfma_f32_16x16x32_bf16 v[106:109], v[164:167], v[196:199], v[106:109]
	v_mfma_f32_16x16x32_bf16 v[94:97], v[150:153], v[212:215], v[94:97]
	v_mfma_f32_16x16x32_bf16 v[90:93], v[164:167], v[212:215], v[90:93]
	v_mfma_f32_16x16x32_bf16 v[78:81], v[150:153], v[220:223], v[78:81]
	v_mfma_f32_16x16x32_bf16 v[74:77], v[164:167], v[220:223], v[74:77]
	s_setprio 0
	s_setprio 1
	v_mfma_f32_16x16x32_bf16 v[118:121], v[168:171], v[184:187], 0
	v_mfma_f32_16x16x32_bf16 v[114:117], v[176:179], v[184:187], 0
	v_mfma_f32_16x16x32_bf16 v[102:105], v[168:171], v[192:195], 0
	v_mfma_f32_16x16x32_bf16 v[98:101], v[176:179], v[192:195], 0
	v_mfma_f32_16x16x32_bf16 v[86:89], v[168:171], v[208:211], 0
	v_mfma_f32_16x16x32_bf16 v[82:85], v[176:179], v[208:211], 0
	v_mfma_f32_16x16x32_bf16 v[70:73], v[168:171], v[216:219], 0
	v_mfma_f32_16x16x32_bf16 v[66:69], v[176:179], v[216:219], 0
	v_mfma_f32_16x16x32_bf16 v[118:121], v[172:175], v[188:191], v[118:121]
	v_mfma_f32_16x16x32_bf16 v[114:117], v[180:183], v[188:191], v[114:117]
	v_mfma_f32_16x16x32_bf16 v[102:105], v[172:175], v[196:199], v[102:105]
	v_mfma_f32_16x16x32_bf16 v[98:101], v[180:183], v[196:199], v[98:101]
	v_mfma_f32_16x16x32_bf16 v[86:89], v[172:175], v[212:215], v[86:89]
	v_mfma_f32_16x16x32_bf16 v[82:85], v[180:183], v[212:215], v[82:85]
	v_mfma_f32_16x16x32_bf16 v[70:73], v[172:175], v[220:223], v[70:73]
	v_mfma_f32_16x16x32_bf16 v[66:69], v[180:183], v[220:223], v[66:69]
	s_setprio 0
	s_barrier
	s_add_i32 s20, s20, s26
	v_lshl_add_u64 v[158:159], s[14:15], 0, v[134:135]
	s_mov_b32 m0, s20
	ds_read_b128 v[184:187], v163 offset:16384
	ds_read_b128 v[188:191], v163 offset:17408
	ds_read_b128 v[192:195], v163 offset:18432
	ds_read_b128 v[196:199], v163 offset:19456
	ds_read_b128 v[208:211], v163 offset:20480
	ds_read_b128 v[212:215], v163 offset:21504
	ds_read_b128 v[216:219], v163 offset:22528
	ds_read_b128 v[220:223], v163 offset:23552
	global_load_lds_dwordx4 v[158:159], off
	s_add_i32 m0, s20, 0x2000
	s_add_u32 s80, s14, 0x40000
	v_lshl_add_u64 v[200:201], s[14:15], 0, v[130:131]
	s_addc_u32 s81, s15, 0
	s_add_i32 s20, s21, s26
	global_load_lds_dwordx4 v[200:201], off
	v_lshl_add_u64 v[224:225], s[80:81], 0, v[134:135]
	s_mov_b32 m0, s20
	v_lshl_add_u64 v[226:227], s[36:37], 0, v[132:133]
	global_load_lds_dwordx4 v[224:225], off
	v_lshl_add_u64 v[224:225], s[80:81], 0, v[130:131]
	s_add_i32 m0, s20, 0x2000
	s_nop 0
	global_load_lds_dwordx4 v[224:225], off
	v_lshl_add_u64 v[224:225], s[36:37], 0, v[136:137]
	s_mov_b32 m0, s54
	s_nop 0
	global_load_lds_dwordx4 v[224:225], off
	s_mov_b32 m0, s55
	s_nop 0
	global_load_lds_dwordx4 v[226:227], off
	s_waitcnt vmcnt(8)
	s_waitcnt lgkmcnt(0)
	s_barrier
; #define PG8_STAGE(bufoff, gbase, voff) do { _Pragma("unroll") for (int _i = 0; _i < 2; ++_i) \
;         __builtin_amdgcn_global_load_lds((const unsigned*)((const char*)(gbase) + (voff)[_i]), (PG8_LAS unsigned*)(lds + (bufoff) + ldsw + _i * 8192), 16, 0, 0); } while (0)
; #define PG8_LDA(dst, b, h) do { _Pragma("unroll") for (int m = 0; m < 4; ++m) _Pragma("unroll") for (int k = 0; k < 2; ++k) dst[m][k] = *(const PG8_LAS bf16x8*)(lds + PG8_SA(b, h) + aoff + m * 2048 + k * 1024); } while (0)
; #define PG8_LDB(dst, b, h) do { _Pragma("unroll") for (int n = 0; n < 2; ++n) _Pragma("unroll") for (int k = 0; k < 2; ++k) dst[n][k] = *(const PG8_LAS bf16x8*)(lds + PG8_SB(b, h) + boff + n * 2048 + k * 1024); } while (0)
; #define PG8_MMA(ai, bj, At, Bt) do { __builtin_amdgcn_s_setprio(1); _Pragma("unroll") for (int m = 0; m < 4; ++m) _Pragma("unroll") for (int n = 0; n < 2; ++n) _Pragma("unroll") for (int k = 0; k < 2; ++k) \
;         acc[ai][bj][m][n] = __builtin_amdgcn_mfma_f32_16x16x32_bf16(Bt[n][k], At[m][k], acc[ai][bj][m][n], 0, 0, 0); __builtin_amdgcn_s_setprio(0); } while (0)
; #define PG8_WAIT_V(n) asm volatile("s_waitcnt vmcnt(" #n ")" ::: "memory")
; #define PG8_WAIT_L(n) asm volatile("s_waitcnt lgkmcnt(" #n ")" ::: "memory")
; #define PG8_BAR __builtin_amdgcn_s_barrier()
; #define PG8_SCHED __builtin_amdgcn_sched_barrier(0)
; template <class Epi, class Sched, bool ALIGN_EPI = false, bool SP2 = false>
; __device__ __forceinline__ void gemm_phase(PG8_LAS unsigned char* lds, const Gemm g, const Sched& S, const Epi& E) {
;     ...
;             PG8_WAIT_V(8); PG8_WAIT_L(0); PG8_BAR; PG8_MMA(1, 0, At, B0); PG8_MMA(1, 1, At, B1); PG8_BAR; PG8_SCHED;
;             PG8_LDB(B0, 1, 0); PG8_LDB(B1, 1, 1); PG8_SCHED; PG8_LDA(At, 1, 0); PG8_STAGE(PG8_SA(0, 1), a2 + hstepA, voffA);
;             PG8_WAIT_V(8); PG8_WAIT_L(0); PG8_BAR; PG8_MMA(0, 0, At, B0); PG8_MMA(0, 1, At, B1); PG8_BAR; PG8_SCHED;
;             PG8_LDA(At, 1, 1); PG8_STAGE(PG8_SB(1, 0), b3, voffB); PG8_STAGE(PG8_SB(1, 1), b3 + hstepB, voffB); PG8_STAGE(PG8_SA(1, 0), a3, voffA);
	s_setprio 1
	s_waitcnt lgkmcnt(0)
	v_mfma_f32_16x16x32_bf16 v[62:65], v[146:149], v[184:187], 0
	v_mfma_f32_16x16x32_bf16 v[58:61], v[154:157], v[184:187], 0
	v_mfma_f32_16x16x32_bf16 v[46:49], v[146:149], v[192:195], 0
	v_mfma_f32_16x16x32_bf16 v[42:45], v[154:157], v[192:195], 0
	v_mfma_f32_16x16x32_bf16 v[30:33], v[146:149], v[208:211], 0
	v_mfma_f32_16x16x32_bf16 v[26:29], v[154:157], v[208:211], 0
	v_mfma_f32_16x16x32_bf16 v[14:17], v[146:149], v[216:219], 0
	v_mfma_f32_16x16x32_bf16 v[10:13], v[154:157], v[216:219], 0
	v_mfma_f32_16x16x32_bf16 v[62:65], v[150:153], v[188:191], v[62:65]
	v_mfma_f32_16x16x32_bf16 v[58:61], v[164:167], v[188:191], v[58:61]
	v_mfma_f32_16x16x32_bf16 v[46:49], v[150:153], v[196:199], v[46:49]
	v_mfma_f32_16x16x32_bf16 v[42:45], v[164:167], v[196:199], v[42:45]
	v_mfma_f32_16x16x32_bf16 v[30:33], v[150:153], v[212:215], v[30:33]
	v_mfma_f32_16x16x32_bf16 v[26:29], v[164:167], v[212:215], v[26:29]
	v_mfma_f32_16x16x32_bf16 v[14:17], v[150:153], v[220:223], v[14:17]
	v_mfma_f32_16x16x32_bf16 v[10:13], v[164:167], v[220:223], v[10:13]
	s_setprio 0
	s_setprio 1
	v_mfma_f32_16x16x32_bf16 v[54:57], v[168:171], v[184:187], 0
	v_mfma_f32_16x16x32_bf16 v[50:53], v[176:179], v[184:187], 0
	v_mfma_f32_16x16x32_bf16 v[38:41], v[168:171], v[192:195], 0
	v_mfma_f32_16x16x32_bf16 v[34:37], v[176:179], v[192:195], 0
	v_mfma_f32_16x16x32_bf16 v[22:25], v[168:171], v[208:211], 0
	v_mfma_f32_16x16x32_bf16 v[18:21], v[176:179], v[208:211], 0
	v_mfma_f32_16x16x32_bf16 v[6:9], v[168:171], v[216:219], 0
	v_mfma_f32_16x16x32_bf16 v[2:5], v[176:179], v[216:219], 0
	v_mfma_f32_16x16x32_bf16 v[54:57], v[172:175], v[188:191], v[54:57]
	v_mfma_f32_16x16x32_bf16 v[50:53], v[180:183], v[188:191], v[50:53]
	v_mfma_f32_16x16x32_bf16 v[38:41], v[172:175], v[196:199], v[38:41]
	v_mfma_f32_16x16x32_bf16 v[34:37], v[180:183], v[196:199], v[34:37]
	v_mfma_f32_16x16x32_bf16 v[22:25], v[172:175], v[212:215], v[22:25]
	v_mfma_f32_16x16x32_bf16 v[18:21], v[180:183], v[212:215], v[18:21]
	v_mfma_f32_16x16x32_bf16 v[6:9], v[172:175], v[220:223], v[6:9]
	v_mfma_f32_16x16x32_bf16 v[2:5], v[180:183], v[220:223], v[2:5]
	s_setprio 0
	s_barrier
	s_add_i32 s20, 0, 0x18000
	v_add_u32_e32 v0, s20, v161
	s_add_i32 s21, 0, 0x1c000
	ds_read_b128 v[146:149], v0
	ds_read_b128 v[150:153], v0 offset:1024
	ds_read_b128 v[154:157], v0 offset:2048
	ds_read_b128 v[164:167], v0 offset:3072
	v_add_u32_e32 v0, s21, v161
	ds_read_b128 v[168:171], v0
	ds_read_b128 v[172:175], v0 offset:1024
	ds_read_b128 v[176:179], v0 offset:2048
	ds_read_b128 v[180:183], v0 offset:3072
	s_add_u32 s36, s36, 0x40000
	s_addc_u32 s37, s37, 0
	s_mov_b32 m0, s56
	v_lshl_add_u64 v[228:229], s[36:37], 0, v[136:137]
	ds_read_b128 v[184:187], v163 offset:32768
	ds_read_b128 v[188:191], v163 offset:33792
	ds_read_b128 v[192:195], v163 offset:34816
	ds_read_b128 v[196:199], v163 offset:35840
	ds_read_b128 v[208:211], v163 offset:36864
	ds_read_b128 v[212:215], v163 offset:37888
	ds_read_b128 v[216:219], v163 offset:38912
	ds_read_b128 v[220:223], v163 offset:39936
	global_load_lds_dwordx4 v[228:229], off
	v_lshl_add_u64 v[228:229], s[36:37], 0, v[132:133]
	s_mov_b32 m0, s57
	s_nop 0
	global_load_lds_dwordx4 v[228:229], off
	s_waitcnt vmcnt(8)
	s_waitcnt lgkmcnt(0)
	s_barrier
	s_setprio 1
	s_waitcnt lgkmcnt(0)
	v_mfma_f32_16x16x32_bf16 v[126:129], v[146:149], v[184:187], v[126:129]
	v_mfma_f32_16x16x32_bf16 v[122:125], v[154:157], v[184:187], v[122:125]
	v_mfma_f32_16x16x32_bf16 v[110:113], v[146:149], v[192:195], v[110:113]
	v_mfma_f32_16x16x32_bf16 v[106:109], v[154:157], v[192:195], v[106:109]
	v_mfma_f32_16x16x32_bf16 v[94:97], v[146:149], v[208:211], v[94:97]
	v_mfma_f32_16x16x32_bf16 v[90:93], v[154:157], v[208:211], v[90:93]
	v_mfma_f32_16x16x32_bf16 v[78:81], v[146:149], v[216:219], v[78:81]
	v_mfma_f32_16x16x32_bf16 v[74:77], v[154:157], v[216:219], v[74:77]
	v_mfma_f32_16x16x32_bf16 v[126:129], v[150:153], v[188:191], v[126:129]
	v_mfma_f32_16x16x32_bf16 v[122:125], v[164:167], v[188:191], v[122:125]
	v_mfma_f32_16x16x32_bf16 v[110:113], v[150:153], v[196:199], v[110:113]
	v_mfma_f32_16x16x32_bf16 v[106:109], v[164:167], v[196:199], v[106:109]
	v_mfma_f32_16x16x32_bf16 v[94:97], v[150:153], v[212:215], v[94:97]
	v_mfma_f32_16x16x32_bf16 v[90:93], v[164:167], v[212:215], v[90:93]
	v_mfma_f32_16x16x32_bf16 v[78:81], v[150:153], v[220:223], v[78:81]
	v_mfma_f32_16x16x32_bf16 v[74:77], v[164:167], v[220:223], v[74:77]
	s_setprio 0
	s_setprio 1
	v_mfma_f32_16x16x32_bf16 v[118:121], v[168:171], v[184:187], v[118:121]
	v_mfma_f32_16x16x32_bf16 v[114:117], v[176:179], v[184:187], v[114:117]
	v_mfma_f32_16x16x32_bf16 v[102:105], v[168:171], v[192:195], v[102:105]
	v_mfma_f32_16x16x32_bf16 v[98:101], v[176:179], v[192:195], v[98:101]
	v_mfma_f32_16x16x32_bf16 v[86:89], v[168:171], v[208:211], v[86:89]
	v_mfma_f32_16x16x32_bf16 v[82:85], v[176:179], v[208:211], v[82:85]
	v_mfma_f32_16x16x32_bf16 v[70:73], v[168:171], v[216:219], v[70:73]
	v_mfma_f32_16x16x32_bf16 v[66:69], v[176:179], v[216:219], v[66:69]
	v_mfma_f32_16x16x32_bf16 v[118:121], v[172:175], v[188:191], v[118:121]
	v_mfma_f32_16x16x32_bf16 v[114:117], v[180:183], v[188:191], v[114:117]
	v_mfma_f32_16x16x32_bf16 v[102:105], v[172:175], v[196:199], v[102:105]
	v_mfma_f32_16x16x32_bf16 v[98:101], v[180:183], v[196:199], v[98:101]
	v_mfma_f32_16x16x32_bf16 v[86:89], v[172:175], v[212:215], v[86:89]
	v_mfma_f32_16x16x32_bf16 v[82:85], v[180:183], v[212:215], v[82:85]
	v_mfma_f32_16x16x32_bf16 v[70:73], v[172:175], v[220:223], v[70:73]
	v_mfma_f32_16x16x32_bf16 v[66:69], v[180:183], v[220:223], v[66:69]
	s_setprio 0
	s_barrier
; #define PG8_STAGE(bufoff, gbase, voff) do { _Pragma("unroll") for (int _i = 0; _i < 2; ++_i) \
;         __builtin_amdgcn_global_load_lds((const unsigned*)((const char*)(gbase) + (voff)[_i]), (PG8_LAS unsigned*)(lds + (bufoff) + ldsw + _i * 8192), 16, 0, 0); } while (0)
; #define PG8_LDA(dst, b, h) do { _Pragma("unroll") for (int m = 0; m < 4; ++m) _Pragma("unroll") for (int k = 0; k < 2; ++k) dst[m][k] = *(const PG8_LAS bf16x8*)(lds + PG8_SA(b, h) + aoff + m * 2048 + k * 1024); } while (0)
; #define PG8_MMA(ai, bj, At, Bt) do { __builtin_amdgcn_s_setprio(1); _Pragma("unroll") for (int m = 0; m < 4; ++m) _Pragma("unroll") for (int n = 0; n < 2; ++n) _Pragma("unroll") for (int k = 0; k < 2; ++k) \
;         acc[ai][bj][m][n] = __builtin_amdgcn_mfma_f32_16x16x32_bf16(Bt[n][k], At[m][k], acc[ai][bj][m][n], 0, 0, 0); __builtin_amdgcn_s_setprio(0); } while (0)
; #define PG8_WAIT_V(n) asm volatile("s_waitcnt vmcnt(" #n ")" ::: "memory")
; #define PG8_WAIT_L(n) asm volatile("s_waitcnt lgkmcnt(" #n ")" ::: "memory")
; #define PG8_BAR __builtin_amdgcn_s_barrier()
; #define PG8_SCHED __builtin_amdgcn_sched_barrier(0)
; template <class Epi, class Sched, bool ALIGN_EPI = false, bool SP2 = false>
; __device__ __forceinline__ void gemm_phase(PG8_LAS unsigned char* lds, const Gemm g, const Sched& S, const Epi& E) {
;     ...
;         for (int t = 0; t < nt; t += 2) {
;             const bool last = (t == nt - 2);
;     ...
;             PG8_LDA(At, 1, 1); PG8_STAGE(PG8_SB(1, 0), b3, voffB); PG8_STAGE(PG8_SB(1, 1), b3 + hstepB, voffB); PG8_STAGE(PG8_SA(1, 0), a3, voffA);
;             PG8_WAIT_V(8); PG8_WAIT_L(0); PG8_BAR; PG8_MMA(1, 0, At, B0); PG8_MMA(1, 1, At, B1); PG8_BAR; PG8_SCHED;
	s_add_i32 s20, s20, s26
	v_lshl_add_u64 v[158:159], v[158:159], 0, s[22:23]
	s_mov_b32 m0, s20
	ds_read_b128 v[184:187], v163 offset:49152
	ds_read_b128 v[188:191], v163 offset:50176
	ds_read_b128 v[192:195], v163 offset:51200
	ds_read_b128 v[196:199], v163 offset:52224
	ds_read_b128 v[208:211], v163 offset:53248
	ds_read_b128 v[212:215], v163 offset:54272
	ds_read_b128 v[216:219], v163 offset:55296
	ds_read_b128 v[220:223], v163 offset:56320
	global_load_lds_dwordx4 v[158:159], off
	s_add_i32 m0, s20, 0x2000
	s_add_u32 s14, s14, 0x40080
	v_lshl_add_u64 v[158:159], v[200:201], 0, s[22:23]
	s_addc_u32 s15, s15, 0
	s_add_i32 s20, s21, s26
	global_load_lds_dwordx4 v[158:159], off
	v_lshl_add_u64 v[158:159], s[14:15], 0, v[134:135]
	s_mov_b32 m0, s20
	s_nop 0
	global_load_lds_dwordx4 v[158:159], off
	v_lshl_add_u64 v[158:159], s[14:15], 0, v[130:131]
	s_add_i32 m0, s20, 0x2000
	s_nop 0
	global_load_lds_dwordx4 v[158:159], off
	v_lshl_add_u64 v[158:159], v[224:225], 0, s[22:23]
	s_mov_b32 m0, s58
	s_nop 0
	global_load_lds_dwordx4 v[158:159], off
	v_lshl_add_u64 v[158:159], v[226:227], 0, s[22:23]
	s_mov_b32 m0, s59
	s_nop 0
	global_load_lds_dwordx4 v[158:159], off
	s_waitcnt vmcnt(8)
	s_waitcnt lgkmcnt(0)
	s_barrier
	s_setprio 1
	s_waitcnt lgkmcnt(0)
	v_mfma_f32_16x16x32_bf16 v[62:65], v[146:149], v[184:187], v[62:65]
	v_mfma_f32_16x16x32_bf16 v[58:61], v[154:157], v[184:187], v[58:61]
	v_mfma_f32_16x16x32_bf16 v[46:49], v[146:149], v[192:195], v[46:49]
	v_mfma_f32_16x16x32_bf16 v[42:45], v[154:157], v[192:195], v[42:45]
	v_mfma_f32_16x16x32_bf16 v[30:33], v[146:149], v[208:211], v[30:33]
	v_mfma_f32_16x16x32_bf16 v[26:29], v[154:157], v[208:211], v[26:29]
	v_mfma_f32_16x16x32_bf16 v[14:17], v[146:149], v[216:219], v[14:17]
	v_mfma_f32_16x16x32_bf16 v[10:13], v[154:157], v[216:219], v[10:13]
	v_mfma_f32_16x16x32_bf16 v[62:65], v[150:153], v[188:191], v[62:65]
	v_mfma_f32_16x16x32_bf16 v[58:61], v[164:167], v[188:191], v[58:61]
	v_mfma_f32_16x16x32_bf16 v[46:49], v[150:153], v[196:199], v[46:49]
	v_mfma_f32_16x16x32_bf16 v[42:45], v[164:167], v[196:199], v[42:45]
	v_mfma_f32_16x16x32_bf16 v[30:33], v[150:153], v[212:215], v[30:33]
	v_mfma_f32_16x16x32_bf16 v[26:29], v[164:167], v[212:215], v[26:29]
	v_mfma_f32_16x16x32_bf16 v[14:17], v[150:153], v[220:223], v[14:17]
	v_mfma_f32_16x16x32_bf16 v[10:13], v[164:167], v[220:223], v[10:13]
	s_setprio 0
	s_setprio 1
	v_mfma_f32_16x16x32_bf16 v[54:57], v[168:171], v[184:187], v[54:57]
	v_mfma_f32_16x16x32_bf16 v[50:53], v[176:179], v[184:187], v[50:53]
	v_mfma_f32_16x16x32_bf16 v[38:41], v[168:171], v[192:195], v[38:41]
	v_mfma_f32_16x16x32_bf16 v[34:37], v[176:179], v[192:195], v[34:37]
	v_mfma_f32_16x16x32_bf16 v[22:25], v[168:171], v[208:211], v[22:25]
	v_mfma_f32_16x16x32_bf16 v[18:21], v[176:179], v[208:211], v[18:21]
	v_mfma_f32_16x16x32_bf16 v[6:9], v[168:171], v[216:219], v[6:9]
	v_mfma_f32_16x16x32_bf16 v[2:5], v[176:179], v[216:219], v[2:5]
	v_mfma_f32_16x16x32_bf16 v[54:57], v[172:175], v[188:191], v[54:57]
	v_mfma_f32_16x16x32_bf16 v[50:53], v[180:183], v[188:191], v[50:53]
	v_mfma_f32_16x16x32_bf16 v[38:41], v[172:175], v[196:199], v[38:41]
	v_mfma_f32_16x16x32_bf16 v[34:37], v[180:183], v[196:199], v[34:37]
	v_mfma_f32_16x16x32_bf16 v[22:25], v[172:175], v[212:215], v[22:25]
	v_mfma_f32_16x16x32_bf16 v[18:21], v[180:183], v[212:215], v[18:21]
	v_mfma_f32_16x16x32_bf16 v[6:9], v[172:175], v[220:223], v[6:9]
	v_mfma_f32_16x16x32_bf16 v[2:5], v[180:183], v[220:223], v[2:5]
	s_setprio 0
	s_barrier
	s_add_i32 s78, s78, 2
	s_add_u32 s8, s8, 0x100
	s_addc_u32 s9, s9, 0
	s_add_u32 s70, s70, 0x100
	s_addc_u32 s71, s71, 0
	s_cmp_gt_u32 s78, 13
	s_cbranch_scc1 .Lpk_done_g597

; #define PG8_BAR __builtin_amdgcn_s_barrier()
; template <class Epi, class Sched, bool ALIGN_EPI = false, bool SP2 = false>
; __device__ __forceinline__ void gemm_phase(PG8_LAS unsigned char* lds, const Gemm g, const Sched& S, const Epi& E) {
;     ...
;         }
;         if constexpr (ALIGN_EPI) { if (wr == 0) PG8_BAR; }
.Lpk_done_g597:
	s_and_b64 vcc, exec, s[18:19]
	s_cbranch_vccz .LBB0_600
	s_barrier

; #define PG8_STAGE(bufoff, gbase, voff) do { _Pragma("unroll") for (int _i = 0; _i < 2; ++_i) \
;         __builtin_amdgcn_global_load_lds((const unsigned*)((const char*)(gbase) + (voff)[_i]), (PG8_LAS unsigned*)(lds + (bufoff) + ldsw + _i * 8192), 16, 0, 0); } while (0)
; #define PG8_LDA(dst, b, h) do { _Pragma("unroll") for (int m = 0; m < 4; ++m) _Pragma("unroll") for (int k = 0; k < 2; ++k) dst[m][k] = *(const PG8_LAS bf16x8*)(lds + PG8_SA(b, h) + aoff + m * 2048 + k * 1024); } while (0)
; #define PG8_LDB(dst, b, h) do { _Pragma("unroll") for (int n = 0; n < 2; ++n) _Pragma("unroll") for (int k = 0; k < 2; ++k) dst[n][k] = *(const PG8_LAS bf16x8*)(lds + PG8_SB(b, h) + boff + n * 2048 + k * 1024); } while (0)
; #define PG8_WAIT_V(n) asm volatile("s_waitcnt vmcnt(" #n ")" ::: "memory")
; #define PG8_BAR __builtin_amdgcn_s_barrier()
; template <class Epi, class Sched, bool ALIGN_EPI = false, bool SP2 = false>
; __device__ __forceinline__ void gemm_phase(PG8_LAS unsigned char* lds, const Gemm g, const Sched& S, const Epi& E) {
;     ...
;         const char* nA = has_next ? (const char*)g.A + (size_t)nxt.pm * tstepA + (size_t)nxt.pb * g.sA : cA; const char* nB = has_next ? (const char*)g.Bt + (size_t)nxt.pn * tstepB + (size_t)nxt.pb * g.sB : cB;
;         for (int t = 0; t < nt; t += 2) {
;             const bool last = (t == nt - 2);
;             const char* a1 = cA + (size_t)(t + 1) * kstep;
;             const char* a2 = last ? nA : cA + (size_t)(t + 2) * kstep; const char* b2 = last ? nB : cB + (size_t)(t + 2) * kstep;
;             const char* a3 = a2 + kstep; const char* b3 = b2 + kstep;
;             if (last && has_next) S.a_ready(nxt);
;             if constexpr (SP2) {
;             PG8_LDB(B0, 0, 0); PG8_LDB(B1, 0, 1); PG8_SCHED; PG8_LDA(At, 0, 0); PG8_STAGE(PG8_SA(1, 1), a1 + hstepA, voffA);
;             PG8_WAIT_V(8); PG8_WAIT_L(0); PG8_BAR; PG8_MMA(0, 0, At, B0); PG8_MMA(0, 1, At, B1); PG8_BAR; PG8_SCHED;
;             PG8_LDA(At, 0, 1); PG8_STAGE(PG8_SB(0, 0), b2, voffB); PG8_STAGE(PG8_SB(0, 1), b2 + hstepB, voffB); PG8_STAGE(PG8_SA(0, 0), a2, voffA);
;     ...
; #pragma unroll
;         for (int a = 0; a < 2; ++a)
; #pragma unroll
;             for (int b = 0; b < 2; ++b)
; #pragma unroll
;                 for (int m = 0; m < 4; ++m)
; #pragma unroll
;                     for (int n = 0; n < 2; ++n) acc[a][b][m][n] = (f32x4){0.f, 0.f, 0.f, 0.f};
.LBB0_782:
	s_lshl_b64 s[28:29], s[12:13], 18
	s_add_u32 s28, s43, s28
	s_addc_u32 s29, s44, s29
	s_and_b64 s[36:37], s[16:17], exec
	s_cselect_b32 s13, s29, s35
	s_cselect_b32 s60, s28, s34
	s_add_u32 s61, s34, 0x100
	s_addc_u32 s62, s35, 0
	s_mov_b32 s63, -2
	s_add_u32 s34, s30, 0x100
	s_addc_u32 s35, s31, 0
	s_add_i32 s20, 0, 0x10000
	s_cmp_eq_u32 s63, 4
	s_cselect_b32 s39, s19, s35
	s_cselect_b32 s38, s18, s34
	v_add_u32_e32 v145, s20, v143
	s_cselect_b32 s37, s13, s62
	s_cselect_b32 s36, s60, s61
	s_add_i32 s21, 0, 0x14000
	ds_read_b128 v[146:149], v145
	ds_read_b128 v[150:153], v145 offset:1024
	ds_read_b128 v[154:157], v145 offset:2048
	ds_read_b128 v[158:161], v145 offset:3072
	v_add_u32_e32 v145, s21, v143
	ds_read_b128 v[162:165], v145
	ds_read_b128 v[166:169], v145 offset:1024
	ds_read_b128 v[170:173], v145 offset:2048
	ds_read_b128 v[174:177], v145 offset:3072
	v_lshl_add_u64 v[216:217], s[30:31], 0, v[138:139]
	s_add_i32 m0, s52, 0xc000
	ds_read_b128 v[178:181], v144
	ds_read_b128 v[182:185], v144 offset:1024
	ds_read_b128 v[186:189], v144 offset:2048
	ds_read_b128 v[190:193], v144 offset:3072
	ds_read_b128 v[194:197], v144 offset:4096
	ds_read_b128 v[198:201], v144 offset:5120
	ds_read_b128 v[208:211], v144 offset:6144
	ds_read_b128 v[212:215], v144 offset:7168
	global_load_lds_dwordx4 v[216:217], off
	v_lshl_add_u64 v[216:217], s[30:31], 0, v[140:141]
	s_add_i32 m0, s52, 0xe000
	s_nop 0
	global_load_lds_dwordx4 v[216:217], off
	s_waitcnt vmcnt(8)
	s_waitcnt lgkmcnt(0)
	s_barrier
	s_setprio 1
	s_waitcnt lgkmcnt(0)
	v_mfma_f32_16x16x32_bf16 v[126:129], v[146:149], v[178:181], 0
	v_mfma_f32_16x16x32_bf16 v[122:125], v[154:157], v[178:181], 0
	v_mfma_f32_16x16x32_bf16 v[118:121], v[146:149], v[186:189], 0
	v_mfma_f32_16x16x32_bf16 v[114:117], v[154:157], v[186:189], 0
	v_mfma_f32_16x16x32_bf16 v[106:109], v[146:149], v[194:197], 0
	v_mfma_f32_16x16x32_bf16 v[98:101], v[154:157], v[194:197], 0
	v_mfma_f32_16x16x32_bf16 v[90:93], v[146:149], v[208:211], 0
	v_mfma_f32_16x16x32_bf16 v[82:85], v[154:157], v[208:211], 0
	v_mfma_f32_16x16x32_bf16 v[126:129], v[150:153], v[182:185], v[126:129]
	v_mfma_f32_16x16x32_bf16 v[122:125], v[158:161], v[182:185], v[122:125]
	v_mfma_f32_16x16x32_bf16 v[118:121], v[150:153], v[190:193], v[118:121]
	v_mfma_f32_16x16x32_bf16 v[114:117], v[158:161], v[190:193], v[114:117]
	v_mfma_f32_16x16x32_bf16 v[106:109], v[150:153], v[198:201], v[106:109]
	v_mfma_f32_16x16x32_bf16 v[98:101], v[158:161], v[198:201], v[98:101]
	v_mfma_f32_16x16x32_bf16 v[90:93], v[150:153], v[212:215], v[90:93]
	v_mfma_f32_16x16x32_bf16 v[82:85], v[158:161], v[212:215], v[82:85]
	s_setprio 0
	s_setprio 1
	v_mfma_f32_16x16x32_bf16 v[110:113], v[162:165], v[178:181], 0
	v_mfma_f32_16x16x32_bf16 v[102:105], v[170:173], v[178:181], 0
	v_mfma_f32_16x16x32_bf16 v[94:97], v[162:165], v[186:189], 0
	v_mfma_f32_16x16x32_bf16 v[86:89], v[170:173], v[186:189], 0
	v_mfma_f32_16x16x32_bf16 v[78:81], v[162:165], v[194:197], 0
	v_mfma_f32_16x16x32_bf16 v[74:77], v[170:173], v[194:197], 0
	v_mfma_f32_16x16x32_bf16 v[70:73], v[162:165], v[208:211], 0
	v_mfma_f32_16x16x32_bf16 v[66:69], v[170:173], v[208:211], 0
	v_mfma_f32_16x16x32_bf16 v[110:113], v[166:169], v[182:185], v[110:113]
	v_mfma_f32_16x16x32_bf16 v[102:105], v[174:177], v[182:185], v[102:105]
	v_mfma_f32_16x16x32_bf16 v[94:97], v[166:169], v[190:193], v[94:97]
	v_mfma_f32_16x16x32_bf16 v[86:89], v[174:177], v[190:193], v[86:89]
	v_mfma_f32_16x16x32_bf16 v[78:81], v[166:169], v[198:201], v[78:81]
	v_mfma_f32_16x16x32_bf16 v[74:77], v[174:177], v[198:201], v[74:77]
	v_mfma_f32_16x16x32_bf16 v[70:73], v[166:169], v[212:215], v[70:73]
	v_mfma_f32_16x16x32_bf16 v[66:69], v[174:177], v[212:215], v[66:69]
	s_setprio 0
	s_barrier
	s_add_i32 s20, s20, s45
	v_lshl_add_u64 v[216:217], s[36:37], 0, v[134:135]
	s_mov_b32 m0, s20
	ds_read_b128 v[178:181], v144 offset:16384
	ds_read_b128 v[182:185], v144 offset:17408
	ds_read_b128 v[186:189], v144 offset:18432
	ds_read_b128 v[190:193], v144 offset:19456
	ds_read_b128 v[194:197], v144 offset:20480
	ds_read_b128 v[198:201], v144 offset:21504
	ds_read_b128 v[208:211], v144 offset:22528
	ds_read_b128 v[212:215], v144 offset:23552
	global_load_lds_dwordx4 v[216:217], off
	s_add_i32 m0, s20, 0x2000
	s_add_u32 s30, s36, 0x20000
	v_lshl_add_u64 v[218:219], s[36:37], 0, v[130:131]
	s_addc_u32 s31, s37, 0
	s_add_i32 s20, s21, s45
	global_load_lds_dwordx4 v[218:219], off
	v_lshl_add_u64 v[220:221], s[30:31], 0, v[134:135]
	s_mov_b32 m0, s20
	v_lshl_add_u64 v[222:223], s[38:39], 0, v[132:133]
	global_load_lds_dwordx4 v[220:221], off
	v_lshl_add_u64 v[220:221], s[30:31], 0, v[130:131]
	s_add_i32 m0, s20, 0x2000
	s_nop 0
	global_load_lds_dwordx4 v[220:221], off
	v_lshl_add_u64 v[220:221], s[38:39], 0, v[136:137]
	s_mov_b32 m0, s52
	s_nop 0
	global_load_lds_dwordx4 v[220:221], off
	s_mov_b32 m0, s53
	s_nop 0
	global_load_lds_dwordx4 v[222:223], off
	s_waitcnt vmcnt(8)
	s_waitcnt lgkmcnt(0)
	s_barrier
; #define PG8_STAGE(bufoff, gbase, voff) do { _Pragma("unroll") for (int _i = 0; _i < 2; ++_i) \
;         __builtin_amdgcn_global_load_lds((const unsigned*)((const char*)(gbase) + (voff)[_i]), (PG8_LAS unsigned*)(lds + (bufoff) + ldsw + _i * 8192), 16, 0, 0); } while (0)
; #define PG8_LDA(dst, b, h) do { _Pragma("unroll") for (int m = 0; m < 4; ++m) _Pragma("unroll") for (int k = 0; k < 2; ++k) dst[m][k] = *(const PG8_LAS bf16x8*)(lds + PG8_SA(b, h) + aoff + m * 2048 + k * 1024); } while (0)
; #define PG8_LDB(dst, b, h) do { _Pragma("unroll") for (int n = 0; n < 2; ++n) _Pragma("unroll") for (int k = 0; k < 2; ++k) dst[n][k] = *(const PG8_LAS bf16x8*)(lds + PG8_SB(b, h) + boff + n * 2048 + k * 1024); } while (0)
; #define PG8_MMA(ai, bj, At, Bt) do { __builtin_amdgcn_s_setprio(1); _Pragma("unroll") for (int m = 0; m < 4; ++m) _Pragma("unroll") for (int n = 0; n < 2; ++n) _Pragma("unroll") for (int k = 0; k < 2; ++k) \
;         acc[ai][bj][m][n] = __builtin_amdgcn_mfma_f32_16x16x32_bf16(Bt[n][k], At[m][k], acc[ai][bj][m][n], 0, 0, 0); __builtin_amdgcn_s_setprio(0); } while (0)
; #define PG8_WAIT_V(n) asm volatile("s_waitcnt vmcnt(" #n ")" ::: "memory")
; #define PG8_WAIT_L(n) asm volatile("s_waitcnt lgkmcnt(" #n ")" ::: "memory")
; #define PG8_BAR __builtin_amdgcn_s_barrier()
; #define PG8_SCHED __builtin_amdgcn_sched_barrier(0)
; template <class Epi, class Sched, bool ALIGN_EPI = false, bool SP2 = false>
; __device__ __forceinline__ void gemm_phase(PG8_LAS unsigned char* lds, const Gemm g, const Sched& S, const Epi& E) {
;     ...
;             PG8_WAIT_V(8); PG8_WAIT_L(0); PG8_BAR; PG8_MMA(1, 0, At, B0); PG8_MMA(1, 1, At, B1); PG8_BAR; PG8_SCHED;
;             PG8_LDB(B0, 1, 0); PG8_LDB(B1, 1, 1); PG8_SCHED; PG8_LDA(At, 1, 0); PG8_STAGE(PG8_SA(0, 1), a2 + hstepA, voffA);
;             PG8_WAIT_V(8); PG8_WAIT_L(0); PG8_BAR; PG8_MMA(0, 0, At, B0); PG8_MMA(0, 1, At, B1); PG8_BAR; PG8_SCHED;
;             PG8_LDA(At, 1, 1); PG8_STAGE(PG8_SB(1, 0), b3, voffB); PG8_STAGE(PG8_SB(1, 1), b3 + hstepB, voffB); PG8_STAGE(PG8_SA(1, 0), a3, voffA);
	s_setprio 1
	s_waitcnt lgkmcnt(0)
	v_mfma_f32_16x16x32_bf16 v[62:65], v[146:149], v[178:181], 0
	v_mfma_f32_16x16x32_bf16 v[58:61], v[154:157], v[178:181], 0
	v_mfma_f32_16x16x32_bf16 v[54:57], v[146:149], v[186:189], 0
	v_mfma_f32_16x16x32_bf16 v[50:53], v[154:157], v[186:189], 0
	v_mfma_f32_16x16x32_bf16 v[38:41], v[146:149], v[194:197], 0
	v_mfma_f32_16x16x32_bf16 v[34:37], v[154:157], v[194:197], 0
	v_mfma_f32_16x16x32_bf16 v[22:25], v[146:149], v[208:211], 0
	v_mfma_f32_16x16x32_bf16 v[18:21], v[154:157], v[208:211], 0
	v_mfma_f32_16x16x32_bf16 v[62:65], v[150:153], v[182:185], v[62:65]
	v_mfma_f32_16x16x32_bf16 v[58:61], v[158:161], v[182:185], v[58:61]
	v_mfma_f32_16x16x32_bf16 v[54:57], v[150:153], v[190:193], v[54:57]
	v_mfma_f32_16x16x32_bf16 v[50:53], v[158:161], v[190:193], v[50:53]
	v_mfma_f32_16x16x32_bf16 v[38:41], v[150:153], v[198:201], v[38:41]
	v_mfma_f32_16x16x32_bf16 v[34:37], v[158:161], v[198:201], v[34:37]
	v_mfma_f32_16x16x32_bf16 v[22:25], v[150:153], v[212:215], v[22:25]
	v_mfma_f32_16x16x32_bf16 v[18:21], v[158:161], v[212:215], v[18:21]
	s_setprio 0
	s_setprio 1
	v_mfma_f32_16x16x32_bf16 v[46:49], v[162:165], v[178:181], 0
	v_mfma_f32_16x16x32_bf16 v[42:45], v[170:173], v[178:181], 0
	v_mfma_f32_16x16x32_bf16 v[30:33], v[162:165], v[186:189], 0
	v_mfma_f32_16x16x32_bf16 v[26:29], v[170:173], v[186:189], 0
	v_mfma_f32_16x16x32_bf16 v[14:17], v[162:165], v[194:197], 0
	v_mfma_f32_16x16x32_bf16 v[10:13], v[170:173], v[194:197], 0
	v_mfma_f32_16x16x32_bf16 v[6:9], v[162:165], v[208:211], 0
	v_mfma_f32_16x16x32_bf16 v[2:5], v[170:173], v[208:211], 0
	v_mfma_f32_16x16x32_bf16 v[46:49], v[166:169], v[182:185], v[46:49]
	v_mfma_f32_16x16x32_bf16 v[42:45], v[174:177], v[182:185], v[42:45]
	v_mfma_f32_16x16x32_bf16 v[30:33], v[166:169], v[190:193], v[30:33]
	v_mfma_f32_16x16x32_bf16 v[26:29], v[174:177], v[190:193], v[26:29]
	v_mfma_f32_16x16x32_bf16 v[14:17], v[166:169], v[198:201], v[14:17]
	v_mfma_f32_16x16x32_bf16 v[10:13], v[174:177], v[198:201], v[10:13]
	v_mfma_f32_16x16x32_bf16 v[6:9], v[166:169], v[212:215], v[6:9]
	v_mfma_f32_16x16x32_bf16 v[2:5], v[174:177], v[212:215], v[2:5]
	s_setprio 0
	s_barrier
	s_add_i32 s20, 0, 0x18000
	v_add_u32_e32 v145, s20, v143
	s_add_i32 s21, 0, 0x1c000
	ds_read_b128 v[146:149], v145
	ds_read_b128 v[150:153], v145 offset:1024
	ds_read_b128 v[154:157], v145 offset:2048
	ds_read_b128 v[158:161], v145 offset:3072
	v_add_u32_e32 v145, s21, v143
	ds_read_b128 v[162:165], v145
	ds_read_b128 v[166:169], v145 offset:1024
	ds_read_b128 v[170:173], v145 offset:2048
	ds_read_b128 v[174:177], v145 offset:3072
	s_add_u32 s30, s38, 0x30000
	s_addc_u32 s31, s39, 0
	s_mov_b32 m0, s54
	v_lshl_add_u64 v[224:225], s[30:31], 0, v[136:137]
	ds_read_b128 v[178:181], v144 offset:32768
	ds_read_b128 v[182:185], v144 offset:33792
	ds_read_b128 v[186:189], v144 offset:34816
	ds_read_b128 v[190:193], v144 offset:35840
	ds_read_b128 v[194:197], v144 offset:36864
	ds_read_b128 v[198:201], v144 offset:37888
	ds_read_b128 v[208:211], v144 offset:38912
	ds_read_b128 v[212:215], v144 offset:39936
	global_load_lds_dwordx4 v[224:225], off
	v_lshl_add_u64 v[224:225], s[30:31], 0, v[132:133]
	s_mov_b32 m0, s55
	s_nop 0
	global_load_lds_dwordx4 v[224:225], off
	s_waitcnt vmcnt(8)
	s_waitcnt lgkmcnt(0)
	s_barrier
	s_setprio 1
	s_waitcnt lgkmcnt(0)
	v_mfma_f32_16x16x32_bf16 v[126:129], v[146:149], v[178:181], v[126:129]
	v_mfma_f32_16x16x32_bf16 v[122:125], v[154:157], v[178:181], v[122:125]
	v_mfma_f32_16x16x32_bf16 v[118:121], v[146:149], v[186:189], v[118:121]
	v_mfma_f32_16x16x32_bf16 v[114:117], v[154:157], v[186:189], v[114:117]
	v_mfma_f32_16x16x32_bf16 v[106:109], v[146:149], v[194:197], v[106:109]
	v_mfma_f32_16x16x32_bf16 v[98:101], v[154:157], v[194:197], v[98:101]
	v_mfma_f32_16x16x32_bf16 v[90:93], v[146:149], v[208:211], v[90:93]
	v_mfma_f32_16x16x32_bf16 v[82:85], v[154:157], v[208:211], v[82:85]
	v_mfma_f32_16x16x32_bf16 v[126:129], v[150:153], v[182:185], v[126:129]
	v_mfma_f32_16x16x32_bf16 v[122:125], v[158:161], v[182:185], v[122:125]
	v_mfma_f32_16x16x32_bf16 v[118:121], v[150:153], v[190:193], v[118:121]
	v_mfma_f32_16x16x32_bf16 v[114:117], v[158:161], v[190:193], v[114:117]
	v_mfma_f32_16x16x32_bf16 v[106:109], v[150:153], v[198:201], v[106:109]
	v_mfma_f32_16x16x32_bf16 v[98:101], v[158:161], v[198:201], v[98:101]
	v_mfma_f32_16x16x32_bf16 v[90:93], v[150:153], v[212:215], v[90:93]
	v_mfma_f32_16x16x32_bf16 v[82:85], v[158:161], v[212:215], v[82:85]
	s_setprio 0
	s_setprio 1
	v_mfma_f32_16x16x32_bf16 v[110:113], v[162:165], v[178:181], v[110:113]
	v_mfma_f32_16x16x32_bf16 v[102:105], v[170:173], v[178:181], v[102:105]
	v_mfma_f32_16x16x32_bf16 v[94:97], v[162:165], v[186:189], v[94:97]
	v_mfma_f32_16x16x32_bf16 v[86:89], v[170:173], v[186:189], v[86:89]
	v_mfma_f32_16x16x32_bf16 v[78:81], v[162:165], v[194:197], v[78:81]
	v_mfma_f32_16x16x32_bf16 v[74:77], v[170:173], v[194:197], v[74:77]
	v_mfma_f32_16x16x32_bf16 v[70:73], v[162:165], v[208:211], v[70:73]
	v_mfma_f32_16x16x32_bf16 v[66:69], v[170:173], v[208:211], v[66:69]
	v_mfma_f32_16x16x32_bf16 v[110:113], v[166:169], v[182:185], v[110:113]
	v_mfma_f32_16x16x32_bf16 v[102:105], v[174:177], v[182:185], v[102:105]
	v_mfma_f32_16x16x32_bf16 v[94:97], v[166:169], v[190:193], v[94:97]
	v_mfma_f32_16x16x32_bf16 v[86:89], v[174:177], v[190:193], v[86:89]
	v_mfma_f32_16x16x32_bf16 v[78:81], v[166:169], v[198:201], v[78:81]
	v_mfma_f32_16x16x32_bf16 v[74:77], v[174:177], v[198:201], v[74:77]
	v_mfma_f32_16x16x32_bf16 v[70:73], v[166:169], v[212:215], v[70:73]
	v_mfma_f32_16x16x32_bf16 v[66:69], v[174:177], v[212:215], v[66:69]
	s_setprio 0
	s_barrier
; #define PG8_STAGE(bufoff, gbase, voff) do { _Pragma("unroll") for (int _i = 0; _i < 2; ++_i) \
;         __builtin_amdgcn_global_load_lds((const unsigned*)((const char*)(gbase) + (voff)[_i]), (PG8_LAS unsigned*)(lds + (bufoff) + ldsw + _i * 8192), 16, 0, 0); } while (0)
; #define PG8_LDA(dst, b, h) do { _Pragma("unroll") for (int m = 0; m < 4; ++m) _Pragma("unroll") for (int k = 0; k < 2; ++k) dst[m][k] = *(const PG8_LAS bf16x8*)(lds + PG8_SA(b, h) + aoff + m * 2048 + k * 1024); } while (0)
; #define PG8_MMA(ai, bj, At, Bt) do { __builtin_amdgcn_s_setprio(1); _Pragma("unroll") for (int m = 0; m < 4; ++m) _Pragma("unroll") for (int n = 0; n < 2; ++n) _Pragma("unroll") for (int k = 0; k < 2; ++k) \
;         acc[ai][bj][m][n] = __builtin_amdgcn_mfma_f32_16x16x32_bf16(Bt[n][k], At[m][k], acc[ai][bj][m][n], 0, 0, 0); __builtin_amdgcn_s_setprio(0); } while (0)
; #define PG8_WAIT_V(n) asm volatile("s_waitcnt vmcnt(" #n ")" ::: "memory")
; #define PG8_WAIT_L(n) asm volatile("s_waitcnt lgkmcnt(" #n ")" ::: "memory")
; #define PG8_BAR __builtin_amdgcn_s_barrier()
; #define PG8_SCHED __builtin_amdgcn_sched_barrier(0)
; template <class Epi, class Sched, bool ALIGN_EPI = false, bool SP2 = false>
; __device__ __forceinline__ void gemm_phase(PG8_LAS unsigned char* lds, const Gemm g, const Sched& S, const Epi& E) {
;     ...
;         for (int t = 0; t < nt; t += 2) {
;             const bool last = (t == nt - 2);
;     ...
;             PG8_LDA(At, 1, 1); PG8_STAGE(PG8_SB(1, 0), b3, voffB); PG8_STAGE(PG8_SB(1, 1), b3 + hstepB, voffB); PG8_STAGE(PG8_SA(1, 0), a3, voffA);
;             PG8_WAIT_V(8); PG8_WAIT_L(0); PG8_BAR; PG8_MMA(1, 0, At, B0); PG8_MMA(1, 1, At, B1); PG8_BAR; PG8_SCHED;
	s_add_i32 s20, s20, s45
	v_lshl_add_u64 v[216:217], v[216:217], 0, s[22:23]
	s_mov_b32 m0, s20
	ds_read_b128 v[178:181], v144 offset:49152
	ds_read_b128 v[182:185], v144 offset:50176
	ds_read_b128 v[186:189], v144 offset:51200
	ds_read_b128 v[190:193], v144 offset:52224
	ds_read_b128 v[194:197], v144 offset:53248
	ds_read_b128 v[198:201], v144 offset:54272
	ds_read_b128 v[208:211], v144 offset:55296
	ds_read_b128 v[212:215], v144 offset:56320
	global_load_lds_dwordx4 v[216:217], off
	s_add_i32 m0, s20, 0x2000
	s_add_u32 s30, s36, 0x20080
	v_lshl_add_u64 v[216:217], v[218:219], 0, s[22:23]
	s_addc_u32 s31, s37, 0
	s_add_i32 s20, s21, s45
	global_load_lds_dwordx4 v[216:217], off
	v_lshl_add_u64 v[216:217], s[30:31], 0, v[134:135]
	s_mov_b32 m0, s20
	s_nop 0
	global_load_lds_dwordx4 v[216:217], off
	v_lshl_add_u64 v[216:217], s[30:31], 0, v[130:131]
	s_add_i32 m0, s20, 0x2000
	s_nop 0
	global_load_lds_dwordx4 v[216:217], off
	v_lshl_add_u64 v[216:217], v[220:221], 0, s[22:23]
	s_mov_b32 m0, s56
	s_nop 0
	global_load_lds_dwordx4 v[216:217], off
	v_lshl_add_u64 v[216:217], v[222:223], 0, s[22:23]
	s_mov_b32 m0, s57
	s_nop 0
	global_load_lds_dwordx4 v[216:217], off
	s_waitcnt vmcnt(8)
	s_waitcnt lgkmcnt(0)
	s_barrier
	s_setprio 1
	s_waitcnt lgkmcnt(0)
	v_mfma_f32_16x16x32_bf16 v[62:65], v[146:149], v[178:181], v[62:65]
	v_mfma_f32_16x16x32_bf16 v[58:61], v[154:157], v[178:181], v[58:61]
	v_mfma_f32_16x16x32_bf16 v[54:57], v[146:149], v[186:189], v[54:57]
	v_mfma_f32_16x16x32_bf16 v[50:53], v[154:157], v[186:189], v[50:53]
	v_mfma_f32_16x16x32_bf16 v[38:41], v[146:149], v[194:197], v[38:41]
	v_mfma_f32_16x16x32_bf16 v[34:37], v[154:157], v[194:197], v[34:37]
	v_mfma_f32_16x16x32_bf16 v[22:25], v[146:149], v[208:211], v[22:25]
	v_mfma_f32_16x16x32_bf16 v[18:21], v[154:157], v[208:211], v[18:21]
	v_mfma_f32_16x16x32_bf16 v[62:65], v[150:153], v[182:185], v[62:65]
	v_mfma_f32_16x16x32_bf16 v[58:61], v[158:161], v[182:185], v[58:61]
	v_mfma_f32_16x16x32_bf16 v[54:57], v[150:153], v[190:193], v[54:57]
	v_mfma_f32_16x16x32_bf16 v[50:53], v[158:161], v[190:193], v[50:53]
	v_mfma_f32_16x16x32_bf16 v[38:41], v[150:153], v[198:201], v[38:41]
	v_mfma_f32_16x16x32_bf16 v[34:37], v[158:161], v[198:201], v[34:37]
	v_mfma_f32_16x16x32_bf16 v[22:25], v[150:153], v[212:215], v[22:25]
	v_mfma_f32_16x16x32_bf16 v[18:21], v[158:161], v[212:215], v[18:21]
	s_setprio 0
	s_setprio 1
	v_mfma_f32_16x16x32_bf16 v[46:49], v[162:165], v[178:181], v[46:49]
	v_mfma_f32_16x16x32_bf16 v[42:45], v[170:173], v[178:181], v[42:45]
	v_mfma_f32_16x16x32_bf16 v[30:33], v[162:165], v[186:189], v[30:33]
	v_mfma_f32_16x16x32_bf16 v[26:29], v[170:173], v[186:189], v[26:29]
	v_mfma_f32_16x16x32_bf16 v[14:17], v[162:165], v[194:197], v[14:17]
	v_mfma_f32_16x16x32_bf16 v[10:13], v[170:173], v[194:197], v[10:13]
	v_mfma_f32_16x16x32_bf16 v[6:9], v[162:165], v[208:211], v[6:9]
	v_mfma_f32_16x16x32_bf16 v[2:5], v[170:173], v[208:211], v[2:5]
	v_mfma_f32_16x16x32_bf16 v[46:49], v[166:169], v[182:185], v[46:49]
	v_mfma_f32_16x16x32_bf16 v[42:45], v[174:177], v[182:185], v[42:45]
	v_mfma_f32_16x16x32_bf16 v[30:33], v[166:169], v[190:193], v[30:33]
	v_mfma_f32_16x16x32_bf16 v[26:29], v[174:177], v[190:193], v[26:29]
	v_mfma_f32_16x16x32_bf16 v[14:17], v[166:169], v[198:201], v[14:17]
	v_mfma_f32_16x16x32_bf16 v[10:13], v[174:177], v[198:201], v[10:13]
	v_mfma_f32_16x16x32_bf16 v[6:9], v[166:169], v[212:215], v[6:9]
	v_mfma_f32_16x16x32_bf16 v[2:5], v[174:177], v[212:215], v[2:5]
	s_setprio 0
	s_barrier
	s_add_i32 s63, s63, 2
	s_add_u32 s61, s61, 0x100
	s_addc_u32 s62, s62, 0
	s_cmp_gt_u32 s63, 5
	s_mov_b64 s[30:31], s[34:35]
	s_cbranch_scc1 .Lpk_done_g783

; #define PG8_BAR __builtin_amdgcn_s_barrier()
; template <class Epi, class Sched, bool ALIGN_EPI = false, bool SP2 = false>
; __device__ __forceinline__ void gemm_phase(PG8_LAS unsigned char* lds, const Gemm g, const Sched& S, const Epi& E) {
;     ...
;         }
;         if constexpr (ALIGN_EPI) { if (wr == 0) PG8_BAR; }
.Lpk_done_g783:
	s_and_b64 vcc, exec, s[8:9]
	s_cbranch_vccz .LBB0_786
	s_barrier

; #define PG8_STAGE(bufoff, gbase, voff) do { _Pragma("unroll") for (int _i = 0; _i < 2; ++_i) \
;         __builtin_amdgcn_global_load_lds((const unsigned*)((const char*)(gbase) + (voff)[_i]), (PG8_LAS unsigned*)(lds + (bufoff) + ldsw + _i * 8192), 16, 0, 0); } while (0)
; #define PG8_LDA(dst, b, h) do { _Pragma("unroll") for (int m = 0; m < 4; ++m) _Pragma("unroll") for (int k = 0; k < 2; ++k) dst[m][k] = *(const PG8_LAS bf16x8*)(lds + PG8_SA(b, h) + aoff + m * 2048 + k * 1024); } while (0)
; #define PG8_LDB(dst, b, h) do { _Pragma("unroll") for (int n = 0; n < 2; ++n) _Pragma("unroll") for (int k = 0; k < 2; ++k) dst[n][k] = *(const PG8_LAS bf16x8*)(lds + PG8_SB(b, h) + boff + n * 2048 + k * 1024); } while (0)
; #define PG8_WAIT_V(n) asm volatile("s_waitcnt vmcnt(" #n ")" ::: "memory")
; #define PG8_BAR __builtin_amdgcn_s_barrier()
; template <class Epi, class Sched, bool ALIGN_EPI = false, bool SP2 = false>
; __device__ __forceinline__ void gemm_phase(PG8_LAS unsigned char* lds, const Gemm g, const Sched& S, const Epi& E) {
;     ...
;         const char* nA = has_next ? (const char*)g.A + (size_t)nxt.pm * tstepA + (size_t)nxt.pb * g.sA : cA; const char* nB = has_next ? (const char*)g.Bt + (size_t)nxt.pn * tstepB + (size_t)nxt.pb * g.sB : cB;
;         for (int t = 0; t < nt; t += 2) {
;             const bool last = (t == nt - 2);
;             const char* a1 = cA + (size_t)(t + 1) * kstep;
;             const char* a2 = last ? nA : cA + (size_t)(t + 2) * kstep; const char* b2 = last ? nB : cB + (size_t)(t + 2) * kstep;
;             const char* a3 = a2 + kstep; const char* b3 = b2 + kstep;
;             if (last && has_next) S.a_ready(nxt);
;             if constexpr (SP2) {
;             PG8_LDB(B0, 0, 0); PG8_LDB(B1, 0, 1); PG8_SCHED; PG8_LDA(At, 0, 0); PG8_STAGE(PG8_SA(1, 1), a1 + hstepA, voffA);
;             PG8_WAIT_V(8); PG8_WAIT_L(0); PG8_BAR; PG8_MMA(0, 0, At, B0); PG8_MMA(0, 1, At, B1); PG8_BAR; PG8_SCHED;
;             PG8_LDA(At, 0, 1); PG8_STAGE(PG8_SB(0, 0), b2, voffB); PG8_STAGE(PG8_SB(0, 1), b2 + hstepB, voffB); PG8_STAGE(PG8_SA(0, 0), a2, voffA);
;     ...
; #pragma unroll
;         for (int a = 0; a < 2; ++a)
; #pragma unroll
;             for (int b = 0; b < 2; ++b)
; #pragma unroll
;                 for (int m = 0; m < 4; ++m)
; #pragma unroll
;                     for (int n = 0; n < 2; ++n) acc[a][b][m][n] = (f32x4){0.f, 0.f, 0.f, 0.f};
.LBB0_958:
	s_add_u32 s63, s8, 0x100
	s_addc_u32 s70, s9, 0
	s_mov_b32 s71, -2
	s_add_u32 s8, s0, 0x100
	s_addc_u32 s9, s1, 0
	s_add_i32 s20, 0, 0x10000
	s_cmp_eq_u32 s71, 8
	s_cselect_b32 s13, s31, s9
	s_cselect_b32 s12, s30, s8
	v_add_u32_e32 v142, s20, v145
	s_cselect_b32 s11, s19, s70
	s_cselect_b32 s10, s18, s63
	s_add_i32 s21, 0, 0x14000
	ds_read_b128 v[148:151], v142
	ds_read_b128 v[152:155], v142 offset:1024
	ds_read_b128 v[156:159], v142 offset:2048
	ds_read_b128 v[160:163], v142 offset:3072
	v_add_u32_e32 v142, s21, v145
	ds_read_b128 v[164:167], v142
	ds_read_b128 v[168:171], v142 offset:1024
	ds_read_b128 v[172:175], v142 offset:2048
	ds_read_b128 v[176:179], v142 offset:3072
	v_lshl_add_u64 v[142:143], s[0:1], 0, v[138:139]
	s_add_i32 m0, s34, 0xc000
	ds_read_b128 v[180:183], v147
	ds_read_b128 v[184:187], v147 offset:1024
	ds_read_b128 v[188:191], v147 offset:2048
	ds_read_b128 v[192:195], v147 offset:3072
	ds_read_b128 v[196:199], v147 offset:4096
	ds_read_b128 v[208:211], v147 offset:5120
	ds_read_b128 v[212:215], v147 offset:6144
	ds_read_b128 v[216:219], v147 offset:7168
	global_load_lds_dwordx4 v[142:143], off
	v_lshl_add_u64 v[142:143], s[0:1], 0, v[140:141]
	s_add_i32 m0, s34, 0xe000
	s_nop 0
	global_load_lds_dwordx4 v[142:143], off
	s_waitcnt vmcnt(8)
	s_waitcnt lgkmcnt(0)
	s_barrier
	s_setprio 1
	s_waitcnt lgkmcnt(0)
	v_mfma_f32_16x16x32_bf16 v[126:129], v[148:151], v[180:183], 0
	v_mfma_f32_16x16x32_bf16 v[122:125], v[156:159], v[180:183], 0
	v_mfma_f32_16x16x32_bf16 v[110:113], v[148:151], v[188:191], 0
	v_mfma_f32_16x16x32_bf16 v[106:109], v[156:159], v[188:191], 0
	v_mfma_f32_16x16x32_bf16 v[94:97], v[148:151], v[196:199], 0
	v_mfma_f32_16x16x32_bf16 v[90:93], v[156:159], v[196:199], 0
	v_mfma_f32_16x16x32_bf16 v[78:81], v[148:151], v[212:215], 0
	v_mfma_f32_16x16x32_bf16 v[74:77], v[156:159], v[212:215], 0
	v_mfma_f32_16x16x32_bf16 v[126:129], v[152:155], v[184:187], v[126:129]
	v_mfma_f32_16x16x32_bf16 v[122:125], v[160:163], v[184:187], v[122:125]
	v_mfma_f32_16x16x32_bf16 v[110:113], v[152:155], v[192:195], v[110:113]
	v_mfma_f32_16x16x32_bf16 v[106:109], v[160:163], v[192:195], v[106:109]
	v_mfma_f32_16x16x32_bf16 v[94:97], v[152:155], v[208:211], v[94:97]
	v_mfma_f32_16x16x32_bf16 v[90:93], v[160:163], v[208:211], v[90:93]
	v_mfma_f32_16x16x32_bf16 v[78:81], v[152:155], v[216:219], v[78:81]
	v_mfma_f32_16x16x32_bf16 v[74:77], v[160:163], v[216:219], v[74:77]
	s_setprio 0
	s_setprio 1
	v_mfma_f32_16x16x32_bf16 v[118:121], v[164:167], v[180:183], 0
	v_mfma_f32_16x16x32_bf16 v[114:117], v[172:175], v[180:183], 0
	v_mfma_f32_16x16x32_bf16 v[102:105], v[164:167], v[188:191], 0
	v_mfma_f32_16x16x32_bf16 v[98:101], v[172:175], v[188:191], 0
	v_mfma_f32_16x16x32_bf16 v[86:89], v[164:167], v[196:199], 0
	v_mfma_f32_16x16x32_bf16 v[82:85], v[172:175], v[196:199], 0
	v_mfma_f32_16x16x32_bf16 v[70:73], v[164:167], v[212:215], 0
	v_mfma_f32_16x16x32_bf16 v[66:69], v[172:175], v[212:215], 0
	v_mfma_f32_16x16x32_bf16 v[118:121], v[168:171], v[184:187], v[118:121]
	v_mfma_f32_16x16x32_bf16 v[114:117], v[176:179], v[184:187], v[114:117]
	v_mfma_f32_16x16x32_bf16 v[102:105], v[168:171], v[192:195], v[102:105]
	v_mfma_f32_16x16x32_bf16 v[98:101], v[176:179], v[192:195], v[98:101]
	v_mfma_f32_16x16x32_bf16 v[86:89], v[168:171], v[208:211], v[86:89]
	v_mfma_f32_16x16x32_bf16 v[82:85], v[176:179], v[208:211], v[82:85]
	v_mfma_f32_16x16x32_bf16 v[70:73], v[168:171], v[216:219], v[70:73]
	v_mfma_f32_16x16x32_bf16 v[66:69], v[176:179], v[216:219], v[66:69]
	s_setprio 0
	s_barrier
	s_add_i32 s0, s20, s26
	v_lshl_add_u64 v[142:143], s[10:11], 0, v[134:135]
	s_mov_b32 m0, s0
	ds_read_b128 v[180:183], v147 offset:16384
	ds_read_b128 v[184:187], v147 offset:17408
	ds_read_b128 v[188:191], v147 offset:18432
	ds_read_b128 v[192:195], v147 offset:19456
	ds_read_b128 v[196:199], v147 offset:20480
	ds_read_b128 v[208:211], v147 offset:21504
	ds_read_b128 v[212:215], v147 offset:22528
	ds_read_b128 v[216:219], v147 offset:23552
	global_load_lds_dwordx4 v[142:143], off
	s_add_i32 m0, s0, 0x2000
	s_add_u32 s0, s10, 0x30000
	v_lshl_add_u64 v[200:201], s[10:11], 0, v[130:131]
	s_addc_u32 s1, s11, 0
	s_add_i32 s20, s21, s26
	global_load_lds_dwordx4 v[200:201], off
	v_lshl_add_u64 v[220:221], s[0:1], 0, v[134:135]
	s_mov_b32 m0, s20
	v_lshl_add_u64 v[222:223], s[12:13], 0, v[132:133]
	global_load_lds_dwordx4 v[220:221], off
	v_lshl_add_u64 v[220:221], s[0:1], 0, v[130:131]
	s_add_i32 m0, s20, 0x2000
	s_nop 0
	global_load_lds_dwordx4 v[220:221], off
	v_lshl_add_u64 v[220:221], s[12:13], 0, v[136:137]
	s_mov_b32 m0, s34
	s_nop 0
	global_load_lds_dwordx4 v[220:221], off
	s_mov_b32 m0, s35
	s_nop 0
	global_load_lds_dwordx4 v[222:223], off
	s_waitcnt vmcnt(8)
	s_waitcnt lgkmcnt(0)
	s_barrier
; #define PG8_STAGE(bufoff, gbase, voff) do { _Pragma("unroll") for (int _i = 0; _i < 2; ++_i) \
;         __builtin_amdgcn_global_load_lds((const unsigned*)((const char*)(gbase) + (voff)[_i]), (PG8_LAS unsigned*)(lds + (bufoff) + ldsw + _i * 8192), 16, 0, 0); } while (0)
; #define PG8_LDA(dst, b, h) do { _Pragma("unroll") for (int m = 0; m < 4; ++m) _Pragma("unroll") for (int k = 0; k < 2; ++k) dst[m][k] = *(const PG8_LAS bf16x8*)(lds + PG8_SA(b, h) + aoff + m * 2048 + k * 1024); } while (0)
; #define PG8_LDB(dst, b, h) do { _Pragma("unroll") for (int n = 0; n < 2; ++n) _Pragma("unroll") for (int k = 0; k < 2; ++k) dst[n][k] = *(const PG8_LAS bf16x8*)(lds + PG8_SB(b, h) + boff + n * 2048 + k * 1024); } while (0)
; #define PG8_MMA(ai, bj, At, Bt) do { __builtin_amdgcn_s_setprio(1); _Pragma("unroll") for (int m = 0; m < 4; ++m) _Pragma("unroll") for (int n = 0; n < 2; ++n) _Pragma("unroll") for (int k = 0; k < 2; ++k) \
;         acc[ai][bj][m][n] = __builtin_amdgcn_mfma_f32_16x16x32_bf16(Bt[n][k], At[m][k], acc[ai][bj][m][n], 0, 0, 0); __builtin_amdgcn_s_setprio(0); } while (0)
; #define PG8_WAIT_V(n) asm volatile("s_waitcnt vmcnt(" #n ")" ::: "memory")
; #define PG8_WAIT_L(n) asm volatile("s_waitcnt lgkmcnt(" #n ")" ::: "memory")
; #define PG8_BAR __builtin_amdgcn_s_barrier()
; #define PG8_SCHED __builtin_amdgcn_sched_barrier(0)
; template <class Epi, class Sched, bool ALIGN_EPI = false, bool SP2 = false>
; __device__ __forceinline__ void gemm_phase(PG8_LAS unsigned char* lds, const Gemm g, const Sched& S, const Epi& E) {
;     ...
;             PG8_WAIT_V(8); PG8_WAIT_L(0); PG8_BAR; PG8_MMA(1, 0, At, B0); PG8_MMA(1, 1, At, B1); PG8_BAR; PG8_SCHED;
;             PG8_LDB(B0, 1, 0); PG8_LDB(B1, 1, 1); PG8_SCHED; PG8_LDA(At, 1, 0); PG8_STAGE(PG8_SA(0, 1), a2 + hstepA, voffA);
;             PG8_WAIT_V(8); PG8_WAIT_L(0); PG8_BAR; PG8_MMA(0, 0, At, B0); PG8_MMA(0, 1, At, B1); PG8_BAR; PG8_SCHED;
;             PG8_LDA(At, 1, 1); PG8_STAGE(PG8_SB(1, 0), b3, voffB); PG8_STAGE(PG8_SB(1, 1), b3 + hstepB, voffB); PG8_STAGE(PG8_SA(1, 0), a3, voffA);
	s_setprio 1
	s_waitcnt lgkmcnt(0)
	v_mfma_f32_16x16x32_bf16 v[62:65], v[148:151], v[180:183], 0
	v_mfma_f32_16x16x32_bf16 v[58:61], v[156:159], v[180:183], 0
	v_mfma_f32_16x16x32_bf16 v[46:49], v[148:151], v[188:191], 0
	v_mfma_f32_16x16x32_bf16 v[42:45], v[156:159], v[188:191], 0
	v_mfma_f32_16x16x32_bf16 v[30:33], v[148:151], v[196:199], 0
	v_mfma_f32_16x16x32_bf16 v[26:29], v[156:159], v[196:199], 0
	v_mfma_f32_16x16x32_bf16 v[14:17], v[148:151], v[212:215], 0
	v_mfma_f32_16x16x32_bf16 v[10:13], v[156:159], v[212:215], 0
	v_mfma_f32_16x16x32_bf16 v[62:65], v[152:155], v[184:187], v[62:65]
	v_mfma_f32_16x16x32_bf16 v[58:61], v[160:163], v[184:187], v[58:61]
	v_mfma_f32_16x16x32_bf16 v[46:49], v[152:155], v[192:195], v[46:49]
	v_mfma_f32_16x16x32_bf16 v[42:45], v[160:163], v[192:195], v[42:45]
	v_mfma_f32_16x16x32_bf16 v[30:33], v[152:155], v[208:211], v[30:33]
	v_mfma_f32_16x16x32_bf16 v[26:29], v[160:163], v[208:211], v[26:29]
	v_mfma_f32_16x16x32_bf16 v[14:17], v[152:155], v[216:219], v[14:17]
	v_mfma_f32_16x16x32_bf16 v[10:13], v[160:163], v[216:219], v[10:13]
	s_setprio 0
	s_setprio 1
	v_mfma_f32_16x16x32_bf16 v[54:57], v[164:167], v[180:183], 0
	v_mfma_f32_16x16x32_bf16 v[50:53], v[172:175], v[180:183], 0
	v_mfma_f32_16x16x32_bf16 v[38:41], v[164:167], v[188:191], 0
	v_mfma_f32_16x16x32_bf16 v[34:37], v[172:175], v[188:191], 0
	v_mfma_f32_16x16x32_bf16 v[22:25], v[164:167], v[196:199], 0
	v_mfma_f32_16x16x32_bf16 v[18:21], v[172:175], v[196:199], 0
	v_mfma_f32_16x16x32_bf16 v[6:9], v[164:167], v[212:215], 0
	v_mfma_f32_16x16x32_bf16 v[2:5], v[172:175], v[212:215], 0
	v_mfma_f32_16x16x32_bf16 v[54:57], v[168:171], v[184:187], v[54:57]
	v_mfma_f32_16x16x32_bf16 v[50:53], v[176:179], v[184:187], v[50:53]
	v_mfma_f32_16x16x32_bf16 v[38:41], v[168:171], v[192:195], v[38:41]
	v_mfma_f32_16x16x32_bf16 v[34:37], v[176:179], v[192:195], v[34:37]
	v_mfma_f32_16x16x32_bf16 v[22:25], v[168:171], v[208:211], v[22:25]
	v_mfma_f32_16x16x32_bf16 v[18:21], v[176:179], v[208:211], v[18:21]
	v_mfma_f32_16x16x32_bf16 v[6:9], v[168:171], v[216:219], v[6:9]
	v_mfma_f32_16x16x32_bf16 v[2:5], v[176:179], v[216:219], v[2:5]
	s_setprio 0
	s_barrier
	s_add_i32 s20, 0, 0x18000
	s_add_i32 s21, 0, 0x1c000
	v_add_u32_e32 v160, s20, v145
	v_add_u32_e32 v176, s21, v145
	ds_read_b128 v[148:151], v160
	ds_read_b128 v[152:155], v160 offset:1024
	ds_read_b128 v[156:159], v160 offset:2048
	ds_read_b128 v[160:163], v160 offset:3072
	ds_read_b128 v[164:167], v176
	ds_read_b128 v[168:171], v176 offset:1024
	ds_read_b128 v[172:175], v176 offset:2048
	ds_read_b128 v[176:179], v176 offset:3072
	s_add_u32 s0, s12, 0x30000
	s_addc_u32 s1, s13, 0
	s_mov_b32 m0, s36
	v_lshl_add_u64 v[224:225], s[0:1], 0, v[136:137]
	ds_read_b128 v[180:183], v147 offset:32768
	ds_read_b128 v[184:187], v147 offset:33792
	ds_read_b128 v[188:191], v147 offset:34816
	ds_read_b128 v[192:195], v147 offset:35840
	ds_read_b128 v[196:199], v147 offset:36864
	ds_read_b128 v[208:211], v147 offset:37888
	ds_read_b128 v[212:215], v147 offset:38912
	ds_read_b128 v[216:219], v147 offset:39936
	global_load_lds_dwordx4 v[224:225], off
	v_lshl_add_u64 v[224:225], s[0:1], 0, v[132:133]
	s_mov_b32 m0, s37
	s_nop 0
	global_load_lds_dwordx4 v[224:225], off
	s_waitcnt vmcnt(8)
	s_waitcnt lgkmcnt(0)
	s_barrier
	s_setprio 1
	s_waitcnt lgkmcnt(0)
	v_mfma_f32_16x16x32_bf16 v[126:129], v[148:151], v[180:183], v[126:129]
	v_mfma_f32_16x16x32_bf16 v[122:125], v[156:159], v[180:183], v[122:125]
	v_mfma_f32_16x16x32_bf16 v[110:113], v[148:151], v[188:191], v[110:113]
	v_mfma_f32_16x16x32_bf16 v[106:109], v[156:159], v[188:191], v[106:109]
	v_mfma_f32_16x16x32_bf16 v[94:97], v[148:151], v[196:199], v[94:97]
	v_mfma_f32_16x16x32_bf16 v[90:93], v[156:159], v[196:199], v[90:93]
	v_mfma_f32_16x16x32_bf16 v[78:81], v[148:151], v[212:215], v[78:81]
	v_mfma_f32_16x16x32_bf16 v[74:77], v[156:159], v[212:215], v[74:77]
	v_mfma_f32_16x16x32_bf16 v[126:129], v[152:155], v[184:187], v[126:129]
	v_mfma_f32_16x16x32_bf16 v[122:125], v[160:163], v[184:187], v[122:125]
	v_mfma_f32_16x16x32_bf16 v[110:113], v[152:155], v[192:195], v[110:113]
	v_mfma_f32_16x16x32_bf16 v[106:109], v[160:163], v[192:195], v[106:109]
	v_mfma_f32_16x16x32_bf16 v[94:97], v[152:155], v[208:211], v[94:97]
	v_mfma_f32_16x16x32_bf16 v[90:93], v[160:163], v[208:211], v[90:93]
	v_mfma_f32_16x16x32_bf16 v[78:81], v[152:155], v[216:219], v[78:81]
	v_mfma_f32_16x16x32_bf16 v[74:77], v[160:163], v[216:219], v[74:77]
	s_setprio 0
	s_setprio 1
	v_mfma_f32_16x16x32_bf16 v[118:121], v[164:167], v[180:183], v[118:121]
	v_mfma_f32_16x16x32_bf16 v[114:117], v[172:175], v[180:183], v[114:117]
	v_mfma_f32_16x16x32_bf16 v[102:105], v[164:167], v[188:191], v[102:105]
	v_mfma_f32_16x16x32_bf16 v[98:101], v[172:175], v[188:191], v[98:101]
	v_mfma_f32_16x16x32_bf16 v[86:89], v[164:167], v[196:199], v[86:89]
	v_mfma_f32_16x16x32_bf16 v[82:85], v[172:175], v[196:199], v[82:85]
	v_mfma_f32_16x16x32_bf16 v[70:73], v[164:167], v[212:215], v[70:73]
	v_mfma_f32_16x16x32_bf16 v[66:69], v[172:175], v[212:215], v[66:69]
	v_mfma_f32_16x16x32_bf16 v[118:121], v[168:171], v[184:187], v[118:121]
	v_mfma_f32_16x16x32_bf16 v[114:117], v[176:179], v[184:187], v[114:117]
	v_mfma_f32_16x16x32_bf16 v[102:105], v[168:171], v[192:195], v[102:105]
	v_mfma_f32_16x16x32_bf16 v[98:101], v[176:179], v[192:195], v[98:101]
	v_mfma_f32_16x16x32_bf16 v[86:89], v[168:171], v[208:211], v[86:89]
	v_mfma_f32_16x16x32_bf16 v[82:85], v[176:179], v[208:211], v[82:85]
	v_mfma_f32_16x16x32_bf16 v[70:73], v[168:171], v[216:219], v[70:73]
	v_mfma_f32_16x16x32_bf16 v[66:69], v[176:179], v[216:219], v[66:69]
	s_setprio 0
	s_barrier
; #define PG8_STAGE(bufoff, gbase, voff) do { _Pragma("unroll") for (int _i = 0; _i < 2; ++_i) \
;         __builtin_amdgcn_global_load_lds((const unsigned*)((const char*)(gbase) + (voff)[_i]), (PG8_LAS unsigned*)(lds + (bufoff) + ldsw + _i * 8192), 16, 0, 0); } while (0)
; #define PG8_LDA(dst, b, h) do { _Pragma("unroll") for (int m = 0; m < 4; ++m) _Pragma("unroll") for (int k = 0; k < 2; ++k) dst[m][k] = *(const PG8_LAS bf16x8*)(lds + PG8_SA(b, h) + aoff + m * 2048 + k * 1024); } while (0)
; #define PG8_MMA(ai, bj, At, Bt) do { __builtin_amdgcn_s_setprio(1); _Pragma("unroll") for (int m = 0; m < 4; ++m) _Pragma("unroll") for (int n = 0; n < 2; ++n) _Pragma("unroll") for (int k = 0; k < 2; ++k) \
;         acc[ai][bj][m][n] = __builtin_amdgcn_mfma_f32_16x16x32_bf16(Bt[n][k], At[m][k], acc[ai][bj][m][n], 0, 0, 0); __builtin_amdgcn_s_setprio(0); } while (0)
; #define PG8_WAIT_V(n) asm volatile("s_waitcnt vmcnt(" #n ")" ::: "memory")
; #define PG8_WAIT_L(n) asm volatile("s_waitcnt lgkmcnt(" #n ")" ::: "memory")
; #define PG8_BAR __builtin_amdgcn_s_barrier()
; #define PG8_SCHED __builtin_amdgcn_sched_barrier(0)
; template <class Epi, class Sched, bool ALIGN_EPI = false, bool SP2 = false>
; __device__ __forceinline__ void gemm_phase(PG8_LAS unsigned char* lds, const Gemm g, const Sched& S, const Epi& E) {
;     ...
;         for (int t = 0; t < nt; t += 2) {
;             const bool last = (t == nt - 2);
;     ...
;             PG8_LDA(At, 1, 1); PG8_STAGE(PG8_SB(1, 0), b3, voffB); PG8_STAGE(PG8_SB(1, 1), b3 + hstepB, voffB); PG8_STAGE(PG8_SA(1, 0), a3, voffA);
;             PG8_WAIT_V(8); PG8_WAIT_L(0); PG8_BAR; PG8_MMA(1, 0, At, B0); PG8_MMA(1, 1, At, B1); PG8_BAR; PG8_SCHED;
	s_add_i32 s0, s20, s26
	v_lshl_add_u64 v[142:143], v[142:143], 0, s[22:23]
	s_mov_b32 m0, s0
	ds_read_b128 v[180:183], v147 offset:49152
	ds_read_b128 v[184:187], v147 offset:50176
	ds_read_b128 v[188:191], v147 offset:51200
	ds_read_b128 v[192:195], v147 offset:52224
	ds_read_b128 v[196:199], v147 offset:53248
	ds_read_b128 v[208:211], v147 offset:54272
	ds_read_b128 v[212:215], v147 offset:55296
	ds_read_b128 v[216:219], v147 offset:56320
	global_load_lds_dwordx4 v[142:143], off
	s_add_i32 m0, s0, 0x2000
	s_add_u32 s0, s10, 0x30080
	v_lshl_add_u64 v[142:143], v[200:201], 0, s[22:23]
	s_addc_u32 s1, s11, 0
	s_add_i32 s10, s21, s26
	global_load_lds_dwordx4 v[142:143], off
	v_lshl_add_u64 v[142:143], s[0:1], 0, v[134:135]
	s_mov_b32 m0, s10
	s_nop 0
	global_load_lds_dwordx4 v[142:143], off
	v_lshl_add_u64 v[142:143], s[0:1], 0, v[130:131]
	s_add_i32 m0, s10, 0x2000
	s_nop 0
	global_load_lds_dwordx4 v[142:143], off
	v_lshl_add_u64 v[142:143], v[220:221], 0, s[22:23]
	s_mov_b32 m0, s38
	s_nop 0
	global_load_lds_dwordx4 v[142:143], off
	v_lshl_add_u64 v[142:143], v[222:223], 0, s[22:23]
	s_mov_b32 m0, s39
	s_nop 0
	global_load_lds_dwordx4 v[142:143], off
	s_waitcnt vmcnt(8)
	s_waitcnt lgkmcnt(0)
	s_barrier
	s_setprio 1
	s_waitcnt lgkmcnt(0)
	v_mfma_f32_16x16x32_bf16 v[62:65], v[148:151], v[180:183], v[62:65]
	v_mfma_f32_16x16x32_bf16 v[58:61], v[156:159], v[180:183], v[58:61]
	v_mfma_f32_16x16x32_bf16 v[46:49], v[148:151], v[188:191], v[46:49]
	v_mfma_f32_16x16x32_bf16 v[42:45], v[156:159], v[188:191], v[42:45]
	v_mfma_f32_16x16x32_bf16 v[30:33], v[148:151], v[196:199], v[30:33]
	v_mfma_f32_16x16x32_bf16 v[26:29], v[156:159], v[196:199], v[26:29]
	v_mfma_f32_16x16x32_bf16 v[14:17], v[148:151], v[212:215], v[14:17]
	v_mfma_f32_16x16x32_bf16 v[10:13], v[156:159], v[212:215], v[10:13]
	v_mfma_f32_16x16x32_bf16 v[62:65], v[152:155], v[184:187], v[62:65]
	v_mfma_f32_16x16x32_bf16 v[58:61], v[160:163], v[184:187], v[58:61]
	v_mfma_f32_16x16x32_bf16 v[46:49], v[152:155], v[192:195], v[46:49]
	v_mfma_f32_16x16x32_bf16 v[42:45], v[160:163], v[192:195], v[42:45]
	v_mfma_f32_16x16x32_bf16 v[30:33], v[152:155], v[208:211], v[30:33]
	v_mfma_f32_16x16x32_bf16 v[26:29], v[160:163], v[208:211], v[26:29]
	v_mfma_f32_16x16x32_bf16 v[14:17], v[152:155], v[216:219], v[14:17]
	v_mfma_f32_16x16x32_bf16 v[10:13], v[160:163], v[216:219], v[10:13]
	s_setprio 0
	s_setprio 1
	v_mfma_f32_16x16x32_bf16 v[54:57], v[164:167], v[180:183], v[54:57]
	v_mfma_f32_16x16x32_bf16 v[50:53], v[172:175], v[180:183], v[50:53]
	v_mfma_f32_16x16x32_bf16 v[38:41], v[164:167], v[188:191], v[38:41]
	v_mfma_f32_16x16x32_bf16 v[34:37], v[172:175], v[188:191], v[34:37]
	v_mfma_f32_16x16x32_bf16 v[22:25], v[164:167], v[196:199], v[22:25]
	v_mfma_f32_16x16x32_bf16 v[18:21], v[172:175], v[196:199], v[18:21]
	v_mfma_f32_16x16x32_bf16 v[6:9], v[164:167], v[212:215], v[6:9]
	v_mfma_f32_16x16x32_bf16 v[2:5], v[172:175], v[212:215], v[2:5]
	v_mfma_f32_16x16x32_bf16 v[54:57], v[168:171], v[184:187], v[54:57]
	v_mfma_f32_16x16x32_bf16 v[50:53], v[176:179], v[184:187], v[50:53]
	v_mfma_f32_16x16x32_bf16 v[38:41], v[168:171], v[192:195], v[38:41]
	v_mfma_f32_16x16x32_bf16 v[34:37], v[176:179], v[192:195], v[34:37]
	v_mfma_f32_16x16x32_bf16 v[22:25], v[168:171], v[208:211], v[22:25]
	v_mfma_f32_16x16x32_bf16 v[18:21], v[176:179], v[208:211], v[18:21]
	v_mfma_f32_16x16x32_bf16 v[6:9], v[168:171], v[216:219], v[6:9]
	v_mfma_f32_16x16x32_bf16 v[2:5], v[176:179], v[216:219], v[2:5]
	s_setprio 0
	s_barrier
	s_add_i32 s71, s71, 2
	s_add_u32 s63, s63, 0x100
	s_addc_u32 s70, s70, 0
	s_cmp_gt_u32 s71, 9
	s_mov_b64 s[0:1], s[8:9]
	s_cbranch_scc1 .Lpk_done_g959

; #define PG8_BAR __builtin_amdgcn_s_barrier()
; template <class Epi, class Sched, bool ALIGN_EPI = false, bool SP2 = false>
; __device__ __forceinline__ void gemm_phase(PG8_LAS unsigned char* lds, const Gemm g, const Sched& S, const Epi& E) {
;     ...
;         }
;         if constexpr (ALIGN_EPI) { if (wr == 0) PG8_BAR; }
.Lpk_done_g959:
	s_and_b64 vcc, exec, s[58:59]
	s_cbranch_vccz .LBB0_962
	s_barrier

; #define PG8_STAGE(bufoff, gbase, voff) do { _Pragma("unroll") for (int _i = 0; _i < 2; ++_i) \
;         __builtin_amdgcn_global_load_lds((const unsigned*)((const char*)(gbase) + (voff)[_i]), (PG8_LAS unsigned*)(lds + (bufoff) + ldsw + _i * 8192), 16, 0, 0); } while (0)
; #define PG8_LDA(dst, b, h) do { _Pragma("unroll") for (int m = 0; m < 4; ++m) _Pragma("unroll") for (int k = 0; k < 2; ++k) dst[m][k] = *(const PG8_LAS bf16x8*)(lds + PG8_SA(b, h) + aoff + m * 2048 + k * 1024); } while (0)
; #define PG8_LDB(dst, b, h) do { _Pragma("unroll") for (int n = 0; n < 2; ++n) _Pragma("unroll") for (int k = 0; k < 2; ++k) dst[n][k] = *(const PG8_LAS bf16x8*)(lds + PG8_SB(b, h) + boff + n * 2048 + k * 1024); } while (0)
; #define PG8_WAIT_V(n) asm volatile("s_waitcnt vmcnt(" #n ")" ::: "memory")
; #define PG8_BAR __builtin_amdgcn_s_barrier()
; template <class Epi, class Sched, bool ALIGN_EPI = false, bool SP2 = false>
; __device__ __forceinline__ void gemm_phase(PG8_LAS unsigned char* lds, const Gemm g, const Sched& S, const Epi& E) {
;     ...
;         const char* nA = has_next ? (const char*)g.A + (size_t)nxt.pm * tstepA + (size_t)nxt.pb * g.sA : cA; const char* nB = has_next ? (const char*)g.Bt + (size_t)nxt.pn * tstepB + (size_t)nxt.pb * g.sB : cB;
;         for (int t = 0; t < nt; t += 2) {
;             const bool last = (t == nt - 2);
;             const char* a1 = cA + (size_t)(t + 1) * kstep;
;             const char* a2 = last ? nA : cA + (size_t)(t + 2) * kstep; const char* b2 = last ? nB : cB + (size_t)(t + 2) * kstep;
;             const char* a3 = a2 + kstep; const char* b3 = b2 + kstep;
;             if (last && has_next) S.a_ready(nxt);
;             if constexpr (SP2) {
;             PG8_LDB(B0, 0, 0); PG8_LDB(B1, 0, 1); PG8_SCHED; PG8_LDA(At, 0, 0); PG8_STAGE(PG8_SA(1, 1), a1 + hstepA, voffA);
;             PG8_WAIT_V(8); PG8_WAIT_L(0); PG8_BAR; PG8_MMA(0, 0, At, B0); PG8_MMA(0, 1, At, B1); PG8_BAR; PG8_SCHED;
;             PG8_LDA(At, 0, 1); PG8_STAGE(PG8_SB(0, 0), b2, voffB); PG8_STAGE(PG8_SB(0, 1), b2 + hstepB, voffB); PG8_STAGE(PG8_SA(0, 0), a2, voffA);
;     ...
; #pragma unroll
;         for (int a = 0; a < 2; ++a)
; #pragma unroll
;             for (int b = 0; b < 2; ++b)
; #pragma unroll
;                 for (int m = 0; m < 4; ++m)
; #pragma unroll
;                     for (int n = 0; n < 2; ++n) acc[a][b][m][n] = (f32x4){0.f, 0.f, 0.f, 0.f};
.LBB0_1047:
	s_ashr_i32 s31, s30, 31
	s_lshl_b64 s[34:35], s[30:31], 18
	s_add_u32 s34, s12, s34
	s_addc_u32 s35, s13, s35
	s_and_b64 s[36:37], s[42:43], exec
	s_cselect_b32 s31, s35, s9
	s_cselect_b32 s61, s34, s8
	s_ashr_i32 s29, s28, 31
	s_lshl_b64 s[36:37], s[28:29], 18
	s_add_u32 s38, s26, s36
	s_addc_u32 s39, s46, s37
	s_and_b64 s[36:37], s[42:43], exec
	s_cselect_b32 s29, s39, s15
	s_cselect_b32 s62, s38, s14
	s_add_u32 s8, s8, 0x20080
	s_addc_u32 s9, s9, 0
	s_add_u32 s63, s14, 0x100
	s_addc_u32 s70, s15, 0
	s_mov_b32 s71, -2
	s_add_u32 s14, s8, 0xfffe0080
	s_addc_u32 s15, s9, -1
	s_add_i32 s20, 0, 0x10000
	s_cmp_eq_u32 s71, 4
	s_cselect_b32 s37, s31, s15
	s_cselect_b32 s36, s61, s14
	s_cselect_b32 s15, s29, s70
	s_cselect_b32 s14, s62, s63
	s_add_i32 s21, 0, 0x14000
	v_add_u32_e32 v102, s20, v239
	v_add_u32_e32 v142, s21, v239
	ds_read_b128 v[82:85], v102
	ds_read_b128 v[86:89], v102 offset:1024
	ds_read_b128 v[94:97], v102 offset:2048
	ds_read_b128 v[102:105], v102 offset:3072
	ds_read_b128 v[114:117], v142
	ds_read_b128 v[122:125], v142 offset:1024
	ds_read_b128 v[134:137], v142 offset:2048
	ds_read_b128 v[142:145], v142 offset:3072
	v_lshl_add_u64 v[194:195], s[8:9], 0, v[214:215]
	s_add_i32 m0, s52, 0xc000
	ds_read_b128 v[154:157], v241
	ds_read_b128 v[166:169], v241 offset:1024
	ds_read_b128 v[170:173], v241 offset:2048
	ds_read_b128 v[174:177], v241 offset:3072
	ds_read_b128 v[178:181], v241 offset:4096
	ds_read_b128 v[182:185], v241 offset:5120
	ds_read_b128 v[186:189], v241 offset:6144
	ds_read_b128 v[190:193], v241 offset:7168
	global_load_lds_dwordx4 v[194:195], off
	v_lshl_add_u64 v[194:195], s[8:9], 0, v[216:217]
	s_add_i32 m0, s52, 0xe000
	s_nop 0
	global_load_lds_dwordx4 v[194:195], off
	s_waitcnt vmcnt(8)
	s_waitcnt lgkmcnt(0)
	s_barrier
	s_setprio 1
	s_waitcnt lgkmcnt(0)
	v_mfma_f32_16x16x32_bf16 v[162:165], v[82:85], v[154:157], 0
	v_mfma_f32_16x16x32_bf16 v[158:161], v[94:97], v[154:157], 0
	v_mfma_f32_16x16x32_bf16 v[150:153], v[82:85], v[170:173], 0
	v_mfma_f32_16x16x32_bf16 v[146:149], v[94:97], v[170:173], 0
	v_mfma_f32_16x16x32_bf16 v[138:141], v[82:85], v[178:181], 0
	v_mfma_f32_16x16x32_bf16 v[130:133], v[94:97], v[178:181], 0
	v_mfma_f32_16x16x32_bf16 v[126:129], v[82:85], v[186:189], 0
	v_mfma_f32_16x16x32_bf16 v[118:121], v[94:97], v[186:189], 0
	v_mfma_f32_16x16x32_bf16 v[162:165], v[86:89], v[166:169], v[162:165]
	v_mfma_f32_16x16x32_bf16 v[158:161], v[102:105], v[166:169], v[158:161]
	v_mfma_f32_16x16x32_bf16 v[150:153], v[86:89], v[174:177], v[150:153]
	v_mfma_f32_16x16x32_bf16 v[146:149], v[102:105], v[174:177], v[146:149]
	v_mfma_f32_16x16x32_bf16 v[138:141], v[86:89], v[182:185], v[138:141]
	v_mfma_f32_16x16x32_bf16 v[130:133], v[102:105], v[182:185], v[130:133]
	v_mfma_f32_16x16x32_bf16 v[126:129], v[86:89], v[190:193], v[126:129]
	v_mfma_f32_16x16x32_bf16 v[118:121], v[102:105], v[190:193], v[118:121]
	s_setprio 0
	s_setprio 1
	v_mfma_f32_16x16x32_bf16 v[62:65], v[114:117], v[154:157], 0
	v_mfma_f32_16x16x32_bf16 v[58:61], v[134:137], v[154:157], 0
	v_mfma_f32_16x16x32_bf16 v[54:57], v[114:117], v[170:173], 0
	v_mfma_f32_16x16x32_bf16 v[50:53], v[134:137], v[170:173], 0
	v_mfma_f32_16x16x32_bf16 v[46:49], v[114:117], v[178:181], 0
	v_mfma_f32_16x16x32_bf16 v[42:45], v[134:137], v[178:181], 0
	v_mfma_f32_16x16x32_bf16 v[38:41], v[114:117], v[186:189], 0
	v_mfma_f32_16x16x32_bf16 v[34:37], v[134:137], v[186:189], 0
	v_mfma_f32_16x16x32_bf16 v[62:65], v[122:125], v[166:169], v[62:65]
	v_mfma_f32_16x16x32_bf16 v[58:61], v[142:145], v[166:169], v[58:61]
	v_mfma_f32_16x16x32_bf16 v[54:57], v[122:125], v[174:177], v[54:57]
	v_mfma_f32_16x16x32_bf16 v[50:53], v[142:145], v[174:177], v[50:53]
	v_mfma_f32_16x16x32_bf16 v[46:49], v[122:125], v[182:185], v[46:49]
	v_mfma_f32_16x16x32_bf16 v[42:45], v[142:145], v[182:185], v[42:45]
	v_mfma_f32_16x16x32_bf16 v[38:41], v[122:125], v[190:193], v[38:41]
	v_mfma_f32_16x16x32_bf16 v[34:37], v[142:145], v[190:193], v[34:37]
	s_setprio 0
	s_barrier
	s_add_i32 s20, s20, s47
	v_lshl_add_u64 v[194:195], s[14:15], 0, v[0:1]
	s_mov_b32 m0, s20
	ds_read_b128 v[154:157], v241 offset:16384
	ds_read_b128 v[166:169], v241 offset:17408
	ds_read_b128 v[170:173], v241 offset:18432
	ds_read_b128 v[174:177], v241 offset:19456
	ds_read_b128 v[178:181], v241 offset:20480
	ds_read_b128 v[182:185], v241 offset:21504
	ds_read_b128 v[186:189], v241 offset:22528
	ds_read_b128 v[190:193], v241 offset:23552
	global_load_lds_dwordx4 v[194:195], off
	s_add_i32 m0, s20, 0x2000
	s_add_u32 s78, s14, 0x20000
	v_lshl_add_u64 v[196:197], s[14:15], 0, v[208:209]
	s_addc_u32 s79, s15, 0
	s_add_i32 s20, s21, s47
	global_load_lds_dwordx4 v[196:197], off
	v_lshl_add_u64 v[198:199], s[78:79], 0, v[0:1]
	s_mov_b32 m0, s20
	v_lshl_add_u64 v[200:201], s[36:37], 0, v[210:211]
	global_load_lds_dwordx4 v[198:199], off
	v_lshl_add_u64 v[198:199], s[78:79], 0, v[208:209]
	s_add_i32 m0, s20, 0x2000
	s_nop 0
	global_load_lds_dwordx4 v[198:199], off
	v_lshl_add_u64 v[198:199], s[36:37], 0, v[212:213]
	s_mov_b32 m0, s52
	s_nop 0
	global_load_lds_dwordx4 v[198:199], off
	s_mov_b32 m0, s53
	s_nop 0
	global_load_lds_dwordx4 v[200:201], off
	s_waitcnt vmcnt(8)
	s_waitcnt lgkmcnt(0)
	s_barrier
; #define PG8_STAGE(bufoff, gbase, voff) do { _Pragma("unroll") for (int _i = 0; _i < 2; ++_i) \
;         __builtin_amdgcn_global_load_lds((const unsigned*)((const char*)(gbase) + (voff)[_i]), (PG8_LAS unsigned*)(lds + (bufoff) + ldsw + _i * 8192), 16, 0, 0); } while (0)
; #define PG8_LDA(dst, b, h) do { _Pragma("unroll") for (int m = 0; m < 4; ++m) _Pragma("unroll") for (int k = 0; k < 2; ++k) dst[m][k] = *(const PG8_LAS bf16x8*)(lds + PG8_SA(b, h) + aoff + m * 2048 + k * 1024); } while (0)
; #define PG8_LDB(dst, b, h) do { _Pragma("unroll") for (int n = 0; n < 2; ++n) _Pragma("unroll") for (int k = 0; k < 2; ++k) dst[n][k] = *(const PG8_LAS bf16x8*)(lds + PG8_SB(b, h) + boff + n * 2048 + k * 1024); } while (0)
; #define PG8_MMA(ai, bj, At, Bt) do { __builtin_amdgcn_s_setprio(1); _Pragma("unroll") for (int m = 0; m < 4; ++m) _Pragma("unroll") for (int n = 0; n < 2; ++n) _Pragma("unroll") for (int k = 0; k < 2; ++k) \
;         acc[ai][bj][m][n] = __builtin_amdgcn_mfma_f32_16x16x32_bf16(Bt[n][k], At[m][k], acc[ai][bj][m][n], 0, 0, 0); __builtin_amdgcn_s_setprio(0); } while (0)
; #define PG8_WAIT_V(n) asm volatile("s_waitcnt vmcnt(" #n ")" ::: "memory")
; #define PG8_WAIT_L(n) asm volatile("s_waitcnt lgkmcnt(" #n ")" ::: "memory")
; #define PG8_BAR __builtin_amdgcn_s_barrier()
; #define PG8_SCHED __builtin_amdgcn_sched_barrier(0)
; template <class Epi, class Sched, bool ALIGN_EPI = false, bool SP2 = false>
; __device__ __forceinline__ void gemm_phase(PG8_LAS unsigned char* lds, const Gemm g, const Sched& S, const Epi& E) {
;     ...
;             PG8_WAIT_V(8); PG8_WAIT_L(0); PG8_BAR; PG8_MMA(1, 0, At, B0); PG8_MMA(1, 1, At, B1); PG8_BAR; PG8_SCHED;
;             PG8_LDB(B0, 1, 0); PG8_LDB(B1, 1, 1); PG8_SCHED; PG8_LDA(At, 1, 0); PG8_STAGE(PG8_SA(0, 1), a2 + hstepA, voffA);
;             PG8_WAIT_V(8); PG8_WAIT_L(0); PG8_BAR; PG8_MMA(0, 0, At, B0); PG8_MMA(0, 1, At, B1); PG8_BAR; PG8_SCHED;
;             PG8_LDA(At, 1, 1); PG8_STAGE(PG8_SB(1, 0), b3, voffB); PG8_STAGE(PG8_SB(1, 1), b3 + hstepB, voffB); PG8_STAGE(PG8_SA(1, 0), a3, voffA);
	s_setprio 1
	s_waitcnt lgkmcnt(0)
	v_mfma_f32_16x16x32_bf16 v[110:113], v[82:85], v[154:157], 0
	v_mfma_f32_16x16x32_bf16 v[106:109], v[94:97], v[154:157], 0
	v_mfma_f32_16x16x32_bf16 v[98:101], v[82:85], v[170:173], 0
	v_mfma_f32_16x16x32_bf16 v[90:93], v[94:97], v[170:173], 0
	v_mfma_f32_16x16x32_bf16 v[78:81], v[82:85], v[178:181], 0
	v_mfma_f32_16x16x32_bf16 v[74:77], v[94:97], v[178:181], 0
	v_mfma_f32_16x16x32_bf16 v[70:73], v[82:85], v[186:189], 0
	v_mfma_f32_16x16x32_bf16 v[66:69], v[94:97], v[186:189], 0
	v_mfma_f32_16x16x32_bf16 v[110:113], v[86:89], v[166:169], v[110:113]
	v_mfma_f32_16x16x32_bf16 v[106:109], v[102:105], v[166:169], v[106:109]
	v_mfma_f32_16x16x32_bf16 v[98:101], v[86:89], v[174:177], v[98:101]
	v_mfma_f32_16x16x32_bf16 v[90:93], v[102:105], v[174:177], v[90:93]
	v_mfma_f32_16x16x32_bf16 v[78:81], v[86:89], v[182:185], v[78:81]
	v_mfma_f32_16x16x32_bf16 v[74:77], v[102:105], v[182:185], v[74:77]
	v_mfma_f32_16x16x32_bf16 v[70:73], v[86:89], v[190:193], v[70:73]
	v_mfma_f32_16x16x32_bf16 v[66:69], v[102:105], v[190:193], v[66:69]
	s_setprio 0
	s_setprio 1
	v_mfma_f32_16x16x32_bf16 v[30:33], v[114:117], v[154:157], 0
	v_mfma_f32_16x16x32_bf16 v[26:29], v[134:137], v[154:157], 0
	v_mfma_f32_16x16x32_bf16 v[22:25], v[114:117], v[170:173], 0
	v_mfma_f32_16x16x32_bf16 v[18:21], v[134:137], v[170:173], 0
	v_mfma_f32_16x16x32_bf16 v[14:17], v[114:117], v[178:181], 0
	v_mfma_f32_16x16x32_bf16 v[10:13], v[134:137], v[178:181], 0
	v_mfma_f32_16x16x32_bf16 v[6:9], v[114:117], v[186:189], 0
	v_mfma_f32_16x16x32_bf16 v[2:5], v[134:137], v[186:189], 0
	v_mfma_f32_16x16x32_bf16 v[30:33], v[122:125], v[166:169], v[30:33]
	v_mfma_f32_16x16x32_bf16 v[26:29], v[142:145], v[166:169], v[26:29]
	v_mfma_f32_16x16x32_bf16 v[22:25], v[122:125], v[174:177], v[22:25]
	v_mfma_f32_16x16x32_bf16 v[18:21], v[142:145], v[174:177], v[18:21]
	v_mfma_f32_16x16x32_bf16 v[14:17], v[122:125], v[182:185], v[14:17]
	v_mfma_f32_16x16x32_bf16 v[10:13], v[142:145], v[182:185], v[10:13]
	v_mfma_f32_16x16x32_bf16 v[6:9], v[122:125], v[190:193], v[6:9]
	v_mfma_f32_16x16x32_bf16 v[2:5], v[142:145], v[190:193], v[2:5]
	s_setprio 0
	s_barrier
	s_add_i32 s20, 0, 0x18000
	s_add_i32 s21, 0, 0x1c000
	v_add_u32_e32 v102, s20, v239
	v_add_u32_e32 v142, s21, v239
	ds_read_b128 v[82:85], v102
	ds_read_b128 v[86:89], v102 offset:1024
	ds_read_b128 v[94:97], v102 offset:2048
	ds_read_b128 v[102:105], v102 offset:3072
	ds_read_b128 v[114:117], v142
	ds_read_b128 v[122:125], v142 offset:1024
	ds_read_b128 v[134:137], v142 offset:2048
	ds_read_b128 v[142:145], v142 offset:3072
	s_add_u32 s36, s36, 0x20000
	s_addc_u32 s37, s37, 0
	s_mov_b32 m0, s54
	v_lshl_add_u64 v[218:219], s[36:37], 0, v[212:213]
	ds_read_b128 v[154:157], v241 offset:32768
	ds_read_b128 v[166:169], v241 offset:33792
	ds_read_b128 v[170:173], v241 offset:34816
	ds_read_b128 v[174:177], v241 offset:35840
	ds_read_b128 v[178:181], v241 offset:36864
	ds_read_b128 v[182:185], v241 offset:37888
	ds_read_b128 v[186:189], v241 offset:38912
	ds_read_b128 v[190:193], v241 offset:39936
	global_load_lds_dwordx4 v[218:219], off
	v_lshl_add_u64 v[218:219], s[36:37], 0, v[210:211]
	s_mov_b32 m0, s55
	s_nop 0
	global_load_lds_dwordx4 v[218:219], off
	s_waitcnt vmcnt(8)
	s_waitcnt lgkmcnt(0)
	s_barrier
	s_setprio 1
	s_waitcnt lgkmcnt(0)
	v_mfma_f32_16x16x32_bf16 v[162:165], v[82:85], v[154:157], v[162:165]
	v_mfma_f32_16x16x32_bf16 v[158:161], v[94:97], v[154:157], v[158:161]
	v_mfma_f32_16x16x32_bf16 v[150:153], v[82:85], v[170:173], v[150:153]
	v_mfma_f32_16x16x32_bf16 v[146:149], v[94:97], v[170:173], v[146:149]
	v_mfma_f32_16x16x32_bf16 v[138:141], v[82:85], v[178:181], v[138:141]
	v_mfma_f32_16x16x32_bf16 v[130:133], v[94:97], v[178:181], v[130:133]
	v_mfma_f32_16x16x32_bf16 v[126:129], v[82:85], v[186:189], v[126:129]
	v_mfma_f32_16x16x32_bf16 v[118:121], v[94:97], v[186:189], v[118:121]
	v_mfma_f32_16x16x32_bf16 v[162:165], v[86:89], v[166:169], v[162:165]
	v_mfma_f32_16x16x32_bf16 v[158:161], v[102:105], v[166:169], v[158:161]
	v_mfma_f32_16x16x32_bf16 v[150:153], v[86:89], v[174:177], v[150:153]
	v_mfma_f32_16x16x32_bf16 v[146:149], v[102:105], v[174:177], v[146:149]
	v_mfma_f32_16x16x32_bf16 v[138:141], v[86:89], v[182:185], v[138:141]
	v_mfma_f32_16x16x32_bf16 v[130:133], v[102:105], v[182:185], v[130:133]
	v_mfma_f32_16x16x32_bf16 v[126:129], v[86:89], v[190:193], v[126:129]
	v_mfma_f32_16x16x32_bf16 v[118:121], v[102:105], v[190:193], v[118:121]
	s_setprio 0
	s_setprio 1
	v_mfma_f32_16x16x32_bf16 v[62:65], v[114:117], v[154:157], v[62:65]
	v_mfma_f32_16x16x32_bf16 v[58:61], v[134:137], v[154:157], v[58:61]
	v_mfma_f32_16x16x32_bf16 v[54:57], v[114:117], v[170:173], v[54:57]
	v_mfma_f32_16x16x32_bf16 v[50:53], v[134:137], v[170:173], v[50:53]
	v_mfma_f32_16x16x32_bf16 v[46:49], v[114:117], v[178:181], v[46:49]
	v_mfma_f32_16x16x32_bf16 v[42:45], v[134:137], v[178:181], v[42:45]
	v_mfma_f32_16x16x32_bf16 v[38:41], v[114:117], v[186:189], v[38:41]
	v_mfma_f32_16x16x32_bf16 v[34:37], v[134:137], v[186:189], v[34:37]
	v_mfma_f32_16x16x32_bf16 v[62:65], v[122:125], v[166:169], v[62:65]
	v_mfma_f32_16x16x32_bf16 v[58:61], v[142:145], v[166:169], v[58:61]
	v_mfma_f32_16x16x32_bf16 v[54:57], v[122:125], v[174:177], v[54:57]
	v_mfma_f32_16x16x32_bf16 v[50:53], v[142:145], v[174:177], v[50:53]
	v_mfma_f32_16x16x32_bf16 v[46:49], v[122:125], v[182:185], v[46:49]
	v_mfma_f32_16x16x32_bf16 v[42:45], v[142:145], v[182:185], v[42:45]
	v_mfma_f32_16x16x32_bf16 v[38:41], v[122:125], v[190:193], v[38:41]
	v_mfma_f32_16x16x32_bf16 v[34:37], v[142:145], v[190:193], v[34:37]
	s_setprio 0
	s_barrier
; #define PG8_STAGE(bufoff, gbase, voff) do { _Pragma("unroll") for (int _i = 0; _i < 2; ++_i) \
;         __builtin_amdgcn_global_load_lds((const unsigned*)((const char*)(gbase) + (voff)[_i]), (PG8_LAS unsigned*)(lds + (bufoff) + ldsw + _i * 8192), 16, 0, 0); } while (0)
; #define PG8_LDA(dst, b, h) do { _Pragma("unroll") for (int m = 0; m < 4; ++m) _Pragma("unroll") for (int k = 0; k < 2; ++k) dst[m][k] = *(const PG8_LAS bf16x8*)(lds + PG8_SA(b, h) + aoff + m * 2048 + k * 1024); } while (0)
; #define PG8_MMA(ai, bj, At, Bt) do { __builtin_amdgcn_s_setprio(1); _Pragma("unroll") for (int m = 0; m < 4; ++m) _Pragma("unroll") for (int n = 0; n < 2; ++n) _Pragma("unroll") for (int k = 0; k < 2; ++k) \
;         acc[ai][bj][m][n] = __builtin_amdgcn_mfma_f32_16x16x32_bf16(Bt[n][k], At[m][k], acc[ai][bj][m][n], 0, 0, 0); __builtin_amdgcn_s_setprio(0); } while (0)
; #define PG8_WAIT_V(n) asm volatile("s_waitcnt vmcnt(" #n ")" ::: "memory")
; #define PG8_WAIT_L(n) asm volatile("s_waitcnt lgkmcnt(" #n ")" ::: "memory")
; #define PG8_BAR __builtin_amdgcn_s_barrier()
; #define PG8_SCHED __builtin_amdgcn_sched_barrier(0)
; template <class Epi, class Sched, bool ALIGN_EPI = false, bool SP2 = false>
; __device__ __forceinline__ void gemm_phase(PG8_LAS unsigned char* lds, const Gemm g, const Sched& S, const Epi& E) {
;     ...
;         for (int t = 0; t < nt; t += 2) {
;             const bool last = (t == nt - 2);
;     ...
;             PG8_LDA(At, 1, 1); PG8_STAGE(PG8_SB(1, 0), b3, voffB); PG8_STAGE(PG8_SB(1, 1), b3 + hstepB, voffB); PG8_STAGE(PG8_SA(1, 0), a3, voffA);
;             PG8_WAIT_V(8); PG8_WAIT_L(0); PG8_BAR; PG8_MMA(1, 0, At, B0); PG8_MMA(1, 1, At, B1); PG8_BAR; PG8_SCHED;
	s_add_i32 s20, s20, s47
	v_lshl_add_u64 v[194:195], v[194:195], 0, s[22:23]
	s_mov_b32 m0, s20
	ds_read_b128 v[154:157], v241 offset:49152
	ds_read_b128 v[166:169], v241 offset:50176
	ds_read_b128 v[170:173], v241 offset:51200
	ds_read_b128 v[174:177], v241 offset:52224
	ds_read_b128 v[178:181], v241 offset:53248
	ds_read_b128 v[182:185], v241 offset:54272
	ds_read_b128 v[186:189], v241 offset:55296
	ds_read_b128 v[190:193], v241 offset:56320
	global_load_lds_dwordx4 v[194:195], off
	s_add_i32 m0, s20, 0x2000
	s_add_u32 s14, s14, 0x20080
	v_lshl_add_u64 v[194:195], v[196:197], 0, s[22:23]
	s_addc_u32 s15, s15, 0
	s_add_i32 s20, s21, s47
	global_load_lds_dwordx4 v[194:195], off
	v_lshl_add_u64 v[194:195], s[14:15], 0, v[0:1]
	s_mov_b32 m0, s20
	s_nop 0
	global_load_lds_dwordx4 v[194:195], off
	v_lshl_add_u64 v[194:195], s[14:15], 0, v[208:209]
	s_add_i32 m0, s20, 0x2000
	s_nop 0
	global_load_lds_dwordx4 v[194:195], off
	v_lshl_add_u64 v[194:195], v[198:199], 0, s[22:23]
	s_mov_b32 m0, s56
	s_nop 0
	global_load_lds_dwordx4 v[194:195], off
	v_lshl_add_u64 v[194:195], v[200:201], 0, s[22:23]
	s_mov_b32 m0, s57
	s_nop 0
	global_load_lds_dwordx4 v[194:195], off
	s_waitcnt vmcnt(8)
	s_waitcnt lgkmcnt(0)
	s_barrier
	s_setprio 1
	s_waitcnt lgkmcnt(0)
	v_mfma_f32_16x16x32_bf16 v[110:113], v[82:85], v[154:157], v[110:113]
	v_mfma_f32_16x16x32_bf16 v[106:109], v[94:97], v[154:157], v[106:109]
	v_mfma_f32_16x16x32_bf16 v[98:101], v[82:85], v[170:173], v[98:101]
	v_mfma_f32_16x16x32_bf16 v[90:93], v[94:97], v[170:173], v[90:93]
	v_mfma_f32_16x16x32_bf16 v[78:81], v[82:85], v[178:181], v[78:81]
	v_mfma_f32_16x16x32_bf16 v[74:77], v[94:97], v[178:181], v[74:77]
	v_mfma_f32_16x16x32_bf16 v[70:73], v[82:85], v[186:189], v[70:73]
	v_mfma_f32_16x16x32_bf16 v[66:69], v[94:97], v[186:189], v[66:69]
	v_mfma_f32_16x16x32_bf16 v[110:113], v[86:89], v[166:169], v[110:113]
	v_mfma_f32_16x16x32_bf16 v[106:109], v[102:105], v[166:169], v[106:109]
	v_mfma_f32_16x16x32_bf16 v[98:101], v[86:89], v[174:177], v[98:101]
	v_mfma_f32_16x16x32_bf16 v[90:93], v[102:105], v[174:177], v[90:93]
	v_mfma_f32_16x16x32_bf16 v[78:81], v[86:89], v[182:185], v[78:81]
	v_mfma_f32_16x16x32_bf16 v[74:77], v[102:105], v[182:185], v[74:77]
	v_mfma_f32_16x16x32_bf16 v[70:73], v[86:89], v[190:193], v[70:73]
	v_mfma_f32_16x16x32_bf16 v[66:69], v[102:105], v[190:193], v[66:69]
	s_setprio 0
	s_setprio 1
	v_mfma_f32_16x16x32_bf16 v[30:33], v[114:117], v[154:157], v[30:33]
	v_mfma_f32_16x16x32_bf16 v[26:29], v[134:137], v[154:157], v[26:29]
	v_mfma_f32_16x16x32_bf16 v[22:25], v[114:117], v[170:173], v[22:25]
	v_mfma_f32_16x16x32_bf16 v[18:21], v[134:137], v[170:173], v[18:21]
	v_mfma_f32_16x16x32_bf16 v[14:17], v[114:117], v[178:181], v[14:17]
	v_mfma_f32_16x16x32_bf16 v[10:13], v[134:137], v[178:181], v[10:13]
	v_mfma_f32_16x16x32_bf16 v[6:9], v[114:117], v[186:189], v[6:9]
	v_mfma_f32_16x16x32_bf16 v[2:5], v[134:137], v[186:189], v[2:5]
	v_mfma_f32_16x16x32_bf16 v[30:33], v[122:125], v[166:169], v[30:33]
	v_mfma_f32_16x16x32_bf16 v[26:29], v[142:145], v[166:169], v[26:29]
	v_mfma_f32_16x16x32_bf16 v[22:25], v[122:125], v[174:177], v[22:25]
	v_mfma_f32_16x16x32_bf16 v[18:21], v[142:145], v[174:177], v[18:21]
	v_mfma_f32_16x16x32_bf16 v[14:17], v[122:125], v[182:185], v[14:17]
	v_mfma_f32_16x16x32_bf16 v[10:13], v[142:145], v[182:185], v[10:13]
	v_mfma_f32_16x16x32_bf16 v[6:9], v[122:125], v[190:193], v[6:9]
	v_mfma_f32_16x16x32_bf16 v[2:5], v[142:145], v[190:193], v[2:5]
	s_setprio 0
	s_barrier
	s_add_i32 s71, s71, 2
	s_add_u32 s8, s8, 0x100
	s_addc_u32 s9, s9, 0
	s_add_u32 s63, s63, 0x100
	s_addc_u32 s70, s70, 0
	s_cmp_gt_u32 s71, 5
	s_cbranch_scc1 .Lpk_done_g1048

; #define PG8_BAR __builtin_amdgcn_s_barrier()
; template <class Epi, class Sched, bool ALIGN_EPI = false, bool SP2 = false>
; __device__ __forceinline__ void gemm_phase(PG8_LAS unsigned char* lds, const Gemm g, const Sched& S, const Epi& E) {
;     ...
;         }
;         if constexpr (ALIGN_EPI) { if (wr == 0) PG8_BAR; }
.Lpk_done_g1048:
	v_mov_b64_e32 v[206:207], 0x400
	s_and_b64 vcc, exec, s[18:19]
	s_cbranch_vccz .LBB0_1051
	s_barrier

; #define PG8_STAGE(bufoff, gbase, voff) do { _Pragma("unroll") for (int _i = 0; _i < 2; ++_i) \
;         __builtin_amdgcn_global_load_lds((const unsigned*)((const char*)(gbase) + (voff)[_i]), (PG8_LAS unsigned*)(lds + (bufoff) + ldsw + _i * 8192), 16, 0, 0); } while (0)
; #define PG8_LDA(dst, b, h) do { _Pragma("unroll") for (int m = 0; m < 4; ++m) _Pragma("unroll") for (int k = 0; k < 2; ++k) dst[m][k] = *(const PG8_LAS bf16x8*)(lds + PG8_SA(b, h) + aoff + m * 2048 + k * 1024); } while (0)
; #define PG8_LDB(dst, b, h) do { _Pragma("unroll") for (int n = 0; n < 2; ++n) _Pragma("unroll") for (int k = 0; k < 2; ++k) dst[n][k] = *(const PG8_LAS bf16x8*)(lds + PG8_SB(b, h) + boff + n * 2048 + k * 1024); } while (0)
; #define PG8_WAIT_V(n) asm volatile("s_waitcnt vmcnt(" #n ")" ::: "memory")
; #define PG8_BAR __builtin_amdgcn_s_barrier()
; template <class Epi, class Sched, bool ALIGN_EPI = false, bool SP2 = false>
; __device__ __forceinline__ void gemm_phase(PG8_LAS unsigned char* lds, const Gemm g, const Sched& S, const Epi& E) {
;     ...
;         const char* nA = has_next ? (const char*)g.A + (size_t)nxt.pm * tstepA + (size_t)nxt.pb * g.sA : cA; const char* nB = has_next ? (const char*)g.Bt + (size_t)nxt.pn * tstepB + (size_t)nxt.pb * g.sB : cB;
;         for (int t = 0; t < nt; t += 2) {
;             const bool last = (t == nt - 2);
;             const char* a1 = cA + (size_t)(t + 1) * kstep;
;             const char* a2 = last ? nA : cA + (size_t)(t + 2) * kstep; const char* b2 = last ? nB : cB + (size_t)(t + 2) * kstep;
;             const char* a3 = a2 + kstep; const char* b3 = b2 + kstep;
;             if (last && has_next) S.a_ready(nxt);
;             if constexpr (SP2) {
;             PG8_LDB(B0, 0, 0); PG8_LDB(B1, 0, 1); PG8_SCHED; PG8_LDA(At, 0, 0); PG8_STAGE(PG8_SA(1, 1), a1 + hstepA, voffA);
;             PG8_WAIT_V(8); PG8_WAIT_L(0); PG8_BAR; PG8_MMA(0, 0, At, B0); PG8_MMA(0, 1, At, B1); PG8_BAR; PG8_SCHED;
;             PG8_LDA(At, 0, 1); PG8_STAGE(PG8_SB(0, 0), b2, voffB); PG8_STAGE(PG8_SB(0, 1), b2 + hstepB, voffB); PG8_STAGE(PG8_SA(0, 0), a2, voffA);
;     ...
; #pragma unroll
;         for (int a = 0; a < 2; ++a)
; #pragma unroll
;             for (int b = 0; b < 2; ++b)
; #pragma unroll
;                 for (int m = 0; m < 4; ++m)
; #pragma unroll
;                     for (int n = 0; n < 2; ++n) acc[a][b][m][n] = (f32x4){0.f, 0.f, 0.f, 0.f};
.LBB0_1136:
	s_ashr_i32 s53, s52, 31
	s_lshl_b64 s[34:35], s[52:53], 19
	s_add_u32 s62, s56, s34
	s_addc_u32 s63, s57, s35
	s_and_b64 s[34:35], s[44:45], exec
	s_cselect_b32 s9, s63, s1
	s_cselect_b32 s39, s62, s0
	s_ashr_i32 s47, s46, 31
	s_lshl_b64 s[34:35], s[46:47], 19
	s_add_u32 s34, s26, s34
	s_addc_u32 s35, s60, s35
	s_and_b64 s[36:37], s[44:45], exec
	s_cselect_b32 s47, s35, s15
	s_cselect_b32 s53, s34, s14
	s_add_u32 s0, s0, 0x40080
	s_addc_u32 s1, s1, 0
	s_add_u32 s54, s14, 0x100
	s_addc_u32 s55, s15, 0
	s_mov_b32 s85, -2
	s_waitcnt lgkmcnt(0)
	s_add_u32 s14, s0, 0xfffc0080
	s_addc_u32 s15, s1, -1
	s_add_i32 s20, 0, 0x10000
	s_cmp_eq_u32 s85, 12
	s_cselect_b32 s37, s9, s15
	s_cselect_b32 s36, s39, s14
	s_cselect_b32 s15, s47, s55
	s_cselect_b32 s14, s53, s54
	s_add_i32 s21, 0, 0x14000
	v_add_u32_e32 v102, s20, v222
	v_add_u32_e32 v158, s21, v222
	ds_read_b128 v[90:93], v102
	ds_read_b128 v[94:97], v102 offset:1024
	ds_read_b128 v[98:101], v102 offset:2048
	ds_read_b128 v[102:105], v102 offset:3072
	ds_read_b128 v[146:149], v158
	ds_read_b128 v[150:153], v158 offset:1024
	ds_read_b128 v[154:157], v158 offset:2048
	ds_read_b128 v[158:161], v158 offset:3072
	v_lshl_add_u64 v[204:205], s[0:1], 0, v[214:215]
	s_add_i32 m0, s70, 0xc000
	ds_read_b128 v[162:165], v227
	ds_read_b128 v[166:169], v227 offset:1024
	ds_read_b128 v[170:173], v227 offset:2048
	ds_read_b128 v[174:177], v227 offset:3072
	ds_read_b128 v[178:181], v227 offset:4096
	ds_read_b128 v[182:185], v227 offset:5120
	ds_read_b128 v[218:221], v227 offset:6144
	ds_read_b128 v[240:243], v227 offset:7168
	global_load_lds_dwordx4 v[204:205], off
	v_lshl_add_u64 v[204:205], s[0:1], 0, v[216:217]
	s_add_i32 m0, s70, 0xe000
	s_nop 0
	global_load_lds_dwordx4 v[204:205], off
	s_waitcnt vmcnt(8)
	s_waitcnt lgkmcnt(0)
	s_barrier
	s_setprio 1
	s_waitcnt lgkmcnt(0)
	v_mfma_f32_16x16x32_bf16 v[142:145], v[90:93], v[162:165], 0
	v_mfma_f32_16x16x32_bf16 v[138:141], v[98:101], v[162:165], 0
	v_mfma_f32_16x16x32_bf16 v[126:129], v[90:93], v[170:173], 0
	v_mfma_f32_16x16x32_bf16 v[122:125], v[98:101], v[170:173], 0
	v_mfma_f32_16x16x32_bf16 v[110:113], v[90:93], v[178:181], 0
	v_mfma_f32_16x16x32_bf16 v[106:109], v[98:101], v[178:181], 0
	v_mfma_f32_16x16x32_bf16 v[78:81], v[90:93], v[218:221], 0
	v_mfma_f32_16x16x32_bf16 v[74:77], v[98:101], v[218:221], 0
	v_mfma_f32_16x16x32_bf16 v[142:145], v[94:97], v[166:169], v[142:145]
	v_mfma_f32_16x16x32_bf16 v[138:141], v[102:105], v[166:169], v[138:141]
	v_mfma_f32_16x16x32_bf16 v[126:129], v[94:97], v[174:177], v[126:129]
	v_mfma_f32_16x16x32_bf16 v[122:125], v[102:105], v[174:177], v[122:125]
	v_mfma_f32_16x16x32_bf16 v[110:113], v[94:97], v[182:185], v[110:113]
	v_mfma_f32_16x16x32_bf16 v[106:109], v[102:105], v[182:185], v[106:109]
	v_mfma_f32_16x16x32_bf16 v[78:81], v[94:97], v[240:243], v[78:81]
	v_mfma_f32_16x16x32_bf16 v[74:77], v[102:105], v[240:243], v[74:77]
	s_setprio 0
	s_setprio 1
	v_mfma_f32_16x16x32_bf16 v[134:137], v[146:149], v[162:165], 0
	v_mfma_f32_16x16x32_bf16 v[130:133], v[154:157], v[162:165], 0
	v_mfma_f32_16x16x32_bf16 v[118:121], v[146:149], v[170:173], 0
	v_mfma_f32_16x16x32_bf16 v[114:117], v[154:157], v[170:173], 0
	v_mfma_f32_16x16x32_bf16 v[86:89], v[146:149], v[178:181], 0
	v_mfma_f32_16x16x32_bf16 v[82:85], v[154:157], v[178:181], 0
	v_mfma_f32_16x16x32_bf16 v[70:73], v[146:149], v[218:221], 0
	v_mfma_f32_16x16x32_bf16 v[66:69], v[154:157], v[218:221], 0
	v_mfma_f32_16x16x32_bf16 v[134:137], v[150:153], v[166:169], v[134:137]
	v_mfma_f32_16x16x32_bf16 v[130:133], v[158:161], v[166:169], v[130:133]
	v_mfma_f32_16x16x32_bf16 v[118:121], v[150:153], v[174:177], v[118:121]
	v_mfma_f32_16x16x32_bf16 v[114:117], v[158:161], v[174:177], v[114:117]
	v_mfma_f32_16x16x32_bf16 v[86:89], v[150:153], v[182:185], v[86:89]
	v_mfma_f32_16x16x32_bf16 v[82:85], v[158:161], v[182:185], v[82:85]
	v_mfma_f32_16x16x32_bf16 v[70:73], v[150:153], v[240:243], v[70:73]
	v_mfma_f32_16x16x32_bf16 v[66:69], v[158:161], v[240:243], v[66:69]
	s_setprio 0
	s_barrier
	s_add_i32 s20, s20, s61
	v_lshl_add_u64 v[204:205], s[14:15], 0, v[0:1]
	s_mov_b32 m0, s20
	ds_read_b128 v[162:165], v227 offset:16384
	ds_read_b128 v[166:169], v227 offset:17408
	ds_read_b128 v[170:173], v227 offset:18432
	ds_read_b128 v[174:177], v227 offset:19456
	ds_read_b128 v[178:181], v227 offset:20480
	ds_read_b128 v[182:185], v227 offset:21504
	ds_read_b128 v[218:221], v227 offset:22528
	ds_read_b128 v[240:243], v227 offset:23552
	global_load_lds_dwordx4 v[204:205], off
	s_add_i32 m0, s20, 0x2000
	s_add_u32 s86, s14, 0x40000
	v_lshl_add_u64 v[234:235], s[14:15], 0, v[186:187]
	s_addc_u32 s87, s15, 0
	s_add_i32 s20, s21, s61
	global_load_lds_dwordx4 v[234:235], off
	v_lshl_add_u64 v[244:245], s[86:87], 0, v[0:1]
	s_mov_b32 m0, s20
	v_lshl_add_u64 v[246:247], s[36:37], 0, v[188:189]
	global_load_lds_dwordx4 v[244:245], off
	v_lshl_add_u64 v[244:245], s[86:87], 0, v[186:187]
	s_add_i32 m0, s20, 0x2000
	s_nop 0
	global_load_lds_dwordx4 v[244:245], off
	v_lshl_add_u64 v[244:245], s[36:37], 0, v[190:191]
	s_mov_b32 m0, s70
	s_nop 0
	global_load_lds_dwordx4 v[244:245], off
	s_mov_b32 m0, s71
	s_nop 0
	global_load_lds_dwordx4 v[246:247], off
	s_waitcnt vmcnt(8)
	s_waitcnt lgkmcnt(0)
	s_barrier
; #define PG8_STAGE(bufoff, gbase, voff) do { _Pragma("unroll") for (int _i = 0; _i < 2; ++_i) \
;         __builtin_amdgcn_global_load_lds((const unsigned*)((const char*)(gbase) + (voff)[_i]), (PG8_LAS unsigned*)(lds + (bufoff) + ldsw + _i * 8192), 16, 0, 0); } while (0)
; #define PG8_LDA(dst, b, h) do { _Pragma("unroll") for (int m = 0; m < 4; ++m) _Pragma("unroll") for (int k = 0; k < 2; ++k) dst[m][k] = *(const PG8_LAS bf16x8*)(lds + PG8_SA(b, h) + aoff + m * 2048 + k * 1024); } while (0)
; #define PG8_LDB(dst, b, h) do { _Pragma("unroll") for (int n = 0; n < 2; ++n) _Pragma("unroll") for (int k = 0; k < 2; ++k) dst[n][k] = *(const PG8_LAS bf16x8*)(lds + PG8_SB(b, h) + boff + n * 2048 + k * 1024); } while (0)
; #define PG8_MMA(ai, bj, At, Bt) do { __builtin_amdgcn_s_setprio(1); _Pragma("unroll") for (int m = 0; m < 4; ++m) _Pragma("unroll") for (int n = 0; n < 2; ++n) _Pragma("unroll") for (int k = 0; k < 2; ++k) \
;         acc[ai][bj][m][n] = __builtin_amdgcn_mfma_f32_16x16x32_bf16(Bt[n][k], At[m][k], acc[ai][bj][m][n], 0, 0, 0); __builtin_amdgcn_s_setprio(0); } while (0)
; #define PG8_WAIT_V(n) asm volatile("s_waitcnt vmcnt(" #n ")" ::: "memory")
; #define PG8_WAIT_L(n) asm volatile("s_waitcnt lgkmcnt(" #n ")" ::: "memory")
; #define PG8_BAR __builtin_amdgcn_s_barrier()
; #define PG8_SCHED __builtin_amdgcn_sched_barrier(0)
; template <class Epi, class Sched, bool ALIGN_EPI = false, bool SP2 = false>
; __device__ __forceinline__ void gemm_phase(PG8_LAS unsigned char* lds, const Gemm g, const Sched& S, const Epi& E) {
;     ...
;             PG8_WAIT_V(8); PG8_WAIT_L(0); PG8_BAR; PG8_MMA(1, 0, At, B0); PG8_MMA(1, 1, At, B1); PG8_BAR; PG8_SCHED;
;             PG8_LDB(B0, 1, 0); PG8_LDB(B1, 1, 1); PG8_SCHED; PG8_LDA(At, 1, 0); PG8_STAGE(PG8_SA(0, 1), a2 + hstepA, voffA);
;             PG8_WAIT_V(8); PG8_WAIT_L(0); PG8_BAR; PG8_MMA(0, 0, At, B0); PG8_MMA(0, 1, At, B1); PG8_BAR; PG8_SCHED;
;             PG8_LDA(At, 1, 1); PG8_STAGE(PG8_SB(1, 0), b3, voffB); PG8_STAGE(PG8_SB(1, 1), b3 + hstepB, voffB); PG8_STAGE(PG8_SA(1, 0), a3, voffA);
	s_setprio 1
	s_waitcnt lgkmcnt(0)
	v_mfma_f32_16x16x32_bf16 v[62:65], v[90:93], v[162:165], 0
	v_mfma_f32_16x16x32_bf16 v[58:61], v[98:101], v[162:165], 0
	v_mfma_f32_16x16x32_bf16 v[46:49], v[90:93], v[170:173], 0
	v_mfma_f32_16x16x32_bf16 v[42:45], v[98:101], v[170:173], 0
	v_mfma_f32_16x16x32_bf16 v[30:33], v[90:93], v[178:181], 0
	v_mfma_f32_16x16x32_bf16 v[26:29], v[98:101], v[178:181], 0
	v_mfma_f32_16x16x32_bf16 v[14:17], v[90:93], v[218:221], 0
	v_mfma_f32_16x16x32_bf16 v[10:13], v[98:101], v[218:221], 0
	v_mfma_f32_16x16x32_bf16 v[62:65], v[94:97], v[166:169], v[62:65]
	v_mfma_f32_16x16x32_bf16 v[58:61], v[102:105], v[166:169], v[58:61]
	v_mfma_f32_16x16x32_bf16 v[46:49], v[94:97], v[174:177], v[46:49]
	v_mfma_f32_16x16x32_bf16 v[42:45], v[102:105], v[174:177], v[42:45]
	v_mfma_f32_16x16x32_bf16 v[30:33], v[94:97], v[182:185], v[30:33]
	v_mfma_f32_16x16x32_bf16 v[26:29], v[102:105], v[182:185], v[26:29]
	v_mfma_f32_16x16x32_bf16 v[14:17], v[94:97], v[240:243], v[14:17]
	v_mfma_f32_16x16x32_bf16 v[10:13], v[102:105], v[240:243], v[10:13]
	s_setprio 0
	s_setprio 1
	v_mfma_f32_16x16x32_bf16 v[54:57], v[146:149], v[162:165], 0
	v_mfma_f32_16x16x32_bf16 v[50:53], v[154:157], v[162:165], 0
	v_mfma_f32_16x16x32_bf16 v[38:41], v[146:149], v[170:173], 0
	v_mfma_f32_16x16x32_bf16 v[34:37], v[154:157], v[170:173], 0
	v_mfma_f32_16x16x32_bf16 v[22:25], v[146:149], v[178:181], 0
	v_mfma_f32_16x16x32_bf16 v[18:21], v[154:157], v[178:181], 0
	v_mfma_f32_16x16x32_bf16 v[6:9], v[146:149], v[218:221], 0
	v_mfma_f32_16x16x32_bf16 v[2:5], v[154:157], v[218:221], 0
	v_mfma_f32_16x16x32_bf16 v[54:57], v[150:153], v[166:169], v[54:57]
	v_mfma_f32_16x16x32_bf16 v[50:53], v[158:161], v[166:169], v[50:53]
	v_mfma_f32_16x16x32_bf16 v[38:41], v[150:153], v[174:177], v[38:41]
	v_mfma_f32_16x16x32_bf16 v[34:37], v[158:161], v[174:177], v[34:37]
	v_mfma_f32_16x16x32_bf16 v[22:25], v[150:153], v[182:185], v[22:25]
	v_mfma_f32_16x16x32_bf16 v[18:21], v[158:161], v[182:185], v[18:21]
	v_mfma_f32_16x16x32_bf16 v[6:9], v[150:153], v[240:243], v[6:9]
	v_mfma_f32_16x16x32_bf16 v[2:5], v[158:161], v[240:243], v[2:5]
	s_setprio 0
	s_barrier
	s_add_i32 s20, 0, 0x18000
	s_add_i32 s21, 0, 0x1c000
	v_add_u32_e32 v102, s20, v222
	v_add_u32_e32 v158, s21, v222
	ds_read_b128 v[90:93], v102
	ds_read_b128 v[94:97], v102 offset:1024
	ds_read_b128 v[98:101], v102 offset:2048
	ds_read_b128 v[102:105], v102 offset:3072
	ds_read_b128 v[146:149], v158
	ds_read_b128 v[150:153], v158 offset:1024
	ds_read_b128 v[154:157], v158 offset:2048
	ds_read_b128 v[158:161], v158 offset:3072
	s_add_u32 s36, s36, 0x40000
	s_addc_u32 s37, s37, 0
	s_mov_b32 m0, s78
	v_lshl_add_u64 v[248:249], s[36:37], 0, v[190:191]
	ds_read_b128 v[162:165], v227 offset:32768
	ds_read_b128 v[166:169], v227 offset:33792
	ds_read_b128 v[170:173], v227 offset:34816
	ds_read_b128 v[174:177], v227 offset:35840
	ds_read_b128 v[178:181], v227 offset:36864
	ds_read_b128 v[182:185], v227 offset:37888
	ds_read_b128 v[218:221], v227 offset:38912
	ds_read_b128 v[240:243], v227 offset:39936
	global_load_lds_dwordx4 v[248:249], off
	v_lshl_add_u64 v[248:249], s[36:37], 0, v[188:189]
	s_mov_b32 m0, s79
	s_nop 0
	global_load_lds_dwordx4 v[248:249], off
	s_waitcnt vmcnt(8)
	s_waitcnt lgkmcnt(0)
	s_barrier
	s_setprio 1
	s_waitcnt lgkmcnt(0)
	v_mfma_f32_16x16x32_bf16 v[142:145], v[90:93], v[162:165], v[142:145]
	v_mfma_f32_16x16x32_bf16 v[138:141], v[98:101], v[162:165], v[138:141]
	v_mfma_f32_16x16x32_bf16 v[126:129], v[90:93], v[170:173], v[126:129]
	v_mfma_f32_16x16x32_bf16 v[122:125], v[98:101], v[170:173], v[122:125]
	v_mfma_f32_16x16x32_bf16 v[110:113], v[90:93], v[178:181], v[110:113]
	v_mfma_f32_16x16x32_bf16 v[106:109], v[98:101], v[178:181], v[106:109]
	v_mfma_f32_16x16x32_bf16 v[78:81], v[90:93], v[218:221], v[78:81]
	v_mfma_f32_16x16x32_bf16 v[74:77], v[98:101], v[218:221], v[74:77]
	v_mfma_f32_16x16x32_bf16 v[142:145], v[94:97], v[166:169], v[142:145]
	v_mfma_f32_16x16x32_bf16 v[138:141], v[102:105], v[166:169], v[138:141]
	v_mfma_f32_16x16x32_bf16 v[126:129], v[94:97], v[174:177], v[126:129]
	v_mfma_f32_16x16x32_bf16 v[122:125], v[102:105], v[174:177], v[122:125]
	v_mfma_f32_16x16x32_bf16 v[110:113], v[94:97], v[182:185], v[110:113]
	v_mfma_f32_16x16x32_bf16 v[106:109], v[102:105], v[182:185], v[106:109]
	v_mfma_f32_16x16x32_bf16 v[78:81], v[94:97], v[240:243], v[78:81]
	v_mfma_f32_16x16x32_bf16 v[74:77], v[102:105], v[240:243], v[74:77]
	s_setprio 0
	s_setprio 1
	v_mfma_f32_16x16x32_bf16 v[134:137], v[146:149], v[162:165], v[134:137]
	v_mfma_f32_16x16x32_bf16 v[130:133], v[154:157], v[162:165], v[130:133]
	v_mfma_f32_16x16x32_bf16 v[118:121], v[146:149], v[170:173], v[118:121]
	v_mfma_f32_16x16x32_bf16 v[114:117], v[154:157], v[170:173], v[114:117]
	v_mfma_f32_16x16x32_bf16 v[86:89], v[146:149], v[178:181], v[86:89]
	v_mfma_f32_16x16x32_bf16 v[82:85], v[154:157], v[178:181], v[82:85]
	v_mfma_f32_16x16x32_bf16 v[70:73], v[146:149], v[218:221], v[70:73]
	v_mfma_f32_16x16x32_bf16 v[66:69], v[154:157], v[218:221], v[66:69]
	v_mfma_f32_16x16x32_bf16 v[134:137], v[150:153], v[166:169], v[134:137]
	v_mfma_f32_16x16x32_bf16 v[130:133], v[158:161], v[166:169], v[130:133]
	v_mfma_f32_16x16x32_bf16 v[118:121], v[150:153], v[174:177], v[118:121]
	v_mfma_f32_16x16x32_bf16 v[114:117], v[158:161], v[174:177], v[114:117]
	v_mfma_f32_16x16x32_bf16 v[86:89], v[150:153], v[182:185], v[86:89]
	v_mfma_f32_16x16x32_bf16 v[82:85], v[158:161], v[182:185], v[82:85]
	v_mfma_f32_16x16x32_bf16 v[70:73], v[150:153], v[240:243], v[70:73]
	v_mfma_f32_16x16x32_bf16 v[66:69], v[158:161], v[240:243], v[66:69]
	s_setprio 0
	s_barrier
; #define PG8_STAGE(bufoff, gbase, voff) do { _Pragma("unroll") for (int _i = 0; _i < 2; ++_i) \
;         __builtin_amdgcn_global_load_lds((const unsigned*)((const char*)(gbase) + (voff)[_i]), (PG8_LAS unsigned*)(lds + (bufoff) + ldsw + _i * 8192), 16, 0, 0); } while (0)
; #define PG8_LDA(dst, b, h) do { _Pragma("unroll") for (int m = 0; m < 4; ++m) _Pragma("unroll") for (int k = 0; k < 2; ++k) dst[m][k] = *(const PG8_LAS bf16x8*)(lds + PG8_SA(b, h) + aoff + m * 2048 + k * 1024); } while (0)
; #define PG8_MMA(ai, bj, At, Bt) do { __builtin_amdgcn_s_setprio(1); _Pragma("unroll") for (int m = 0; m < 4; ++m) _Pragma("unroll") for (int n = 0; n < 2; ++n) _Pragma("unroll") for (int k = 0; k < 2; ++k) \
;         acc[ai][bj][m][n] = __builtin_amdgcn_mfma_f32_16x16x32_bf16(Bt[n][k], At[m][k], acc[ai][bj][m][n], 0, 0, 0); __builtin_amdgcn_s_setprio(0); } while (0)
; #define PG8_WAIT_V(n) asm volatile("s_waitcnt vmcnt(" #n ")" ::: "memory")
; #define PG8_WAIT_L(n) asm volatile("s_waitcnt lgkmcnt(" #n ")" ::: "memory")
; #define PG8_BAR __builtin_amdgcn_s_barrier()
; #define PG8_SCHED __builtin_amdgcn_sched_barrier(0)
; template <class Epi, class Sched, bool ALIGN_EPI = false, bool SP2 = false>
; __device__ __forceinline__ void gemm_phase(PG8_LAS unsigned char* lds, const Gemm g, const Sched& S, const Epi& E) {
;     ...
;         for (int t = 0; t < nt; t += 2) {
;             const bool last = (t == nt - 2);
;     ...
;             PG8_LDA(At, 1, 1); PG8_STAGE(PG8_SB(1, 0), b3, voffB); PG8_STAGE(PG8_SB(1, 1), b3 + hstepB, voffB); PG8_STAGE(PG8_SA(1, 0), a3, voffA);
;             PG8_WAIT_V(8); PG8_WAIT_L(0); PG8_BAR; PG8_MMA(1, 0, At, B0); PG8_MMA(1, 1, At, B1); PG8_BAR; PG8_SCHED;
	s_add_i32 s20, s20, s61
	v_lshl_add_u64 v[204:205], v[204:205], 0, s[22:23]
	s_mov_b32 m0, s20
	ds_read_b128 v[162:165], v227 offset:49152
	ds_read_b128 v[166:169], v227 offset:50176
	ds_read_b128 v[170:173], v227 offset:51200
	ds_read_b128 v[174:177], v227 offset:52224
	ds_read_b128 v[178:181], v227 offset:53248
	ds_read_b128 v[182:185], v227 offset:54272
	ds_read_b128 v[218:221], v227 offset:55296
	ds_read_b128 v[240:243], v227 offset:56320
	global_load_lds_dwordx4 v[204:205], off
	s_add_i32 m0, s20, 0x2000
	s_add_u32 s14, s14, 0x40080
	v_lshl_add_u64 v[204:205], v[234:235], 0, s[22:23]
	s_addc_u32 s15, s15, 0
	s_add_i32 s20, s21, s61
	global_load_lds_dwordx4 v[204:205], off
	v_lshl_add_u64 v[204:205], s[14:15], 0, v[0:1]
	s_mov_b32 m0, s20
	s_nop 0
	global_load_lds_dwordx4 v[204:205], off
	v_lshl_add_u64 v[204:205], s[14:15], 0, v[186:187]
	s_add_i32 m0, s20, 0x2000
	s_nop 0
	global_load_lds_dwordx4 v[204:205], off
	v_lshl_add_u64 v[204:205], v[244:245], 0, s[22:23]
	s_mov_b32 m0, s82
	s_nop 0
	global_load_lds_dwordx4 v[204:205], off
	v_lshl_add_u64 v[204:205], v[246:247], 0, s[22:23]
	s_mov_b32 m0, s83
	s_nop 0
	global_load_lds_dwordx4 v[204:205], off
	s_waitcnt vmcnt(8)
	s_waitcnt lgkmcnt(0)
	s_barrier
	s_setprio 1
	s_waitcnt lgkmcnt(0)
	v_mfma_f32_16x16x32_bf16 v[62:65], v[90:93], v[162:165], v[62:65]
	v_mfma_f32_16x16x32_bf16 v[58:61], v[98:101], v[162:165], v[58:61]
	v_mfma_f32_16x16x32_bf16 v[46:49], v[90:93], v[170:173], v[46:49]
	v_mfma_f32_16x16x32_bf16 v[42:45], v[98:101], v[170:173], v[42:45]
	v_mfma_f32_16x16x32_bf16 v[30:33], v[90:93], v[178:181], v[30:33]
	v_mfma_f32_16x16x32_bf16 v[26:29], v[98:101], v[178:181], v[26:29]
	v_mfma_f32_16x16x32_bf16 v[14:17], v[90:93], v[218:221], v[14:17]
	v_mfma_f32_16x16x32_bf16 v[10:13], v[98:101], v[218:221], v[10:13]
	v_mfma_f32_16x16x32_bf16 v[62:65], v[94:97], v[166:169], v[62:65]
	v_mfma_f32_16x16x32_bf16 v[58:61], v[102:105], v[166:169], v[58:61]
	v_mfma_f32_16x16x32_bf16 v[46:49], v[94:97], v[174:177], v[46:49]
	v_mfma_f32_16x16x32_bf16 v[42:45], v[102:105], v[174:177], v[42:45]
	v_mfma_f32_16x16x32_bf16 v[30:33], v[94:97], v[182:185], v[30:33]
	v_mfma_f32_16x16x32_bf16 v[26:29], v[102:105], v[182:185], v[26:29]
	v_mfma_f32_16x16x32_bf16 v[14:17], v[94:97], v[240:243], v[14:17]
	v_mfma_f32_16x16x32_bf16 v[10:13], v[102:105], v[240:243], v[10:13]
	s_setprio 0
	s_setprio 1
	v_mfma_f32_16x16x32_bf16 v[54:57], v[146:149], v[162:165], v[54:57]
	v_mfma_f32_16x16x32_bf16 v[50:53], v[154:157], v[162:165], v[50:53]
	v_mfma_f32_16x16x32_bf16 v[38:41], v[146:149], v[170:173], v[38:41]
	v_mfma_f32_16x16x32_bf16 v[34:37], v[154:157], v[170:173], v[34:37]
	v_mfma_f32_16x16x32_bf16 v[22:25], v[146:149], v[178:181], v[22:25]
	v_mfma_f32_16x16x32_bf16 v[18:21], v[154:157], v[178:181], v[18:21]
	v_mfma_f32_16x16x32_bf16 v[6:9], v[146:149], v[218:221], v[6:9]
	v_mfma_f32_16x16x32_bf16 v[2:5], v[154:157], v[218:221], v[2:5]
	v_mfma_f32_16x16x32_bf16 v[54:57], v[150:153], v[166:169], v[54:57]
	v_mfma_f32_16x16x32_bf16 v[50:53], v[158:161], v[166:169], v[50:53]
	v_mfma_f32_16x16x32_bf16 v[38:41], v[150:153], v[174:177], v[38:41]
	v_mfma_f32_16x16x32_bf16 v[34:37], v[158:161], v[174:177], v[34:37]
	v_mfma_f32_16x16x32_bf16 v[22:25], v[150:153], v[182:185], v[22:25]
	v_mfma_f32_16x16x32_bf16 v[18:21], v[158:161], v[182:185], v[18:21]
	v_mfma_f32_16x16x32_bf16 v[6:9], v[150:153], v[240:243], v[6:9]
	v_mfma_f32_16x16x32_bf16 v[2:5], v[158:161], v[240:243], v[2:5]
	s_setprio 0
	s_barrier
	s_add_i32 s85, s85, 2
	s_add_u32 s0, s0, 0x100
	s_addc_u32 s1, s1, 0
	s_add_u32 s54, s54, 0x100
	s_addc_u32 s55, s55, 0
	s_cmp_gt_u32 s85, 13
	s_cbranch_scc1 .Lpk_done_g1137

; __device__ __forceinline__ void unpack8(const u32x4 w, float (&v)[8]) { v[0] = bf_lo(w.x); v[1] = bf_hi(w.x); v[2] = bf_lo(w.y); v[3] = bf_hi(w.y); v[4] = bf_lo(w.z); v[5] = bf_hi(w.z); v[6] = bf_lo(w.w); v[7] = bf_hi(w.w); }
;     __device__ __forceinline__ void operator()(const f32x4 (&acc)[2][2][4][2], const Unit& u, int wr, int wc, int fr, int fq) const {
;     ...
;         if (tid < 256) { float ss = 0.f;
; #pragma unroll
;             for (int t = 0; t < 4; ++t) ss += __uint_as_float(__hip_atomic_load((unsigned*)(XS + (grow0 + tid) * 4 + t), __ATOMIC_RELAXED, __HIP_MEMORY_SCOPE_AGENT));
;             S[tid] = alpha * rsqrtf(ss * (1.0f / DM) + RMS_EPS); }
;         asm volatile("s_waitcnt vmcnt(0) lgkmcnt(0)" ::: "memory"); __builtin_amdgcn_s_barrier(); asm volatile("" ::: "memory");
; #pragma unroll
;         for (int ai = 0; ai < 2; ++ai)
; #pragma unroll
;             for (int m = 0; m < 4; ++m) { const int rloc = rloc0 + ai * 128 + m * 16; const float rs = S[rloc]; float q2 = 0.f;
;                 u32x4 cur[2]; cur[0] = pre[m][0]; cur[1] = pre[m][1];
;                 if (ai == 0) {
; #pragma unroll
;                     for (int bj = 0; bj < 2; ++bj) pre[m][bj] = *(const u32x4*)(HB + (grow0 + rloc + 128) * DM + colb + bj * 128); }
; #pragma unroll
;                 for (int bj = 0; bj < 2; ++bj) { float h[8]; unpack8(cur[bj], h);
; #pragma unroll
;                     for (int e = 0; e < 4; ++e) { h[e] += acc[ai][bj][m][0][e] * g[bj][0][e] * rs; h[4 + e] += acc[ai][bj][m][1][e] * g[bj][1][e] * rs; }
.LBB0_1169:
	s_or_b64 exec, exec, s[14:15]
	s_waitcnt vmcnt(0) lgkmcnt(0)
	s_barrier
	s_and_saveexec_b64 s[8:9], s[40:41]
	s_cbranch_execz .LBB0_1171
	v_mov_b32_e32 v221, s1
	s_waitcnt lgkmcnt(0)
	v_lshl_add_u64 v[176:177], v[220:221], 4, s[28:29]
	global_load_dwordx4 v[182:185], v[176:177], off sc1
	s_mov_b32 s14, 0x800000
	s_waitcnt vmcnt(0)
	v_add_f32_e32 v182, 0, v182
	v_add_f32_e32 v182, v182, v183
	v_add_f32_e32 v182, v182, v184
	v_add_f32_e32 v176, v182, v185
	v_fmamk_f32 v176, v176, 0x3a800000, v203
	v_cmp_gt_f32_e32 vcc, s14, v176
	v_mul_f32_e32 v177, 0x4b800000, v176
	s_nop 0
	v_cndmask_b32_e32 v176, v176, v177, vcc
	v_rsq_f32_e32 v176, v176
	s_nop 0
	v_mul_f32_e32 v177, 0x45800000, v176
	v_cndmask_b32_e32 v176, v176, v177, vcc
	ds_write_b32 v252, v176
.LBB0_1171:
	s_or_b64 exec, exec, s[8:9]
	v_lshl_add_u64 v[174:175], s[58:59], 0, v[174:175]
	v_lshl_add_u64 v[204:205], v[218:219], 1, v[174:175]
	s_mov_b32 s8, 0x40000
	v_add_co_u32_e32 v176, vcc, s8, v204
	s_waitcnt vmcnt(0) lgkmcnt(0)
	s_barrier
	v_lshl_add_u64 v[174:175], v[204:205], 0, s[24:25]
	s_waitcnt lgkmcnt(0)
	v_addc_co_u32_e32 v177, vcc, 0, v205, vcc
	ds_read_b32 v221, v225
	global_load_dwordx4 v[182:185], v[176:177], off
	s_nop 0
	global_load_dwordx4 v[174:177], v[174:175], off offset:256
	s_waitcnt vmcnt(2)
	v_lshlrev_b32_e32 v241, 16, v180
	v_mul_f32_e32 v138, v138, v98
	v_lshlrev_b32_e32 v234, 16, v178
	v_and_b32_e32 v178, 0xffff0000, v178
	s_waitcnt lgkmcnt(0)
	v_fmac_f32_e32 v241, v138, v221
	v_mul_f32_e32 v138, v143, v103
	v_and_b32_e32 v180, 0xffff0000, v180
	v_fmac_f32_e32 v178, v138, v221
	v_mul_f32_e32 v138, v139, v99
	v_lshlrev_b32_e32 v235, 16, v179
	v_fmac_f32_e32 v180, v138, v221
	v_mul_f32_e32 v138, v144, v104
	v_lshlrev_b32_e32 v242, 16, v181
	v_fmac_f32_e32 v235, v138, v221
	v_mul_f32_e32 v138, v140, v100
	v_and_b32_e32 v179, 0xffff0000, v179
	v_fmac_f32_e32 v242, v138, v221
	v_mul_f32_e32 v138, v145, v105
	v_and_b32_e32 v181, 0xffff0000, v181
	v_mul_f32_e32 v142, v142, v102
	v_fmac_f32_e32 v179, v138, v221
	v_mul_f32_e32 v138, v141, v101
	v_fmac_f32_e32 v234, v142, v221
	v_fmac_f32_e32 v181, v138, v221
	v_cvt_pk_bf16_f32 v138, v234, v178
	v_cvt_pk_bf16_f32 v139, v235, v179
	v_cvt_pk_bf16_f32 v140, v241, v180
	v_cvt_pk_bf16_f32 v141, v242, v181
	global_store_dwordx4 v[204:205], v[138:141], off
	v_lshlrev_b32_e32 v142, 16, v138
	v_lshlrev_b32_e32 v143, 16, v139
	v_and_b32_e32 v138, 0xffff0000, v138
	v_mul_f32_e32 v138, v138, v138
	v_fmac_f32_e32 v138, v142, v142
	v_and_b32_e32 v139, 0xffff0000, v139
	v_fmac_f32_e32 v138, v143, v143
	v_lshlrev_b32_e32 v144, 16, v140
	v_fmac_f32_e32 v138, v139, v139
	v_and_b32_e32 v140, 0xffff0000, v140
	v_fmac_f32_e32 v138, v144, v144
	v_lshlrev_b32_e32 v143, 16, v172
	v_mul_f32_e32 v130, v130, v90
	v_lshlrev_b32_e32 v145, 16, v141
	v_fmac_f32_e32 v138, v140, v140
	v_and_b32_e32 v140, 0xffff0000, v170
	v_fmac_f32_e32 v143, v130, v221
	v_mul_f32_e32 v130, v135, v95
	v_and_b32_e32 v141, 0xffff0000, v141
	v_fmac_f32_e32 v138, v145, v145
	v_and_b32_e32 v144, 0xffff0000, v172
	v_fmac_f32_e32 v140, v130, v221
	v_mul_f32_e32 v130, v131, v91
	v_fmac_f32_e32 v138, v141, v141
	v_lshlrev_b32_e32 v141, 16, v171
	v_fmac_f32_e32 v144, v130, v221
	v_mul_f32_e32 v130, v136, v96
	v_lshlrev_b32_e32 v145, 16, v173
	v_fmac_f32_e32 v141, v130, v221
	v_mul_f32_e32 v130, v132, v92
	v_and_b32_e32 v142, 0xffff0000, v171
	v_fmac_f32_e32 v145, v130, v221
	v_mul_f32_e32 v130, v137, v97
	v_lshlrev_b32_e32 v139, 16, v170
	v_and_b32_e32 v170, 0xffff0000, v173
	v_mul_f32_e32 v134, v134, v94
	v_fmac_f32_e32 v142, v130, v221
	v_mul_f32_e32 v130, v133, v93
	v_fmac_f32_e32 v139, v134, v221
	v_fmac_f32_e32 v170, v130, v221
	v_cvt_pk_bf16_f32 v132, v139, v140
	v_cvt_pk_bf16_f32 v133, v141, v142
	v_cvt_pk_bf16_f32 v134, v143, v144
	v_cvt_pk_bf16_f32 v135, v145, v170
	global_store_dwordx4 v[204:205], v[132:135], off offset:256
	v_lshlrev_b32_e32 v130, 16, v132
	v_and_b32_e32 v131, 0xffff0000, v132
	v_fmac_f32_e32 v138, v130, v130
	v_lshlrev_b32_e32 v136, 16, v133
	v_fmac_f32_e32 v138, v131, v131
	v_and_b32_e32 v137, 0xffff0000, v133
	v_fmac_f32_e32 v138, v136, v136
	v_lshlrev_b32_e32 v139, 16, v134
	v_fmac_f32_e32 v138, v137, v137
	v_and_b32_e32 v140, 0xffff0000, v134
	v_fmac_f32_e32 v138, v139, v139
	v_lshlrev_b32_e32 v141, 16, v135
	v_fmac_f32_e32 v138, v140, v140
	v_and_b32_e32 v142, 0xffff0000, v135
	v_fmac_f32_e32 v138, v141, v141
	v_fmac_f32_e32 v138, v142, v142
	ds_bpermute_b32 v130, v239, v138
	s_waitcnt lgkmcnt(0)
	v_add_f32_e32 v130, v138, v130
	ds_bpermute_b32 v131, v240, v130
	s_and_saveexec_b64 s[8:9], s[42:43]
	s_cbranch_execz .LBB0_1173
	s_waitcnt lgkmcnt(0)
	v_add_f32_e32 v130, v130, v131
	ds_write_b32 v224, v130

; __device__ __forceinline__ unsigned cvt_pk_bf16(float lo, float hi) { unsigned r; asm volatile("v_cvt_pk_bf16_f32 %0, %1, %2" : "=v"(r) : "v"(lo), "v"(hi)); return r; }
; __device__ __forceinline__ void unpack8(const u32x4 w, float (&v)[8]) { v[0] = bf_lo(w.x); v[1] = bf_hi(w.x); v[2] = bf_lo(w.y); v[3] = bf_hi(w.y); v[4] = bf_lo(w.z); v[5] = bf_hi(w.z); v[6] = bf_lo(w.w); v[7] = bf_hi(w.w); }
;     __device__ __forceinline__ void operator()(const f32x4 (&acc)[2][2][4][2], const Unit& u, int wr, int wc, int fr, int fq) const {
;     ...
;         for (int ai = 0; ai < 2; ++ai)
; #pragma unroll
;             for (int m = 0; m < 4; ++m) { const int rloc = rloc0 + ai * 128 + m * 16; const float rs = S[rloc]; float q2 = 0.f;
;                 u32x4 cur[2]; cur[0] = pre[m][0]; cur[1] = pre[m][1];
;                 if (ai == 0) {
; #pragma unroll
;                     for (int bj = 0; bj < 2; ++bj) pre[m][bj] = *(const u32x4*)(HB + (grow0 + rloc + 128) * DM + colb + bj * 128); }
; #pragma unroll
;                 for (int bj = 0; bj < 2; ++bj) { float h[8]; unpack8(cur[bj], h);
; #pragma unroll
;                     for (int e = 0; e < 4; ++e) { h[e] += acc[ai][bj][m][0][e] * g[bj][0][e] * rs; h[4 + e] += acc[ai][bj][m][1][e] * g[bj][1][e] * rs; }
;                     if (OUT) { float* op = OUT + (grow0 + rloc) * DM + colb + bj * 128; *(f32x4*)op = (f32x4){h[0], h[1], h[2], h[3]}; *(f32x4*)(op + 4) = (f32x4){h[4], h[5], h[6], h[7]}; }
;                     else { u32x4 w; w.x = cvt_pk_bf16(h[0], h[1]); w.y = cvt_pk_bf16(h[2], h[3]); w.z = cvt_pk_bf16(h[4], h[5]); w.w = cvt_pk_bf16(h[6], h[7]);
;                         *(u32x4*)(HB + (grow0 + rloc) * DM + colb + bj * 128) = w; float qv[8]; unpack8(w, qv);
; #pragma unroll
;                         for (int e = 0; e < 8; ++e) q2 += qv[e] * qv[e]; } }
;                 q2 += __shfl_xor(q2, 16); q2 += __shfl_xor(q2, 32);
;                 if (fq == 0) P[rloc * 4 + wc] = q2; }
.LBB0_1179:
	s_or_b64 exec, exec, s[8:9]
	v_lshl_add_u32 v66, v200, 2, s64
	ds_read_b32 v68, v66
	s_waitcnt vmcnt(8)
	v_lshlrev_b32_e32 v73, 16, v184
	v_mul_f32_e32 v58, v58, v98
	v_and_b32_e32 v70, 0xffff0000, v182
	v_and_b32_e32 v74, 0xffff0000, v184
	s_waitcnt lgkmcnt(0)
	v_fmac_f32_e32 v73, v58, v68
	v_mul_f32_e32 v58, v63, v103
	v_fmac_f32_e32 v70, v58, v68
	v_mul_f32_e32 v58, v59, v99
	v_lshlrev_b32_e32 v71, 16, v183
	v_fmac_f32_e32 v74, v58, v68
	v_mul_f32_e32 v58, v64, v104
	v_lshl_add_u64 v[66:67], s[0:1], 0, v[200:201]
	v_lshlrev_b32_e32 v75, 16, v185
	v_fmac_f32_e32 v71, v58, v68
	v_mul_f32_e32 v58, v60, v100
	v_lshlrev_b64 v[66:67], 11, v[66:67]
	v_lshlrev_b32_e32 v69, 16, v182
	v_and_b32_e32 v72, 0xffff0000, v183
	v_mul_f32_e32 v62, v62, v102
	v_fmac_f32_e32 v75, v58, v68
	v_mul_f32_e32 v58, v65, v105
	v_and_b32_e32 v76, 0xffff0000, v185
	v_fmac_f32_e32 v69, v62, v68
	v_fmac_f32_e32 v72, v58, v68
	v_mul_f32_e32 v58, v61, v101
	v_lshl_add_u64 v[62:63], s[58:59], 0, v[66:67]
	v_fmac_f32_e32 v76, v58, v68
	v_cvt_pk_bf16_f32 v58, v69, v70
	v_lshl_add_u64 v[62:63], v[218:219], 1, v[62:63]
	v_cvt_pk_bf16_f32 v59, v71, v72
	v_cvt_pk_bf16_f32 v60, v73, v74
	v_cvt_pk_bf16_f32 v61, v75, v76
	global_store_dwordx4 v[62:63], v[58:61], off
	v_lshlrev_b32_e32 v64, 16, v58
	v_lshlrev_b32_e32 v65, 16, v59
	v_and_b32_e32 v58, 0xffff0000, v58
	v_mul_f32_e32 v58, v58, v58
	v_fmac_f32_e32 v58, v64, v64
	v_and_b32_e32 v59, 0xffff0000, v59
	v_fmac_f32_e32 v58, v65, v65
	v_lshlrev_b32_e32 v66, 16, v60
	v_fmac_f32_e32 v58, v59, v59
	v_and_b32_e32 v60, 0xffff0000, v60
	v_fmac_f32_e32 v58, v66, v66
	v_lshlrev_b32_e32 v65, 16, v176
	v_mul_f32_e32 v50, v50, v90
	v_lshlrev_b32_e32 v67, 16, v61
	v_fmac_f32_e32 v58, v60, v60
	v_and_b32_e32 v60, 0xffff0000, v174
	v_fmac_f32_e32 v65, v50, v68
	v_mul_f32_e32 v50, v55, v95
	v_and_b32_e32 v61, 0xffff0000, v61
	v_fmac_f32_e32 v58, v67, v67
	v_and_b32_e32 v66, 0xffff0000, v176
	v_fmac_f32_e32 v60, v50, v68
	v_mul_f32_e32 v50, v51, v91
	v_fmac_f32_e32 v58, v61, v61
	v_lshlrev_b32_e32 v61, 16, v175
	v_fmac_f32_e32 v66, v50, v68
	v_mul_f32_e32 v50, v56, v96
	v_lshlrev_b32_e32 v67, 16, v177
	v_fmac_f32_e32 v61, v50, v68
	v_mul_f32_e32 v50, v52, v92
	v_and_b32_e32 v64, 0xffff0000, v175
	v_fmac_f32_e32 v67, v50, v68
	v_mul_f32_e32 v50, v57, v97
	v_lshlrev_b32_e32 v59, 16, v174
	v_and_b32_e32 v69, 0xffff0000, v177
	v_mul_f32_e32 v54, v54, v94
	v_fmac_f32_e32 v64, v50, v68
	v_mul_f32_e32 v50, v53, v93
	v_fmac_f32_e32 v59, v54, v68
	v_fmac_f32_e32 v69, v50, v68
	v_cvt_pk_bf16_f32 v52, v59, v60
	v_cvt_pk_bf16_f32 v53, v61, v64
	v_cvt_pk_bf16_f32 v54, v65, v66
	v_cvt_pk_bf16_f32 v55, v67, v69
	global_store_dwordx4 v[62:63], v[52:55], off offset:256
	v_lshlrev_b32_e32 v50, 16, v52
	v_and_b32_e32 v51, 0xffff0000, v52
	v_fmac_f32_e32 v58, v50, v50
	v_lshlrev_b32_e32 v56, 16, v53
	v_fmac_f32_e32 v58, v51, v51
	v_and_b32_e32 v57, 0xffff0000, v53
	v_fmac_f32_e32 v58, v56, v56
	v_lshlrev_b32_e32 v59, 16, v54
	v_fmac_f32_e32 v58, v57, v57
	v_and_b32_e32 v60, 0xffff0000, v54
	v_fmac_f32_e32 v58, v59, v59
	v_lshlrev_b32_e32 v61, 16, v55
	v_fmac_f32_e32 v58, v60, v60
	v_and_b32_e32 v64, 0xffff0000, v55
	v_fmac_f32_e32 v58, v61, v61
	v_fmac_f32_e32 v58, v64, v64
	ds_bpermute_b32 v50, v239, v58
	s_waitcnt lgkmcnt(0)
	v_add_f32_e32 v50, v58, v50
	ds_bpermute_b32 v51, v240, v50
	s_and_saveexec_b64 s[8:9], s[42:43]
	s_cbranch_execz .LBB0_1181
	s_waitcnt lgkmcnt(0)
	v_add_f32_e32 v50, v50, v51
	ds_write_b32 v231, v50

; #define PG8_STAGE(bufoff, gbase, voff) do { _Pragma("unroll") for (int _i = 0; _i < 2; ++_i) \
;         __builtin_amdgcn_global_load_lds((const unsigned*)((const char*)(gbase) + (voff)[_i]), (PG8_LAS unsigned*)(lds + (bufoff) + ldsw + _i * 8192), 16, 0, 0); } while (0)
; #define PG8_LDA(dst, b, h) do { _Pragma("unroll") for (int m = 0; m < 4; ++m) _Pragma("unroll") for (int k = 0; k < 2; ++k) dst[m][k] = *(const PG8_LAS bf16x8*)(lds + PG8_SA(b, h) + aoff + m * 2048 + k * 1024); } while (0)
; #define PG8_LDB(dst, b, h) do { _Pragma("unroll") for (int n = 0; n < 2; ++n) _Pragma("unroll") for (int k = 0; k < 2; ++k) dst[n][k] = *(const PG8_LAS bf16x8*)(lds + PG8_SB(b, h) + boff + n * 2048 + k * 1024); } while (0)
; #define PG8_BAR __builtin_amdgcn_s_barrier()
; template <class Epi, class Sched, bool ALIGN_EPI = false, bool SP2 = false>
; __device__ __forceinline__ void gemm_phase(PG8_LAS unsigned char* lds, const Gemm g, const Sched& S, const Epi& E) {
;     ...
;         const char* nA = has_next ? (const char*)g.A + (size_t)nxt.pm * tstepA + (size_t)nxt.pb * g.sA : cA; const char* nB = has_next ? (const char*)g.Bt + (size_t)nxt.pn * tstepB + (size_t)nxt.pb * g.sB : cB;
;         for (int t = 0; t < nt; t += 2) {
;             const bool last = (t == nt - 2);
;             const char* a1 = cA + (size_t)(t + 1) * kstep;
;             const char* a2 = last ? nA : cA + (size_t)(t + 2) * kstep; const char* b2 = last ? nB : cB + (size_t)(t + 2) * kstep;
;             const char* a3 = a2 + kstep; const char* b3 = b2 + kstep;
;             if (last && has_next) S.a_ready(nxt);
;             if constexpr (SP2) {
;             PG8_LDB(B0, 0, 0); PG8_LDB(B1, 0, 1); PG8_SCHED; PG8_LDA(At, 0, 0); PG8_STAGE(PG8_SA(1, 1), a1 + hstepA, voffA);
;             PG8_WAIT_V(8); PG8_WAIT_L(0); PG8_BAR; PG8_MMA(0, 0, At, B0); PG8_MMA(0, 1, At, B1); PG8_BAR; PG8_SCHED;
;             PG8_LDA(At, 0, 1); PG8_STAGE(PG8_SB(0, 0), b2, voffB); PG8_STAGE(PG8_SB(0, 1), b2 + hstepB, voffB); PG8_STAGE(PG8_SA(0, 0), a2, voffA);
;             PG8_WAIT_V(8); PG8_WAIT_L(0); PG8_BAR; PG8_MMA(1, 0, At, B0); PG8_MMA(1, 1, At, B1); PG8_BAR; PG8_SCHED;
;             PG8_LDB(B0, 1, 0); PG8_LDB(B1, 1, 1); PG8_SCHED; PG8_LDA(At, 1, 0); PG8_STAGE(PG8_SA(0, 1), a2 + hstepA, voffA);
;             PG8_WAIT_V(8); PG8_WAIT_L(0); PG8_BAR; PG8_MMA(0, 0, At, B0); PG8_MMA(0, 1, At, B1); PG8_BAR; PG8_SCHED;
.LBB0_1211:
	s_ashr_i32 s29, s28, 31
	s_lshl_b64 s[20:21], s[28:29], 19
	s_add_u32 s30, s10, s20
	s_addc_u32 s31, s11, s21
	s_and_b64 s[20:21], s[42:43], exec
	s_cselect_b32 s29, s31, s9
	s_cselect_b32 s62, s30, s8
	s_ashr_i32 s19, s18, 31
	s_lshl_b64 s[20:21], s[18:19], 19
	s_add_u32 s34, s45, s20
	s_addc_u32 s35, s46, s21
	s_and_b64 s[20:21], s[42:43], exec
	s_cselect_b32 s19, s35, s37
	s_cselect_b32 s63, s34, s36
	s_add_u32 s8, s8, 0x40080
	s_addc_u32 s9, s9, 0
	s_add_u32 s70, s36, 0x100
	s_addc_u32 s71, s37, 0
	s_mov_b32 s76, -2
	s_add_u32 s20, s8, 0xfffc0080
	s_addc_u32 s21, s9, -1
	s_add_i32 s77, 0, 0x10000
	s_cmp_eq_u32 s76, 12
	s_cselect_b32 s39, s29, s21
	s_cselect_b32 s38, s62, s20
	v_add_u32_e32 v149, s77, v146
	s_cselect_b32 s37, s19, s71
	s_cselect_b32 s36, s63, s70
	s_add_i32 s78, 0, 0x14000
	ds_read_b128 v[140:143], v149
	ds_read_b128 v[150:153], v149 offset:1024
	ds_read_b128 v[154:157], v149 offset:2048
	ds_read_b128 v[158:161], v149 offset:3072
	v_add_u32_e32 v149, s78, v146
	ds_read_b128 v[162:165], v149
	ds_read_b128 v[166:169], v149 offset:1024
	ds_read_b128 v[170:173], v149 offset:2048
	ds_read_b128 v[174:177], v149 offset:3072
	v_lshl_add_u64 v[204:205], s[8:9], 0, v[136:137]
	s_add_i32 m0, s52, 0xc000
	ds_read_b128 v[178:181], v148
	ds_read_b128 v[182:185], v148 offset:1024
	ds_read_b128 v[186:189], v148 offset:2048
	ds_read_b128 v[190:193], v148 offset:3072
	ds_read_b128 v[194:197], v148 offset:4096
	ds_read_b128 v[198:201], v148 offset:5120
	ds_read_b128 v[208:211], v148 offset:6144
	ds_read_b128 v[212:215], v148 offset:7168
	global_load_lds_dwordx4 v[204:205], off
	v_lshl_add_u64 v[204:205], s[8:9], 0, v[138:139]
	s_add_i32 m0, s52, 0xe000
	s_nop 0
	global_load_lds_dwordx4 v[204:205], off
	s_waitcnt vmcnt(8)
	s_waitcnt lgkmcnt(0)
	s_barrier
	s_setprio 1
	s_waitcnt lgkmcnt(0)
	v_mfma_f32_16x16x32_bf16 v[126:129], v[140:143], v[178:181], 0
	v_mfma_f32_16x16x32_bf16 v[118:121], v[154:157], v[178:181], 0
	v_mfma_f32_16x16x32_bf16 v[110:113], v[140:143], v[186:189], 0
	v_mfma_f32_16x16x32_bf16 v[102:105], v[154:157], v[186:189], 0
	v_mfma_f32_16x16x32_bf16 v[94:97], v[140:143], v[194:197], 0
	v_mfma_f32_16x16x32_bf16 v[86:89], v[154:157], v[194:197], 0
	v_mfma_f32_16x16x32_bf16 v[78:81], v[140:143], v[208:211], 0
	v_mfma_f32_16x16x32_bf16 v[70:73], v[154:157], v[208:211], 0
	v_mfma_f32_16x16x32_bf16 v[126:129], v[150:153], v[182:185], v[126:129]
	v_mfma_f32_16x16x32_bf16 v[118:121], v[158:161], v[182:185], v[118:121]
	v_mfma_f32_16x16x32_bf16 v[110:113], v[150:153], v[190:193], v[110:113]
	v_mfma_f32_16x16x32_bf16 v[102:105], v[158:161], v[190:193], v[102:105]
	v_mfma_f32_16x16x32_bf16 v[94:97], v[150:153], v[198:201], v[94:97]
	v_mfma_f32_16x16x32_bf16 v[86:89], v[158:161], v[198:201], v[86:89]
	v_mfma_f32_16x16x32_bf16 v[78:81], v[150:153], v[212:215], v[78:81]
	v_mfma_f32_16x16x32_bf16 v[70:73], v[158:161], v[212:215], v[70:73]
	s_setprio 0
	s_setprio 1
	v_mfma_f32_16x16x32_bf16 v[122:125], v[162:165], v[178:181], 0
	v_mfma_f32_16x16x32_bf16 v[114:117], v[170:173], v[178:181], 0
	v_mfma_f32_16x16x32_bf16 v[106:109], v[162:165], v[186:189], 0
	v_mfma_f32_16x16x32_bf16 v[98:101], v[170:173], v[186:189], 0
	v_mfma_f32_16x16x32_bf16 v[90:93], v[162:165], v[194:197], 0
	v_mfma_f32_16x16x32_bf16 v[82:85], v[170:173], v[194:197], 0
	v_mfma_f32_16x16x32_bf16 v[74:77], v[162:165], v[208:211], 0
	v_mfma_f32_16x16x32_bf16 v[66:69], v[170:173], v[208:211], 0
	v_mfma_f32_16x16x32_bf16 v[122:125], v[166:169], v[182:185], v[122:125]
	v_mfma_f32_16x16x32_bf16 v[114:117], v[174:177], v[182:185], v[114:117]
	v_mfma_f32_16x16x32_bf16 v[106:109], v[166:169], v[190:193], v[106:109]
	v_mfma_f32_16x16x32_bf16 v[98:101], v[174:177], v[190:193], v[98:101]
	v_mfma_f32_16x16x32_bf16 v[90:93], v[166:169], v[198:201], v[90:93]
	v_mfma_f32_16x16x32_bf16 v[82:85], v[174:177], v[198:201], v[82:85]
	v_mfma_f32_16x16x32_bf16 v[74:77], v[166:169], v[212:215], v[74:77]
	v_mfma_f32_16x16x32_bf16 v[66:69], v[174:177], v[212:215], v[66:69]
	s_setprio 0
	s_barrier
	s_add_i32 s20, s77, s47
	v_lshl_add_u64 v[204:205], s[36:37], 0, v[0:1]
	s_mov_b32 m0, s20
	ds_read_b128 v[178:181], v148 offset:16384
	ds_read_b128 v[182:185], v148 offset:17408
	ds_read_b128 v[186:189], v148 offset:18432
	ds_read_b128 v[190:193], v148 offset:19456
	ds_read_b128 v[194:197], v148 offset:20480
	ds_read_b128 v[198:201], v148 offset:21504
	ds_read_b128 v[208:211], v148 offset:22528
	ds_read_b128 v[212:215], v148 offset:23552
	global_load_lds_dwordx4 v[204:205], off
	s_add_i32 m0, s20, 0x2000
	s_add_u32 s20, s36, 0x40000
	v_lshl_add_u64 v[216:217], s[36:37], 0, v[130:131]
	s_addc_u32 s21, s37, 0
	s_add_i32 s77, s78, s47
	global_load_lds_dwordx4 v[216:217], off
	v_lshl_add_u64 v[218:219], s[20:21], 0, v[0:1]
	s_mov_b32 m0, s77
	v_lshl_add_u64 v[220:221], s[38:39], 0, v[132:133]
	global_load_lds_dwordx4 v[218:219], off
	v_lshl_add_u64 v[218:219], s[20:21], 0, v[130:131]
	s_add_i32 m0, s77, 0x2000
	s_nop 0
	global_load_lds_dwordx4 v[218:219], off
	v_lshl_add_u64 v[218:219], s[38:39], 0, v[134:135]
	s_mov_b32 m0, s52
	s_nop 0
	global_load_lds_dwordx4 v[218:219], off
	s_mov_b32 m0, s53
	s_nop 0
	global_load_lds_dwordx4 v[220:221], off
	s_waitcnt vmcnt(8)
	s_waitcnt lgkmcnt(0)
	s_barrier
; #define PG8_STAGE(bufoff, gbase, voff) do { _Pragma("unroll") for (int _i = 0; _i < 2; ++_i) \
;         __builtin_amdgcn_global_load_lds((const unsigned*)((const char*)(gbase) + (voff)[_i]), (PG8_LAS unsigned*)(lds + (bufoff) + ldsw + _i * 8192), 16, 0, 0); } while (0)
; #define PG8_LDA(dst, b, h) do { _Pragma("unroll") for (int m = 0; m < 4; ++m) _Pragma("unroll") for (int k = 0; k < 2; ++k) dst[m][k] = *(const PG8_LAS bf16x8*)(lds + PG8_SA(b, h) + aoff + m * 2048 + k * 1024); } while (0)
; #define PG8_LDB(dst, b, h) do { _Pragma("unroll") for (int n = 0; n < 2; ++n) _Pragma("unroll") for (int k = 0; k < 2; ++k) dst[n][k] = *(const PG8_LAS bf16x8*)(lds + PG8_SB(b, h) + boff + n * 2048 + k * 1024); } while (0)
; #define PG8_MMA(ai, bj, At, Bt) do { __builtin_amdgcn_s_setprio(1); _Pragma("unroll") for (int m = 0; m < 4; ++m) _Pragma("unroll") for (int n = 0; n < 2; ++n) _Pragma("unroll") for (int k = 0; k < 2; ++k) \
;         acc[ai][bj][m][n] = __builtin_amdgcn_mfma_f32_16x16x32_bf16(Bt[n][k], At[m][k], acc[ai][bj][m][n], 0, 0, 0); __builtin_amdgcn_s_setprio(0); } while (0)
; #define PG8_WAIT_V(n) asm volatile("s_waitcnt vmcnt(" #n ")" ::: "memory")
; #define PG8_WAIT_L(n) asm volatile("s_waitcnt lgkmcnt(" #n ")" ::: "memory")
; #define PG8_BAR __builtin_amdgcn_s_barrier()
; #define PG8_SCHED __builtin_amdgcn_sched_barrier(0)
; template <class Epi, class Sched, bool ALIGN_EPI = false, bool SP2 = false>
; __device__ __forceinline__ void gemm_phase(PG8_LAS unsigned char* lds, const Gemm g, const Sched& S, const Epi& E) {
;     ...
;             PG8_WAIT_V(8); PG8_WAIT_L(0); PG8_BAR; PG8_MMA(1, 0, At, B0); PG8_MMA(1, 1, At, B1); PG8_BAR; PG8_SCHED;
;             PG8_LDB(B0, 1, 0); PG8_LDB(B1, 1, 1); PG8_SCHED; PG8_LDA(At, 1, 0); PG8_STAGE(PG8_SA(0, 1), a2 + hstepA, voffA);
;             PG8_WAIT_V(8); PG8_WAIT_L(0); PG8_BAR; PG8_MMA(0, 0, At, B0); PG8_MMA(0, 1, At, B1); PG8_BAR; PG8_SCHED;
	s_setprio 1
	s_waitcnt lgkmcnt(0)
	v_mfma_f32_16x16x32_bf16 v[62:65], v[140:143], v[178:181], 0
	v_mfma_f32_16x16x32_bf16 v[54:57], v[154:157], v[178:181], 0
	v_mfma_f32_16x16x32_bf16 v[46:49], v[140:143], v[186:189], 0
	v_mfma_f32_16x16x32_bf16 v[38:41], v[154:157], v[186:189], 0
	v_mfma_f32_16x16x32_bf16 v[30:33], v[140:143], v[194:197], 0
	v_mfma_f32_16x16x32_bf16 v[22:25], v[154:157], v[194:197], 0
	v_mfma_f32_16x16x32_bf16 v[14:17], v[140:143], v[208:211], 0
	v_mfma_f32_16x16x32_bf16 v[6:9], v[154:157], v[208:211], 0
	v_mfma_f32_16x16x32_bf16 v[62:65], v[150:153], v[182:185], v[62:65]
	v_mfma_f32_16x16x32_bf16 v[54:57], v[158:161], v[182:185], v[54:57]
	v_mfma_f32_16x16x32_bf16 v[46:49], v[150:153], v[190:193], v[46:49]
	v_mfma_f32_16x16x32_bf16 v[38:41], v[158:161], v[190:193], v[38:41]
	v_mfma_f32_16x16x32_bf16 v[30:33], v[150:153], v[198:201], v[30:33]
	v_mfma_f32_16x16x32_bf16 v[22:25], v[158:161], v[198:201], v[22:25]
	v_mfma_f32_16x16x32_bf16 v[14:17], v[150:153], v[212:215], v[14:17]
	v_mfma_f32_16x16x32_bf16 v[6:9], v[158:161], v[212:215], v[6:9]
	s_setprio 0
	s_setprio 1
	v_mfma_f32_16x16x32_bf16 v[58:61], v[162:165], v[178:181], 0
	v_mfma_f32_16x16x32_bf16 v[50:53], v[170:173], v[178:181], 0
	v_mfma_f32_16x16x32_bf16 v[42:45], v[162:165], v[186:189], 0
	v_mfma_f32_16x16x32_bf16 v[34:37], v[170:173], v[186:189], 0
	v_mfma_f32_16x16x32_bf16 v[26:29], v[162:165], v[194:197], 0
	v_mfma_f32_16x16x32_bf16 v[18:21], v[170:173], v[194:197], 0
	v_mfma_f32_16x16x32_bf16 v[10:13], v[162:165], v[208:211], 0
	v_mfma_f32_16x16x32_bf16 v[2:5], v[170:173], v[208:211], 0
	v_mfma_f32_16x16x32_bf16 v[58:61], v[166:169], v[182:185], v[58:61]
	v_mfma_f32_16x16x32_bf16 v[50:53], v[174:177], v[182:185], v[50:53]
	v_mfma_f32_16x16x32_bf16 v[42:45], v[166:169], v[190:193], v[42:45]
	v_mfma_f32_16x16x32_bf16 v[34:37], v[174:177], v[190:193], v[34:37]
	v_mfma_f32_16x16x32_bf16 v[26:29], v[166:169], v[198:201], v[26:29]
	v_mfma_f32_16x16x32_bf16 v[18:21], v[174:177], v[198:201], v[18:21]
	v_mfma_f32_16x16x32_bf16 v[10:13], v[166:169], v[212:215], v[10:13]
	v_mfma_f32_16x16x32_bf16 v[2:5], v[174:177], v[212:215], v[2:5]
	s_setprio 0
	s_barrier
	s_add_i32 s77, 0, 0x18000
	v_add_u32_e32 v149, s77, v146
	s_add_i32 s78, 0, 0x1c000
	ds_read_b128 v[140:143], v149
	ds_read_b128 v[150:153], v149 offset:1024
	ds_read_b128 v[154:157], v149 offset:2048
	ds_read_b128 v[158:161], v149 offset:3072
	v_add_u32_e32 v149, s78, v146
	ds_read_b128 v[162:165], v149
	ds_read_b128 v[166:169], v149 offset:1024
	ds_read_b128 v[170:173], v149 offset:2048
	ds_read_b128 v[174:177], v149 offset:3072
	s_add_u32 s20, s38, 0x40000
	s_addc_u32 s21, s39, 0
	s_mov_b32 m0, s54
	v_lshl_add_u64 v[222:223], s[20:21], 0, v[134:135]
	ds_read_b128 v[178:181], v148 offset:32768
	ds_read_b128 v[182:185], v148 offset:33792
	ds_read_b128 v[186:189], v148 offset:34816
	ds_read_b128 v[190:193], v148 offset:35840
	ds_read_b128 v[194:197], v148 offset:36864
	ds_read_b128 v[198:201], v148 offset:37888
	ds_read_b128 v[208:211], v148 offset:38912
	ds_read_b128 v[212:215], v148 offset:39936
	global_load_lds_dwordx4 v[222:223], off
	v_lshl_add_u64 v[222:223], s[20:21], 0, v[132:133]
	s_mov_b32 m0, s55
	s_nop 0
	global_load_lds_dwordx4 v[222:223], off
	s_waitcnt vmcnt(8)
	s_waitcnt lgkmcnt(0)
	s_barrier
	s_setprio 1
	s_waitcnt lgkmcnt(0)
	v_mfma_f32_16x16x32_bf16 v[126:129], v[140:143], v[178:181], v[126:129]
	v_mfma_f32_16x16x32_bf16 v[118:121], v[154:157], v[178:181], v[118:121]
	v_mfma_f32_16x16x32_bf16 v[110:113], v[140:143], v[186:189], v[110:113]
	v_mfma_f32_16x16x32_bf16 v[102:105], v[154:157], v[186:189], v[102:105]
	v_mfma_f32_16x16x32_bf16 v[94:97], v[140:143], v[194:197], v[94:97]
	v_mfma_f32_16x16x32_bf16 v[86:89], v[154:157], v[194:197], v[86:89]
	v_mfma_f32_16x16x32_bf16 v[78:81], v[140:143], v[208:211], v[78:81]
	v_mfma_f32_16x16x32_bf16 v[70:73], v[154:157], v[208:211], v[70:73]
	v_mfma_f32_16x16x32_bf16 v[126:129], v[150:153], v[182:185], v[126:129]
	v_mfma_f32_16x16x32_bf16 v[118:121], v[158:161], v[182:185], v[118:121]
	v_mfma_f32_16x16x32_bf16 v[110:113], v[150:153], v[190:193], v[110:113]
	v_mfma_f32_16x16x32_bf16 v[102:105], v[158:161], v[190:193], v[102:105]
	v_mfma_f32_16x16x32_bf16 v[94:97], v[150:153], v[198:201], v[94:97]
	v_mfma_f32_16x16x32_bf16 v[86:89], v[158:161], v[198:201], v[86:89]
	v_mfma_f32_16x16x32_bf16 v[78:81], v[150:153], v[212:215], v[78:81]
	v_mfma_f32_16x16x32_bf16 v[70:73], v[158:161], v[212:215], v[70:73]
	s_setprio 0
	s_setprio 1
	v_mfma_f32_16x16x32_bf16 v[122:125], v[162:165], v[178:181], v[122:125]
	v_mfma_f32_16x16x32_bf16 v[114:117], v[170:173], v[178:181], v[114:117]
	v_mfma_f32_16x16x32_bf16 v[106:109], v[162:165], v[186:189], v[106:109]
	v_mfma_f32_16x16x32_bf16 v[98:101], v[170:173], v[186:189], v[98:101]
	v_mfma_f32_16x16x32_bf16 v[90:93], v[162:165], v[194:197], v[90:93]
	v_mfma_f32_16x16x32_bf16 v[82:85], v[170:173], v[194:197], v[82:85]
	v_mfma_f32_16x16x32_bf16 v[74:77], v[162:165], v[208:211], v[74:77]
	v_mfma_f32_16x16x32_bf16 v[66:69], v[170:173], v[208:211], v[66:69]
	v_mfma_f32_16x16x32_bf16 v[122:125], v[166:169], v[182:185], v[122:125]
	v_mfma_f32_16x16x32_bf16 v[114:117], v[174:177], v[182:185], v[114:117]
	v_mfma_f32_16x16x32_bf16 v[106:109], v[166:169], v[190:193], v[106:109]
	v_mfma_f32_16x16x32_bf16 v[98:101], v[174:177], v[190:193], v[98:101]
	v_mfma_f32_16x16x32_bf16 v[90:93], v[166:169], v[198:201], v[90:93]
	v_mfma_f32_16x16x32_bf16 v[82:85], v[174:177], v[198:201], v[82:85]
	v_mfma_f32_16x16x32_bf16 v[74:77], v[166:169], v[212:215], v[74:77]
	v_mfma_f32_16x16x32_bf16 v[66:69], v[174:177], v[212:215], v[66:69]
	s_setprio 0
	s_barrier
; #define PG8_STAGE(bufoff, gbase, voff) do { _Pragma("unroll") for (int _i = 0; _i < 2; ++_i) \
;         __builtin_amdgcn_global_load_lds((const unsigned*)((const char*)(gbase) + (voff)[_i]), (PG8_LAS unsigned*)(lds + (bufoff) + ldsw + _i * 8192), 16, 0, 0); } while (0)
; #define PG8_LDA(dst, b, h) do { _Pragma("unroll") for (int m = 0; m < 4; ++m) _Pragma("unroll") for (int k = 0; k < 2; ++k) dst[m][k] = *(const PG8_LAS bf16x8*)(lds + PG8_SA(b, h) + aoff + m * 2048 + k * 1024); } while (0)
; #define PG8_MMA(ai, bj, At, Bt) do { __builtin_amdgcn_s_setprio(1); _Pragma("unroll") for (int m = 0; m < 4; ++m) _Pragma("unroll") for (int n = 0; n < 2; ++n) _Pragma("unroll") for (int k = 0; k < 2; ++k) \
;         acc[ai][bj][m][n] = __builtin_amdgcn_mfma_f32_16x16x32_bf16(Bt[n][k], At[m][k], acc[ai][bj][m][n], 0, 0, 0); __builtin_amdgcn_s_setprio(0); } while (0)
; #define PG8_WAIT_V(n) asm volatile("s_waitcnt vmcnt(" #n ")" ::: "memory")
; #define PG8_WAIT_L(n) asm volatile("s_waitcnt lgkmcnt(" #n ")" ::: "memory")
; #define PG8_BAR __builtin_amdgcn_s_barrier()
; #define PG8_SCHED __builtin_amdgcn_sched_barrier(0)
; template <class Epi, class Sched, bool ALIGN_EPI = false, bool SP2 = false>
; __device__ __forceinline__ void gemm_phase(PG8_LAS unsigned char* lds, const Gemm g, const Sched& S, const Epi& E) {
;     ...
;             PG8_LDA(At, 1, 1); PG8_STAGE(PG8_SB(1, 0), b3, voffB); PG8_STAGE(PG8_SB(1, 1), b3 + hstepB, voffB); PG8_STAGE(PG8_SA(1, 0), a3, voffA);
;             PG8_WAIT_V(8); PG8_WAIT_L(0); PG8_BAR; PG8_MMA(1, 0, At, B0); PG8_MMA(1, 1, At, B1); PG8_BAR; PG8_SCHED;
	s_add_i32 s20, s77, s47
	v_lshl_add_u64 v[204:205], v[204:205], 0, s[22:23]
	s_mov_b32 m0, s20
	ds_read_b128 v[178:181], v148 offset:49152
	ds_read_b128 v[182:185], v148 offset:50176
	ds_read_b128 v[186:189], v148 offset:51200
	ds_read_b128 v[190:193], v148 offset:52224
	ds_read_b128 v[194:197], v148 offset:53248
	ds_read_b128 v[198:201], v148 offset:54272
	ds_read_b128 v[208:211], v148 offset:55296
	ds_read_b128 v[212:215], v148 offset:56320
	global_load_lds_dwordx4 v[204:205], off
	s_add_i32 m0, s20, 0x2000
	s_add_u32 s20, s36, 0x40080
	v_lshl_add_u64 v[204:205], v[216:217], 0, s[22:23]
	s_addc_u32 s21, s37, 0
	s_add_i32 s36, s78, s47
	global_load_lds_dwordx4 v[204:205], off
	v_lshl_add_u64 v[204:205], s[20:21], 0, v[0:1]
	s_mov_b32 m0, s36
	s_nop 0
	global_load_lds_dwordx4 v[204:205], off
	v_lshl_add_u64 v[204:205], s[20:21], 0, v[130:131]
	s_add_i32 m0, s36, 0x2000
	s_nop 0
	global_load_lds_dwordx4 v[204:205], off
	v_lshl_add_u64 v[204:205], v[218:219], 0, s[22:23]
	s_mov_b32 m0, s56
	s_nop 0
	global_load_lds_dwordx4 v[204:205], off
	v_lshl_add_u64 v[204:205], v[220:221], 0, s[22:23]
	s_mov_b32 m0, s57
	s_nop 0
	global_load_lds_dwordx4 v[204:205], off
	s_waitcnt vmcnt(8)
	s_waitcnt lgkmcnt(0)
	s_barrier
	s_setprio 1
	s_waitcnt lgkmcnt(0)
	v_mfma_f32_16x16x32_bf16 v[62:65], v[140:143], v[178:181], v[62:65]
	v_mfma_f32_16x16x32_bf16 v[54:57], v[154:157], v[178:181], v[54:57]
	v_mfma_f32_16x16x32_bf16 v[46:49], v[140:143], v[186:189], v[46:49]
	v_mfma_f32_16x16x32_bf16 v[38:41], v[154:157], v[186:189], v[38:41]
	v_mfma_f32_16x16x32_bf16 v[30:33], v[140:143], v[194:197], v[30:33]
	v_mfma_f32_16x16x32_bf16 v[22:25], v[154:157], v[194:197], v[22:25]
	v_mfma_f32_16x16x32_bf16 v[14:17], v[140:143], v[208:211], v[14:17]
	v_mfma_f32_16x16x32_bf16 v[6:9], v[154:157], v[208:211], v[6:9]
	v_mfma_f32_16x16x32_bf16 v[62:65], v[150:153], v[182:185], v[62:65]
	v_mfma_f32_16x16x32_bf16 v[54:57], v[158:161], v[182:185], v[54:57]
	v_mfma_f32_16x16x32_bf16 v[46:49], v[150:153], v[190:193], v[46:49]
	v_mfma_f32_16x16x32_bf16 v[38:41], v[158:161], v[190:193], v[38:41]
	v_mfma_f32_16x16x32_bf16 v[30:33], v[150:153], v[198:201], v[30:33]
	v_mfma_f32_16x16x32_bf16 v[22:25], v[158:161], v[198:201], v[22:25]
	v_mfma_f32_16x16x32_bf16 v[14:17], v[150:153], v[212:215], v[14:17]
	v_mfma_f32_16x16x32_bf16 v[6:9], v[158:161], v[212:215], v[6:9]
	s_setprio 0
	s_setprio 1
	v_mfma_f32_16x16x32_bf16 v[58:61], v[162:165], v[178:181], v[58:61]
	v_mfma_f32_16x16x32_bf16 v[50:53], v[170:173], v[178:181], v[50:53]
	v_mfma_f32_16x16x32_bf16 v[42:45], v[162:165], v[186:189], v[42:45]
	v_mfma_f32_16x16x32_bf16 v[34:37], v[170:173], v[186:189], v[34:37]
	v_mfma_f32_16x16x32_bf16 v[26:29], v[162:165], v[194:197], v[26:29]
	v_mfma_f32_16x16x32_bf16 v[18:21], v[170:173], v[194:197], v[18:21]
	v_mfma_f32_16x16x32_bf16 v[10:13], v[162:165], v[208:211], v[10:13]
	v_mfma_f32_16x16x32_bf16 v[2:5], v[170:173], v[208:211], v[2:5]
	v_mfma_f32_16x16x32_bf16 v[58:61], v[166:169], v[182:185], v[58:61]
	v_mfma_f32_16x16x32_bf16 v[50:53], v[174:177], v[182:185], v[50:53]
	v_mfma_f32_16x16x32_bf16 v[42:45], v[166:169], v[190:193], v[42:45]
	v_mfma_f32_16x16x32_bf16 v[34:37], v[174:177], v[190:193], v[34:37]
	v_mfma_f32_16x16x32_bf16 v[26:29], v[166:169], v[198:201], v[26:29]
	v_mfma_f32_16x16x32_bf16 v[18:21], v[174:177], v[198:201], v[18:21]
	v_mfma_f32_16x16x32_bf16 v[10:13], v[166:169], v[212:215], v[10:13]
	v_mfma_f32_16x16x32_bf16 v[2:5], v[174:177], v[212:215], v[2:5]
	s_setprio 0
	s_barrier
	s_add_i32 s76, s76, 2
	s_add_u32 s8, s8, 0x100
	s_addc_u32 s9, s9, 0
	s_add_u32 s70, s70, 0x100
	s_addc_u32 s71, s71, 0
	s_cmp_gt_u32 s76, 13
	s_cbranch_scc1 .Lpk_done_up

; #define PG8_BAR __builtin_amdgcn_s_barrier()
; template <class Epi, class Sched, bool ALIGN_EPI = false, bool SP2 = false>
; __device__ __forceinline__ void gemm_phase(PG8_LAS unsigned char* lds, const Gemm g, const Sched& S, const Epi& E) {
;     ...
;         if constexpr (ALIGN_EPI) { if (wr == 0) PG8_BAR; }
.Lpk_done_up:
	s_and_b64 vcc, exec, s[16:17]
	s_cbranch_vccz .LBB0_1215
	s_barrier

; #define PG8_STAGE(bufoff, gbase, voff) do { _Pragma("unroll") for (int _i = 0; _i < 2; ++_i) \
;         __builtin_amdgcn_global_load_lds((const unsigned*)((const char*)(gbase) + (voff)[_i]), (PG8_LAS unsigned*)(lds + (bufoff) + ldsw + _i * 8192), 16, 0, 0); } while (0)
; #define PG8_LDA(dst, b, h) do { _Pragma("unroll") for (int m = 0; m < 4; ++m) _Pragma("unroll") for (int k = 0; k < 2; ++k) dst[m][k] = *(const PG8_LAS bf16x8*)(lds + PG8_SA(b, h) + aoff + m * 2048 + k * 1024); } while (0)
; #define PG8_LDB(dst, b, h) do { _Pragma("unroll") for (int n = 0; n < 2; ++n) _Pragma("unroll") for (int k = 0; k < 2; ++k) dst[n][k] = *(const PG8_LAS bf16x8*)(lds + PG8_SB(b, h) + boff + n * 2048 + k * 1024); } while (0)
; #define PG8_BAR __builtin_amdgcn_s_barrier()
; template <class Epi, class Sched, bool ALIGN_EPI = false, bool SP2 = false>
; __device__ __forceinline__ void gemm_phase(PG8_LAS unsigned char* lds, const Gemm g, const Sched& S, const Epi& E) {
;     ...
;         const char* nA = has_next ? (const char*)g.A + (size_t)nxt.pm * tstepA + (size_t)nxt.pb * g.sA : cA; const char* nB = has_next ? (const char*)g.Bt + (size_t)nxt.pn * tstepB + (size_t)nxt.pb * g.sB : cB;
;         for (int t = 0; t < nt; t += 2) {
;             const bool last = (t == nt - 2);
;             const char* a1 = cA + (size_t)(t + 1) * kstep;
;             const char* a2 = last ? nA : cA + (size_t)(t + 2) * kstep; const char* b2 = last ? nB : cB + (size_t)(t + 2) * kstep;
;             const char* a3 = a2 + kstep; const char* b3 = b2 + kstep;
;             if (last && has_next) S.a_ready(nxt);
;             if constexpr (SP2) {
;             PG8_LDB(B0, 0, 0); PG8_LDB(B1, 0, 1); PG8_SCHED; PG8_LDA(At, 0, 0); PG8_STAGE(PG8_SA(1, 1), a1 + hstepA, voffA);
;             PG8_WAIT_V(8); PG8_WAIT_L(0); PG8_BAR; PG8_MMA(0, 0, At, B0); PG8_MMA(0, 1, At, B1); PG8_BAR; PG8_SCHED;
;             PG8_LDA(At, 0, 1); PG8_STAGE(PG8_SB(0, 0), b2, voffB); PG8_STAGE(PG8_SB(0, 1), b2 + hstepB, voffB); PG8_STAGE(PG8_SA(0, 0), a2, voffA);
;             PG8_WAIT_V(8); PG8_WAIT_L(0); PG8_BAR; PG8_MMA(1, 0, At, B0); PG8_MMA(1, 1, At, B1); PG8_BAR; PG8_SCHED;
;             PG8_LDB(B0, 1, 0); PG8_LDB(B1, 1, 1); PG8_SCHED; PG8_LDA(At, 1, 0); PG8_STAGE(PG8_SA(0, 1), a2 + hstepA, voffA);
;             PG8_WAIT_V(8); PG8_WAIT_L(0); PG8_BAR; PG8_MMA(0, 0, At, B0); PG8_MMA(0, 1, At, B1); PG8_BAR; PG8_SCHED;
.LBB0_1314:
	s_add_u32 s9, s34, 0x100
	s_addc_u32 s17, s35, 0
	s_mov_b32 s87, -2
	s_waitcnt lgkmcnt(0)
	s_add_u32 s34, s0, 0x100
	s_addc_u32 s35, s1, 0
	s_add_i32 vcc_lo, 0, 0x10000
	s_cmp_eq_u32 s87, 40
	s_cselect_b32 s47, s39, s35
	s_cselect_b32 s46, s38, s34
	s_cselect_b32 s37, s53, s17
	s_cselect_b32 s36, s52, s9
	s_add_i32 vcc_hi, 0, 0x14000
	v_add_u32_e32 v78, vcc_lo, v228
	v_add_u32_e32 v158, vcc_hi, v228
	ds_read_b128 v[58:61], v78
	ds_read_b128 v[62:65], v78 offset:1024
	ds_read_b128 v[74:77], v78 offset:2048
	ds_read_b128 v[78:81], v78 offset:3072
	ds_read_b128 v[130:133], v158
	ds_read_b128 v[142:145], v158 offset:1024
	ds_read_b128 v[154:157], v158 offset:2048
	ds_read_b128 v[158:161], v158 offset:3072
	v_lshl_add_u64 v[204:205], s[0:1], 0, v[214:215]
	s_add_i32 m0, s71, 0xc000
	ds_read_b128 v[162:165], v233
	ds_read_b128 v[166:169], v233 offset:1024
	ds_read_b128 v[170:173], v233 offset:2048
	ds_read_b128 v[174:177], v233 offset:3072
	ds_read_b128 v[178:181], v233 offset:4096
	ds_read_b128 v[182:185], v233 offset:5120
	ds_read_b128 v[218:221], v233 offset:6144
	ds_read_b128 v[222:225], v233 offset:7168
	global_load_lds_dwordx4 v[204:205], off
	v_lshl_add_u64 v[204:205], s[0:1], 0, v[216:217]
	s_add_i32 m0, s71, 0xe000
	s_nop 0
	global_load_lds_dwordx4 v[204:205], off
	s_waitcnt vmcnt(8)
	s_waitcnt lgkmcnt(0)
	s_barrier
	s_setprio 1
	s_waitcnt lgkmcnt(0)
	v_mfma_f32_16x16x32_bf16 v[150:153], v[58:61], v[162:165], 0
	v_mfma_f32_16x16x32_bf16 v[146:149], v[74:77], v[162:165], 0
	v_mfma_f32_16x16x32_bf16 v[126:129], v[58:61], v[170:173], 0
	v_mfma_f32_16x16x32_bf16 v[122:125], v[74:77], v[170:173], 0
	v_mfma_f32_16x16x32_bf16 v[110:113], v[58:61], v[178:181], 0
	v_mfma_f32_16x16x32_bf16 v[106:109], v[74:77], v[178:181], 0
	v_mfma_f32_16x16x32_bf16 v[94:97], v[58:61], v[218:221], 0
	v_mfma_f32_16x16x32_bf16 v[90:93], v[74:77], v[218:221], 0
	v_mfma_f32_16x16x32_bf16 v[150:153], v[62:65], v[166:169], v[150:153]
	v_mfma_f32_16x16x32_bf16 v[146:149], v[78:81], v[166:169], v[146:149]
	v_mfma_f32_16x16x32_bf16 v[126:129], v[62:65], v[174:177], v[126:129]
	v_mfma_f32_16x16x32_bf16 v[122:125], v[78:81], v[174:177], v[122:125]
	v_mfma_f32_16x16x32_bf16 v[110:113], v[62:65], v[182:185], v[110:113]
	v_mfma_f32_16x16x32_bf16 v[106:109], v[78:81], v[182:185], v[106:109]
	v_mfma_f32_16x16x32_bf16 v[94:97], v[62:65], v[222:225], v[94:97]
	v_mfma_f32_16x16x32_bf16 v[90:93], v[78:81], v[222:225], v[90:93]
	s_setprio 0
	s_setprio 1
	v_mfma_f32_16x16x32_bf16 v[138:141], v[130:133], v[162:165], 0
	v_mfma_f32_16x16x32_bf16 v[134:137], v[154:157], v[162:165], 0
	v_mfma_f32_16x16x32_bf16 v[118:121], v[130:133], v[170:173], 0
	v_mfma_f32_16x16x32_bf16 v[114:117], v[154:157], v[170:173], 0
	v_mfma_f32_16x16x32_bf16 v[102:105], v[130:133], v[178:181], 0
	v_mfma_f32_16x16x32_bf16 v[98:101], v[154:157], v[178:181], 0
	v_mfma_f32_16x16x32_bf16 v[86:89], v[130:133], v[218:221], 0
	v_mfma_f32_16x16x32_bf16 v[82:85], v[154:157], v[218:221], 0
	v_mfma_f32_16x16x32_bf16 v[138:141], v[142:145], v[166:169], v[138:141]
	v_mfma_f32_16x16x32_bf16 v[134:137], v[158:161], v[166:169], v[134:137]
	v_mfma_f32_16x16x32_bf16 v[118:121], v[142:145], v[174:177], v[118:121]
	v_mfma_f32_16x16x32_bf16 v[114:117], v[158:161], v[174:177], v[114:117]
	v_mfma_f32_16x16x32_bf16 v[102:105], v[142:145], v[182:185], v[102:105]
	v_mfma_f32_16x16x32_bf16 v[98:101], v[158:161], v[182:185], v[98:101]
	v_mfma_f32_16x16x32_bf16 v[86:89], v[142:145], v[222:225], v[86:89]
	v_mfma_f32_16x16x32_bf16 v[82:85], v[158:161], v[222:225], v[82:85]
	s_setprio 0
	s_barrier
	s_add_i32 s0, vcc_lo, s54
	v_lshl_add_u64 v[204:205], s[36:37], 0, v[0:1]
	s_mov_b32 m0, s0
	ds_read_b128 v[162:165], v233 offset:16384
	ds_read_b128 v[166:169], v233 offset:17408
	ds_read_b128 v[170:173], v233 offset:18432
	ds_read_b128 v[174:177], v233 offset:19456
	ds_read_b128 v[178:181], v233 offset:20480
	ds_read_b128 v[182:185], v233 offset:21504
	ds_read_b128 v[218:221], v233 offset:22528
	ds_read_b128 v[222:225], v233 offset:23552
	global_load_lds_dwordx4 v[204:205], off
	s_add_i32 m0, s0, 0x2000
	s_add_u32 s0, s36, 0xb0000
	v_lshl_add_u64 v[226:227], s[36:37], 0, v[186:187]
	s_addc_u32 s1, s37, 0
	s_add_i32 vcc_lo, vcc_hi, s54
	global_load_lds_dwordx4 v[226:227], off
	v_lshl_add_u64 v[234:235], s[0:1], 0, v[0:1]
	s_mov_b32 m0, vcc_lo
	v_lshl_add_u64 v[246:247], s[46:47], 0, v[188:189]
	global_load_lds_dwordx4 v[234:235], off
	v_lshl_add_u64 v[234:235], s[0:1], 0, v[186:187]
	s_add_i32 m0, vcc_lo, 0x2000
	s_nop 0
	global_load_lds_dwordx4 v[234:235], off
	v_lshl_add_u64 v[234:235], s[46:47], 0, v[190:191]
	s_mov_b32 m0, s71
	s_nop 0
	global_load_lds_dwordx4 v[234:235], off
	s_mov_b32 m0, s76
	s_nop 0
	global_load_lds_dwordx4 v[246:247], off
	s_waitcnt vmcnt(8)
	s_waitcnt lgkmcnt(0)
	s_barrier
; #define PG8_STAGE(bufoff, gbase, voff) do { _Pragma("unroll") for (int _i = 0; _i < 2; ++_i) \
;         __builtin_amdgcn_global_load_lds((const unsigned*)((const char*)(gbase) + (voff)[_i]), (PG8_LAS unsigned*)(lds + (bufoff) + ldsw + _i * 8192), 16, 0, 0); } while (0)
; #define PG8_LDA(dst, b, h) do { _Pragma("unroll") for (int m = 0; m < 4; ++m) _Pragma("unroll") for (int k = 0; k < 2; ++k) dst[m][k] = *(const PG8_LAS bf16x8*)(lds + PG8_SA(b, h) + aoff + m * 2048 + k * 1024); } while (0)
; #define PG8_LDB(dst, b, h) do { _Pragma("unroll") for (int n = 0; n < 2; ++n) _Pragma("unroll") for (int k = 0; k < 2; ++k) dst[n][k] = *(const PG8_LAS bf16x8*)(lds + PG8_SB(b, h) + boff + n * 2048 + k * 1024); } while (0)
; #define PG8_MMA(ai, bj, At, Bt) do { __builtin_amdgcn_s_setprio(1); _Pragma("unroll") for (int m = 0; m < 4; ++m) _Pragma("unroll") for (int n = 0; n < 2; ++n) _Pragma("unroll") for (int k = 0; k < 2; ++k) \
;         acc[ai][bj][m][n] = __builtin_amdgcn_mfma_f32_16x16x32_bf16(Bt[n][k], At[m][k], acc[ai][bj][m][n], 0, 0, 0); __builtin_amdgcn_s_setprio(0); } while (0)
; #define PG8_WAIT_V(n) asm volatile("s_waitcnt vmcnt(" #n ")" ::: "memory")
; #define PG8_WAIT_L(n) asm volatile("s_waitcnt lgkmcnt(" #n ")" ::: "memory")
; #define PG8_BAR __builtin_amdgcn_s_barrier()
; #define PG8_SCHED __builtin_amdgcn_sched_barrier(0)
; template <class Epi, class Sched, bool ALIGN_EPI = false, bool SP2 = false>
; __device__ __forceinline__ void gemm_phase(PG8_LAS unsigned char* lds, const Gemm g, const Sched& S, const Epi& E) {
;     ...
;             PG8_WAIT_V(8); PG8_WAIT_L(0); PG8_BAR; PG8_MMA(1, 0, At, B0); PG8_MMA(1, 1, At, B1); PG8_BAR; PG8_SCHED;
;             PG8_LDB(B0, 1, 0); PG8_LDB(B1, 1, 1); PG8_SCHED; PG8_LDA(At, 1, 0); PG8_STAGE(PG8_SA(0, 1), a2 + hstepA, voffA);
;             PG8_WAIT_V(8); PG8_WAIT_L(0); PG8_BAR; PG8_MMA(0, 0, At, B0); PG8_MMA(0, 1, At, B1); PG8_BAR; PG8_SCHED;
	s_setprio 1
	s_waitcnt lgkmcnt(0)
	v_mfma_f32_16x16x32_bf16 v[70:73], v[58:61], v[162:165], 0
	v_mfma_f32_16x16x32_bf16 v[66:69], v[74:77], v[162:165], 0
	v_mfma_f32_16x16x32_bf16 v[46:49], v[58:61], v[170:173], 0
	v_mfma_f32_16x16x32_bf16 v[42:45], v[74:77], v[170:173], 0
	v_mfma_f32_16x16x32_bf16 v[30:33], v[58:61], v[178:181], 0
	v_mfma_f32_16x16x32_bf16 v[26:29], v[74:77], v[178:181], 0
	v_mfma_f32_16x16x32_bf16 v[14:17], v[58:61], v[218:221], 0
	v_mfma_f32_16x16x32_bf16 v[10:13], v[74:77], v[218:221], 0
	v_mfma_f32_16x16x32_bf16 v[70:73], v[62:65], v[166:169], v[70:73]
	v_mfma_f32_16x16x32_bf16 v[66:69], v[78:81], v[166:169], v[66:69]
	v_mfma_f32_16x16x32_bf16 v[46:49], v[62:65], v[174:177], v[46:49]
	v_mfma_f32_16x16x32_bf16 v[42:45], v[78:81], v[174:177], v[42:45]
	v_mfma_f32_16x16x32_bf16 v[30:33], v[62:65], v[182:185], v[30:33]
	v_mfma_f32_16x16x32_bf16 v[26:29], v[78:81], v[182:185], v[26:29]
	v_mfma_f32_16x16x32_bf16 v[14:17], v[62:65], v[222:225], v[14:17]
	v_mfma_f32_16x16x32_bf16 v[10:13], v[78:81], v[222:225], v[10:13]
	s_setprio 0
	s_setprio 1
	v_mfma_f32_16x16x32_bf16 v[54:57], v[130:133], v[162:165], 0
	v_mfma_f32_16x16x32_bf16 v[50:53], v[154:157], v[162:165], 0
	v_mfma_f32_16x16x32_bf16 v[38:41], v[130:133], v[170:173], 0
	v_mfma_f32_16x16x32_bf16 v[34:37], v[154:157], v[170:173], 0
	v_mfma_f32_16x16x32_bf16 v[22:25], v[130:133], v[178:181], 0
	v_mfma_f32_16x16x32_bf16 v[18:21], v[154:157], v[178:181], 0
	v_mfma_f32_16x16x32_bf16 v[6:9], v[130:133], v[218:221], 0
	v_mfma_f32_16x16x32_bf16 v[2:5], v[154:157], v[218:221], 0
	v_mfma_f32_16x16x32_bf16 v[54:57], v[142:145], v[166:169], v[54:57]
	v_mfma_f32_16x16x32_bf16 v[50:53], v[158:161], v[166:169], v[50:53]
	v_mfma_f32_16x16x32_bf16 v[38:41], v[142:145], v[174:177], v[38:41]
	v_mfma_f32_16x16x32_bf16 v[34:37], v[158:161], v[174:177], v[34:37]
	v_mfma_f32_16x16x32_bf16 v[22:25], v[142:145], v[182:185], v[22:25]
	v_mfma_f32_16x16x32_bf16 v[18:21], v[158:161], v[182:185], v[18:21]
	v_mfma_f32_16x16x32_bf16 v[6:9], v[142:145], v[222:225], v[6:9]
	v_mfma_f32_16x16x32_bf16 v[2:5], v[158:161], v[222:225], v[2:5]
	s_setprio 0
	s_barrier
	s_add_i32 vcc_lo, 0, 0x18000
	s_add_i32 vcc_hi, 0, 0x1c000
	v_add_u32_e32 v78, vcc_lo, v228
	v_add_u32_e32 v158, vcc_hi, v228
	ds_read_b128 v[58:61], v78
	ds_read_b128 v[62:65], v78 offset:1024
	ds_read_b128 v[74:77], v78 offset:2048
	ds_read_b128 v[78:81], v78 offset:3072
	ds_read_b128 v[130:133], v158
	ds_read_b128 v[142:145], v158 offset:1024
	ds_read_b128 v[154:157], v158 offset:2048
	ds_read_b128 v[158:161], v158 offset:3072
	s_add_u32 s0, s46, 0xb0000
	s_addc_u32 s1, s47, 0
	s_mov_b32 m0, s77
	v_lshl_add_u64 v[248:249], s[0:1], 0, v[190:191]
	ds_read_b128 v[162:165], v233 offset:32768
	ds_read_b128 v[166:169], v233 offset:33792
	ds_read_b128 v[170:173], v233 offset:34816
	ds_read_b128 v[174:177], v233 offset:35840
	ds_read_b128 v[178:181], v233 offset:36864
	ds_read_b128 v[182:185], v233 offset:37888
	ds_read_b128 v[218:221], v233 offset:38912
	ds_read_b128 v[222:225], v233 offset:39936
	global_load_lds_dwordx4 v[248:249], off
	v_lshl_add_u64 v[248:249], s[0:1], 0, v[188:189]
	s_mov_b32 m0, s78
	s_nop 0
	global_load_lds_dwordx4 v[248:249], off
	s_waitcnt vmcnt(8)
	s_waitcnt lgkmcnt(0)
	s_barrier
	s_setprio 1
	s_waitcnt lgkmcnt(0)
	v_mfma_f32_16x16x32_bf16 v[150:153], v[58:61], v[162:165], v[150:153]
	v_mfma_f32_16x16x32_bf16 v[146:149], v[74:77], v[162:165], v[146:149]
	v_mfma_f32_16x16x32_bf16 v[126:129], v[58:61], v[170:173], v[126:129]
	v_mfma_f32_16x16x32_bf16 v[122:125], v[74:77], v[170:173], v[122:125]
	v_mfma_f32_16x16x32_bf16 v[110:113], v[58:61], v[178:181], v[110:113]
	v_mfma_f32_16x16x32_bf16 v[106:109], v[74:77], v[178:181], v[106:109]
	v_mfma_f32_16x16x32_bf16 v[94:97], v[58:61], v[218:221], v[94:97]
	v_mfma_f32_16x16x32_bf16 v[90:93], v[74:77], v[218:221], v[90:93]
	v_mfma_f32_16x16x32_bf16 v[150:153], v[62:65], v[166:169], v[150:153]
	v_mfma_f32_16x16x32_bf16 v[146:149], v[78:81], v[166:169], v[146:149]
	v_mfma_f32_16x16x32_bf16 v[126:129], v[62:65], v[174:177], v[126:129]
	v_mfma_f32_16x16x32_bf16 v[122:125], v[78:81], v[174:177], v[122:125]
	v_mfma_f32_16x16x32_bf16 v[110:113], v[62:65], v[182:185], v[110:113]
	v_mfma_f32_16x16x32_bf16 v[106:109], v[78:81], v[182:185], v[106:109]
	v_mfma_f32_16x16x32_bf16 v[94:97], v[62:65], v[222:225], v[94:97]
	v_mfma_f32_16x16x32_bf16 v[90:93], v[78:81], v[222:225], v[90:93]
	s_setprio 0
	s_setprio 1
	v_mfma_f32_16x16x32_bf16 v[138:141], v[130:133], v[162:165], v[138:141]
	v_mfma_f32_16x16x32_bf16 v[134:137], v[154:157], v[162:165], v[134:137]
	v_mfma_f32_16x16x32_bf16 v[118:121], v[130:133], v[170:173], v[118:121]
	v_mfma_f32_16x16x32_bf16 v[114:117], v[154:157], v[170:173], v[114:117]
	v_mfma_f32_16x16x32_bf16 v[102:105], v[130:133], v[178:181], v[102:105]
	v_mfma_f32_16x16x32_bf16 v[98:101], v[154:157], v[178:181], v[98:101]
	v_mfma_f32_16x16x32_bf16 v[86:89], v[130:133], v[218:221], v[86:89]
	v_mfma_f32_16x16x32_bf16 v[82:85], v[154:157], v[218:221], v[82:85]
	v_mfma_f32_16x16x32_bf16 v[138:141], v[142:145], v[166:169], v[138:141]
	v_mfma_f32_16x16x32_bf16 v[134:137], v[158:161], v[166:169], v[134:137]
	v_mfma_f32_16x16x32_bf16 v[118:121], v[142:145], v[174:177], v[118:121]
	v_mfma_f32_16x16x32_bf16 v[114:117], v[158:161], v[174:177], v[114:117]
	v_mfma_f32_16x16x32_bf16 v[102:105], v[142:145], v[182:185], v[102:105]
	v_mfma_f32_16x16x32_bf16 v[98:101], v[158:161], v[182:185], v[98:101]
	v_mfma_f32_16x16x32_bf16 v[86:89], v[142:145], v[222:225], v[86:89]
	v_mfma_f32_16x16x32_bf16 v[82:85], v[158:161], v[222:225], v[82:85]
	s_setprio 0
	s_barrier
; #define PG8_STAGE(bufoff, gbase, voff) do { _Pragma("unroll") for (int _i = 0; _i < 2; ++_i) \
;         __builtin_amdgcn_global_load_lds((const unsigned*)((const char*)(gbase) + (voff)[_i]), (PG8_LAS unsigned*)(lds + (bufoff) + ldsw + _i * 8192), 16, 0, 0); } while (0)
; #define PG8_LDA(dst, b, h) do { _Pragma("unroll") for (int m = 0; m < 4; ++m) _Pragma("unroll") for (int k = 0; k < 2; ++k) dst[m][k] = *(const PG8_LAS bf16x8*)(lds + PG8_SA(b, h) + aoff + m * 2048 + k * 1024); } while (0)
; #define PG8_MMA(ai, bj, At, Bt) do { __builtin_amdgcn_s_setprio(1); _Pragma("unroll") for (int m = 0; m < 4; ++m) _Pragma("unroll") for (int n = 0; n < 2; ++n) _Pragma("unroll") for (int k = 0; k < 2; ++k) \
;         acc[ai][bj][m][n] = __builtin_amdgcn_mfma_f32_16x16x32_bf16(Bt[n][k], At[m][k], acc[ai][bj][m][n], 0, 0, 0); __builtin_amdgcn_s_setprio(0); } while (0)
; #define PG8_WAIT_V(n) asm volatile("s_waitcnt vmcnt(" #n ")" ::: "memory")
; #define PG8_WAIT_L(n) asm volatile("s_waitcnt lgkmcnt(" #n ")" ::: "memory")
; #define PG8_BAR __builtin_amdgcn_s_barrier()
; #define PG8_SCHED __builtin_amdgcn_sched_barrier(0)
; template <class Epi, class Sched, bool ALIGN_EPI = false, bool SP2 = false>
; __device__ __forceinline__ void gemm_phase(PG8_LAS unsigned char* lds, const Gemm g, const Sched& S, const Epi& E) {
;     ...
;             PG8_LDA(At, 1, 1); PG8_STAGE(PG8_SB(1, 0), b3, voffB); PG8_STAGE(PG8_SB(1, 1), b3 + hstepB, voffB); PG8_STAGE(PG8_SA(1, 0), a3, voffA);
;             PG8_WAIT_V(8); PG8_WAIT_L(0); PG8_BAR; PG8_MMA(1, 0, At, B0); PG8_MMA(1, 1, At, B1); PG8_BAR; PG8_SCHED;
	s_add_i32 s0, vcc_lo, s54
	v_lshl_add_u64 v[204:205], v[204:205], 0, s[22:23]
	s_mov_b32 m0, s0
	ds_read_b128 v[162:165], v233 offset:49152
	ds_read_b128 v[166:169], v233 offset:50176
	ds_read_b128 v[170:173], v233 offset:51200
	ds_read_b128 v[174:177], v233 offset:52224
	ds_read_b128 v[178:181], v233 offset:53248
	ds_read_b128 v[182:185], v233 offset:54272
	ds_read_b128 v[218:221], v233 offset:55296
	ds_read_b128 v[222:225], v233 offset:56320
	global_load_lds_dwordx4 v[204:205], off
	s_add_i32 m0, s0, 0x2000
	s_add_u32 s0, s36, 0xb0080
	v_lshl_add_u64 v[204:205], v[226:227], 0, s[22:23]
	s_addc_u32 s1, s37, 0
	s_add_i32 s36, vcc_hi, s54
	global_load_lds_dwordx4 v[204:205], off
	v_lshl_add_u64 v[204:205], s[0:1], 0, v[0:1]
	s_mov_b32 m0, s36
	s_nop 0
	global_load_lds_dwordx4 v[204:205], off
	v_lshl_add_u64 v[204:205], s[0:1], 0, v[186:187]
	s_add_i32 m0, s36, 0x2000
	s_nop 0
	global_load_lds_dwordx4 v[204:205], off
	v_lshl_add_u64 v[204:205], v[234:235], 0, s[22:23]
	s_mov_b32 m0, s82
	s_nop 0
	global_load_lds_dwordx4 v[204:205], off
	v_lshl_add_u64 v[204:205], v[246:247], 0, s[22:23]
	s_mov_b32 m0, s83
	s_nop 0
	global_load_lds_dwordx4 v[204:205], off
	s_waitcnt vmcnt(8)
	s_waitcnt lgkmcnt(0)
	s_barrier
	s_setprio 1
	s_waitcnt lgkmcnt(0)
	v_mfma_f32_16x16x32_bf16 v[70:73], v[58:61], v[162:165], v[70:73]
	v_mfma_f32_16x16x32_bf16 v[66:69], v[74:77], v[162:165], v[66:69]
	v_mfma_f32_16x16x32_bf16 v[46:49], v[58:61], v[170:173], v[46:49]
	v_mfma_f32_16x16x32_bf16 v[42:45], v[74:77], v[170:173], v[42:45]
	v_mfma_f32_16x16x32_bf16 v[30:33], v[58:61], v[178:181], v[30:33]
	v_mfma_f32_16x16x32_bf16 v[26:29], v[74:77], v[178:181], v[26:29]
	v_mfma_f32_16x16x32_bf16 v[14:17], v[58:61], v[218:221], v[14:17]
	v_mfma_f32_16x16x32_bf16 v[10:13], v[74:77], v[218:221], v[10:13]
	v_mfma_f32_16x16x32_bf16 v[70:73], v[62:65], v[166:169], v[70:73]
	v_mfma_f32_16x16x32_bf16 v[66:69], v[78:81], v[166:169], v[66:69]
	v_mfma_f32_16x16x32_bf16 v[46:49], v[62:65], v[174:177], v[46:49]
	v_mfma_f32_16x16x32_bf16 v[42:45], v[78:81], v[174:177], v[42:45]
	v_mfma_f32_16x16x32_bf16 v[30:33], v[62:65], v[182:185], v[30:33]
	v_mfma_f32_16x16x32_bf16 v[26:29], v[78:81], v[182:185], v[26:29]
	v_mfma_f32_16x16x32_bf16 v[14:17], v[62:65], v[222:225], v[14:17]
	v_mfma_f32_16x16x32_bf16 v[10:13], v[78:81], v[222:225], v[10:13]
	s_setprio 0
	s_setprio 1
	v_mfma_f32_16x16x32_bf16 v[54:57], v[130:133], v[162:165], v[54:57]
	v_mfma_f32_16x16x32_bf16 v[50:53], v[154:157], v[162:165], v[50:53]
	v_mfma_f32_16x16x32_bf16 v[38:41], v[130:133], v[170:173], v[38:41]
	v_mfma_f32_16x16x32_bf16 v[34:37], v[154:157], v[170:173], v[34:37]
	v_mfma_f32_16x16x32_bf16 v[22:25], v[130:133], v[178:181], v[22:25]
	v_mfma_f32_16x16x32_bf16 v[18:21], v[154:157], v[178:181], v[18:21]
	v_mfma_f32_16x16x32_bf16 v[6:9], v[130:133], v[218:221], v[6:9]
	v_mfma_f32_16x16x32_bf16 v[2:5], v[154:157], v[218:221], v[2:5]
	v_mfma_f32_16x16x32_bf16 v[54:57], v[142:145], v[166:169], v[54:57]
	v_mfma_f32_16x16x32_bf16 v[50:53], v[158:161], v[166:169], v[50:53]
	v_mfma_f32_16x16x32_bf16 v[38:41], v[142:145], v[174:177], v[38:41]
	v_mfma_f32_16x16x32_bf16 v[34:37], v[158:161], v[174:177], v[34:37]
	v_mfma_f32_16x16x32_bf16 v[22:25], v[142:145], v[182:185], v[22:25]
	v_mfma_f32_16x16x32_bf16 v[18:21], v[158:161], v[182:185], v[18:21]
	v_mfma_f32_16x16x32_bf16 v[6:9], v[142:145], v[222:225], v[6:9]
	v_mfma_f32_16x16x32_bf16 v[2:5], v[158:161], v[222:225], v[2:5]
	s_setprio 0
	s_barrier
	s_add_i32 s87, s87, 2
	s_add_u32 s9, s9, 0x100
	s_addc_u32 s17, s17, 0
	s_cmp_gt_u32 s87, 41
	s_mov_b64 s[0:1], s[34:35]
	s_cbranch_scc1 .Lpk_done_g1315

; __device__ __forceinline__ void unpack8(const u32x4 w, float (&v)[8]) { v[0] = bf_lo(w.x); v[1] = bf_hi(w.x); v[2] = bf_lo(w.y); v[3] = bf_hi(w.y); v[4] = bf_lo(w.z); v[5] = bf_hi(w.z); v[6] = bf_lo(w.w); v[7] = bf_hi(w.w); }
;     __device__ __forceinline__ void operator()(const f32x4 (&acc)[2][2][4][2], const Unit& u, int wr, int wc, int fr, int fq) const {
;     ...
;         if (tid == 0) { (void)__hip_atomic_fetch_add(cnt + u.pm, 1u, __ATOMIC_RELAXED, __HIP_MEMORY_SCOPE_AGENT); unsigned sp = 0;
;             while (__hip_atomic_load(cnt + u.pm, __ATOMIC_RELAXED, __HIP_MEMORY_SCOPE_AGENT) < need) { __builtin_amdgcn_s_sleep(1); if (++sp > (1u << 22)) break; } }
;         asm volatile("s_waitcnt vmcnt(0) lgkmcnt(0)" ::: "memory"); __builtin_amdgcn_s_barrier(); asm volatile("" ::: "memory");
;         if (tid < 256) { float ss = 0.f;
; #pragma unroll
;             for (int t = 0; t < 4; ++t) ss += __uint_as_float(__hip_atomic_load((unsigned*)(XS + (grow0 + tid) * 4 + t), __ATOMIC_RELAXED, __HIP_MEMORY_SCOPE_AGENT));
;             S[tid] = alpha * rsqrtf(ss * (1.0f / DM) + RMS_EPS); }
;         asm volatile("s_waitcnt vmcnt(0) lgkmcnt(0)" ::: "memory"); __builtin_amdgcn_s_barrier(); asm volatile("" ::: "memory");
; #pragma unroll
;         for (int ai = 0; ai < 2; ++ai)
; #pragma unroll
;             for (int m = 0; m < 4; ++m) { const int rloc = rloc0 + ai * 128 + m * 16; const float rs = S[rloc]; float q2 = 0.f;
;                 u32x4 cur[2]; cur[0] = pre[m][0]; cur[1] = pre[m][1];
;                 if (ai == 0) {
; #pragma unroll
;                     for (int bj = 0; bj < 2; ++bj) pre[m][bj] = *(const u32x4*)(HB + (grow0 + rloc + 128) * DM + colb + bj * 128); }
; #pragma unroll
;                 for (int bj = 0; bj < 2; ++bj) { float h[8]; unpack8(cur[bj], h);
; #pragma unroll
;                     for (int e = 0; e < 4; ++e) { h[e] += acc[ai][bj][m][0][e] * g[bj][0][e] * rs; h[4 + e] += acc[ai][bj][m][1][e] * g[bj][1][e] * rs; }
;                     if (OUT) { float* op = OUT + (grow0 + rloc) * DM + colb + bj * 128; *(f32x4*)op = (f32x4){h[0], h[1], h[2], h[3]}; *(f32x4*)(op + 4) = (f32x4){h[4], h[5], h[6], h[7]}; }
.LBB0_1347:
	s_or_b64 exec, exec, s[34:35]
	s_waitcnt vmcnt(0) lgkmcnt(0)
	s_barrier
	s_and_saveexec_b64 s[8:9], s[40:41]
	s_cbranch_execz .LBB0_1349
	v_mov_b32_e32 v221, s1
	s_waitcnt lgkmcnt(0)
	v_lshl_add_u64 v[164:165], v[220:221], 4, s[58:59]
	global_load_dwordx4 v[170:173], v[164:165], off sc1
	s_mov_b32 s17, 0x800000
	s_waitcnt vmcnt(0)
	v_add_f32_e32 v170, 0, v170
	v_add_f32_e32 v170, v170, v171
	v_add_f32_e32 v170, v170, v172
	v_add_f32_e32 v164, v170, v173
	v_fmamk_f32 v164, v164, 0x3a800000, v203
	v_cmp_gt_f32_e32 vcc, s17, v164
	v_mul_f32_e32 v165, 0x4b800000, v164
	s_nop 0
	v_cndmask_b32_e32 v164, v164, v165, vcc
	v_rsq_f32_e32 v164, v164
	s_nop 0
	v_mul_f32_e32 v165, 0x45800000, v164
	v_cndmask_b32_e32 v164, v164, v165, vcc
	v_mul_f32_e32 v164, 0.5, v164
	ds_write_b32 v252, v164
.LBB0_1349:
	s_or_b64 exec, exec, s[8:9]
	v_lshl_add_u64 v[162:163], s[20:21], 0, v[162:163]
	v_lshl_add_u64 v[224:225], v[218:219], 1, v[162:163]
	v_add_co_u32_e32 v164, vcc, 0x40000, v224
	s_waitcnt vmcnt(0) lgkmcnt(0)
	s_barrier
	v_lshl_add_u64 v[162:163], v[224:225], 0, s[24:25]
	s_waitcnt lgkmcnt(0)
	v_addc_co_u32_e32 v165, vcc, 0, v225, vcc
	global_load_dwordx4 v[170:173], v[164:165], off
	s_nop 0
	global_load_dwordx4 v[162:165], v[162:163], off offset:256
	ds_read_b32 v226, v231
	v_lshlrev_b64 v[204:205], 12, v[222:223]
	s_waitcnt vmcnt(2)
	v_lshlrev_b32_e32 v222, 16, v182
	v_and_b32_e32 v223, 0xffff0000, v182
	v_pk_mul_f32 v[152:153], v[152:153], v[80:81]
	v_lshlrev_b32_e32 v182, 16, v183
	v_and_b32_e32 v183, 0xffff0000, v183
	v_pk_mul_f32 v[148:149], v[148:149], v[76:77]
	s_waitcnt lgkmcnt(0)
	v_pk_fma_f32 v[152:153], v[152:153], v[226:227], v[182:183] op_sel_hi:[1,0,1]
	v_lshlrev_b32_e32 v182, 16, v185
	v_and_b32_e32 v183, 0xffff0000, v185
	v_pk_mul_f32 v[150:151], v[150:151], v[78:79]
	v_pk_fma_f32 v[148:149], v[148:149], v[226:227], v[182:183] op_sel_hi:[1,0,1]
	v_cndmask_b32_e64 v182, 0, 1, s[62:63]
	v_pk_fma_f32 v[150:151], v[150:151], v[226:227], v[222:223] op_sel_hi:[1,0,1]
	v_lshlrev_b32_e32 v222, 16, v184
	v_and_b32_e32 v223, 0xffff0000, v184
	v_pk_mul_f32 v[146:147], v[146:147], v[74:75]
	v_cmp_ne_u32_e64 s[46:47], 1, v182
	v_lshl_add_u64 v[182:183], s[18:19], 0, v[204:205]
	v_pk_fma_f32 v[146:147], v[146:147], v[226:227], v[222:223] op_sel_hi:[1,0,1]
	s_mov_b64 s[8:9], -1
	s_andn2_b64 vcc, exec, s[62:63]
	v_lshl_add_u64 v[182:183], v[218:219], 2, v[182:183]
	s_cbranch_vccnz .LBB0_1351
	s_mov_b64 s[8:9], 0
	global_store_dwordx4 v[182:183], v[150:153], off
	global_store_dwordx4 v[182:183], v[146:149], off offset:16

; __device__ __forceinline__ void unpack8(const u32x4 w, float (&v)[8]) { v[0] = bf_lo(w.x); v[1] = bf_hi(w.x); v[2] = bf_lo(w.y); v[3] = bf_hi(w.y); v[4] = bf_lo(w.z); v[5] = bf_hi(w.z); v[6] = bf_lo(w.w); v[7] = bf_hi(w.w); }
;     __device__ __forceinline__ void operator()(const f32x4 (&acc)[2][2][4][2], const Unit& u, int wr, int wc, int fr, int fq) const {
;     ...
;             for (int m = 0; m < 4; ++m) { const int rloc = rloc0 + ai * 128 + m * 16; const float rs = S[rloc]; float q2 = 0.f;
;                 u32x4 cur[2]; cur[0] = pre[m][0]; cur[1] = pre[m][1];
;                 if (ai == 0) {
; #pragma unroll
;                     for (int bj = 0; bj < 2; ++bj) pre[m][bj] = *(const u32x4*)(HB + (grow0 + rloc + 128) * DM + colb + bj * 128); }
; #pragma unroll
;                 for (int bj = 0; bj < 2; ++bj) { float h[8]; unpack8(cur[bj], h);
; #pragma unroll
;                     for (int e = 0; e < 4; ++e) { h[e] += acc[ai][bj][m][0][e] * g[bj][0][e] * rs; h[4 + e] += acc[ai][bj][m][1][e] * g[bj][1][e] * rs; }
;                     if (OUT) { float* op = OUT + (grow0 + rloc) * DM + colb + bj * 128; *(f32x4*)op = (f32x4){h[0], h[1], h[2], h[3]}; *(f32x4*)(op + 4) = (f32x4){h[4], h[5], h[6], h[7]}; }
.LBB0_1389:
	s_or_b64 exec, exec, s[8:9]
	v_lshl_add_u32 v82, v200, 2, s64
	ds_read_b32 v82, v82
	v_pk_mul_f32 v[70:71], v[70:71], v[78:79]
	s_waitcnt vmcnt(8)
	v_lshlrev_b32_e32 v88, 16, v170
	v_and_b32_e32 v89, 0xffff0000, v170
	v_lshl_add_u64 v[84:85], s[0:1], 0, v[200:201]
	v_pk_mul_f32 v[66:67], v[66:67], v[74:75]
	s_waitcnt lgkmcnt(0)
	v_pk_fma_f32 v[70:71], v[70:71], v[82:83], v[88:89] op_sel_hi:[1,0,1]
	v_lshlrev_b32_e32 v88, 16, v172
	v_and_b32_e32 v89, 0xffff0000, v172
	v_lshlrev_b64 v[86:87], 12, v[84:85]
	v_pk_mul_f32 v[72:73], v[72:73], v[80:81]
	v_pk_fma_f32 v[66:67], v[66:67], v[82:83], v[88:89] op_sel_hi:[1,0,1]
	v_lshlrev_b32_e32 v88, 16, v171
	v_and_b32_e32 v89, 0xffff0000, v171
	v_pk_mul_f32 v[68:69], v[68:69], v[76:77]
	v_pk_fma_f32 v[72:73], v[72:73], v[82:83], v[88:89] op_sel_hi:[1,0,1]
	v_lshlrev_b32_e32 v88, 16, v173
	v_and_b32_e32 v89, 0xffff0000, v173
	v_lshl_add_u64 v[86:87], s[18:19], 0, v[86:87]
	v_pk_fma_f32 v[68:69], v[68:69], v[82:83], v[88:89] op_sel_hi:[1,0,1]
	s_mov_b64 s[8:9], -1
	s_and_b64 vcc, exec, s[46:47]
	v_lshl_add_u64 v[86:87], v[218:219], 2, v[86:87]
	s_cbranch_vccnz .LBB0_1391
	s_mov_b64 s[8:9], 0
	global_store_dwordx4 v[86:87], v[70:73], off
	global_store_dwordx4 v[86:87], v[66:69], off offset:16
